# v9 + in-proj epilogue kinds 1 and 3: second-half wmax/lb/gain loads hoisted above the first half's stores
# speedup vs baseline: 1.0001x; 1.0001x over previous
;     template <int KIND>
;     __device__ __forceinline__ void run(const f32x4 (&acc)[2][2][4][2], const Unit& u, int wr, int wc, int fr, int fq) const {
;         const int row0 = u.pm * BM + wr * 64 + fr, col0 = u.pn * BM + wc * 32 + 8 * fq;
;         const float sa_lo = sa[u.pm * BM + wr * 64 + fr + 16 * fq], sa_hi = sa[u.pm * BM + HALF + wr * 64 + fr + 16 * fq];
; #pragma unroll
;         for (int bj = 0; bj < 2; ++bj) {
;             f32x2_t sc2[4], aux2[4];
; #pragma unroll
;             for (int j = 0; j < 4; ++j) {
;                 const float k0 = (KIND == 4) ? (0.125f * LOG2E / 127.0f) : (1.0f / 127.0f);
;                 sc2[j] = (f32x2_t){wmax[col0 + bj * HALF + 2 * j] * k0, wmax[col0 + bj * HALF + 2 * j + 1] * k0};
;                 if (KIND == 1) aux2[j] = (f32x2_t){lb[col0 - C_HG + bj * HALF + 2 * j], lb[col0 - C_HG + bj * HALF + 2 * j + 1]};
;                 else if (KIND == 3) aux2[j] = (f32x2_t){gain[col0 - C_HGATE + bj * HALF + 2 * j], gain[col0 - C_HGATE + bj * HALF + 2 * j + 1]};
;                 else aux2[j] = (f32x2_t){0.f, 0.f};
;             }
; #pragma unroll
;             for (int ai = 0; ai < 2; ++ai)
; #pragma unroll
;                 for (int m = 0; m < 4; ++m) { const int row = row0 + ai * HALF + m * 16; const float a = __shfl(ai ? sa_hi : sa_lo, 16 * m + fr);
;                     const f32x4 f0 = __builtin_convertvector(__builtin_bit_cast(i32x4, acc[ai][bj][m][0]), f32x4), f1 = __builtin_convertvector(__builtin_bit_cast(i32x4, acc[ai][bj][m][1]), f32x4);
;                     f32x2_t v[4] = {(f32x2_t){f0[0], f0[1]}, (f32x2_t){f0[2], f0[3]}, (f32x2_t){f1[0], f1[1]}, (f32x2_t){f1[2], f1[3]}};
; #pragma unroll
;                     for (int j = 0; j < 4; ++j) {
;                         v[j] = v[j] * (sc2[j] * (f32x2_t){a, a});
;                         if (KIND == 0 || KIND == 1 || KIND == 3) {
;                             const f32x2_t e = v[j] * (f32x2_t){-LOG2E, -LOG2E};
;                             const f32x2_t dn = (f32x2_t){__builtin_amdgcn_exp2f(e[0]), __builtin_amdgcn_exp2f(e[1])} + (f32x2_t){1.0f, 1.0f};
;                             const f32x2_t sg = (f32x2_t){fast_rcp(dn[0]), fast_rcp(dn[1])};
;                             if (KIND == 0) v[j] = v[j] * sg;
;                             else if (KIND == 3) v[j] = (v[j] * sg) * aux2[j];
.LBB0_217:
	s_and_b64 vcc, exec, s[10:11]
	s_cbranch_vccz .LBB0_219
	v_lshl_add_u64 v[156:157], v[146:147], 2, s[44:45]
	s_movk_i32 s2, 0xe800
	s_mov_b32 s3, -1
	v_add_co_u32_e32 v152, vcc, 0xfffff000, v156
	v_lshl_add_u64 v[132:133], v[156:157], 0, s[2:3]
	s_nop 0
	v_addc_co_u32_e32 v153, vcc, -1, v157, vcc
	global_load_dwordx4 v[136:139], v[152:153], off offset:-2048
	s_nop 0
	global_load_dwordx4 v[132:135], v[132:133], off offset:16
	s_nop 0
	global_load_dwordx2 v[150:151], v[148:149], off offset:24
	global_load_dwordx4 v[158:161], v[148:149], off offset:8
	s_mov_b32 s6, 0x3c010204
	v_cvt_f32_i32_e32 v169, v129
	v_cvt_f32_i32_e32 v168, v128
	s_waitcnt vmcnt(0)
	v_pk_mul_f32 v[164:165], v[154:155], s[6:7] op_sel_hi:[1,0]
	s_mov_b32 s10, 0xbfb8aa3b
	v_cvt_f32_i32_e32 v163, v131
	v_cvt_f32_i32_e32 v162, v130
	global_load_dwordx4 v[236:239], v[148:149], off offset:528
	global_load_dwordx4 v[240:243], v[148:149], off offset:512
	global_load_dwordx4 v[244:247], v[152:153], off offset:-1536
	global_load_dwordx4 v[128:131], v[152:153], off offset:-1520
	v_cvt_f32_i32_e32 v173, v125
	v_cvt_f32_i32_e32 v172, v124
	v_cvt_f32_i32_e32 v171, v127
	v_cvt_f32_i32_e32 v170, v126
	v_mov_b64_e32 v[188:189], s[14:15]
	v_lshlrev_b64 v[192:193], 1, v[146:147]
	v_or_b32_e32 v174, 16, v175
	v_cvt_f32_i32_e32 v185, v101
	v_cvt_f32_i32_e32 v184, v100
	v_cvt_f32_i32_e32 v191, v93
	v_cvt_f32_i32_e32 v190, v92
	v_cvt_f32_i32_e32 v199, v77
	v_cvt_f32_i32_e32 v198, v76
	v_cvt_f32_i32_e32 v203, v69
	v_cvt_f32_i32_e32 v202, v68
	v_pk_mul_f32 v[150:151], v[150:151], s[6:7] op_sel_hi:[1,0]
	v_pk_mul_f32 v[166:167], v[158:159], s[6:7] op_sel_hi:[1,0]
	v_lshlrev_b32_e32 v159, 2, v233
	ds_bpermute_b32 v66, v159, v209
	v_pk_mul_f32 v[160:161], v[160:161], s[6:7] op_sel_hi:[1,0]
	ds_bpermute_b32 v158, v159, v209 offset:64
	s_waitcnt lgkmcnt(1)
	v_pk_mul_f32 v[176:177], v[164:165], v[66:67] op_sel_hi:[1,0]
	s_nop 0
	v_pk_mul_f32 v[168:169], v[168:169], v[176:177]
	s_waitcnt lgkmcnt(0)
	v_pk_mul_f32 v[178:179], v[164:165], v[158:159] op_sel_hi:[1,0]
	v_pk_mul_f32 v[176:177], v[168:169], s[10:11] op_sel_hi:[1,0]
	s_nop 0
	v_exp_f32_e32 v176, v176
	v_exp_f32_e32 v177, v177
	s_nop 0
	v_pk_add_f32 v[176:177], v[176:177], 1.0 op_sel_hi:[1,0]
	s_nop 0
	v_rcp_f32_e32 v176, v176
	v_rcp_f32_e32 v177, v177
	s_nop 0
	v_pk_mul_f32 v[168:169], v[168:169], v[176:177]
	v_pk_mul_f32 v[176:177], v[166:167], v[66:67] op_sel_hi:[1,0]
	v_pk_mul_f32 v[168:169], v[136:137], v[168:169]
	v_pk_mul_f32 v[162:163], v[162:163], v[176:177]
	v_cvt_pk_bf16_f32 v168, v168, v169
	v_pk_mul_f32 v[176:177], v[162:163], s[10:11] op_sel_hi:[1,0]
	s_nop 0
	v_exp_f32_e32 v176, v176
	v_exp_f32_e32 v177, v177
	s_nop 0
	v_pk_add_f32 v[176:177], v[176:177], 1.0 op_sel_hi:[1,0]
	s_nop 0
	v_rcp_f32_e32 v176, v176
	v_rcp_f32_e32 v177, v177
	s_nop 0
	v_pk_mul_f32 v[162:163], v[162:163], v[176:177]
	v_pk_mul_f32 v[176:177], v[160:161], v[66:67] op_sel_hi:[1,0]
	v_pk_mul_f32 v[162:163], v[138:139], v[162:163]
	v_pk_mul_f32 v[172:173], v[172:173], v[176:177]
	v_cvt_pk_bf16_f32 v169, v162, v163
	v_pk_mul_f32 v[176:177], v[172:173], s[10:11] op_sel_hi:[1,0]
	v_mad_i64_i32 v[162:163], s[2:3], v175, s81, v[188:189]
	v_exp_f32_e32 v176, v176
	v_exp_f32_e32 v177, v177
	v_lshl_add_u64 v[162:163], v[162:163], 0, v[192:193]
	v_pk_add_f32 v[176:177], v[176:177], 1.0 op_sel_hi:[1,0]
	s_nop 0
	v_rcp_f32_e32 v176, v176
	v_rcp_f32_e32 v177, v177
	s_nop 0
	v_pk_mul_f32 v[172:173], v[172:173], v[176:177]
	v_pk_mul_f32 v[176:177], v[150:151], v[66:67] op_sel_hi:[1,0]
	v_pk_mul_f32 v[172:173], v[132:133], v[172:173]
	v_pk_mul_f32 v[170:171], v[170:171], v[176:177]
	s_nop 0
	v_pk_mul_f32 v[176:177], v[170:171], s[10:11] op_sel_hi:[1,0]
	s_nop 0
	v_exp_f32_e32 v176, v176
	v_exp_f32_e32 v177, v177
	s_nop 0
	v_pk_add_f32 v[176:177], v[176:177], 1.0 op_sel_hi:[1,0]
	s_nop 0
	v_rcp_f32_e32 v176, v176
	v_rcp_f32_e32 v177, v177
	s_nop 0
	v_pk_mul_f32 v[170:171], v[170:171], v[176:177]
	s_nop 0
	v_pk_mul_f32 v[176:177], v[134:135], v[170:171]
	v_cvt_pk_bf16_f32 v170, v172, v173
	v_cvt_pk_bf16_f32 v171, v176, v177
	global_store_dwordx4 v[162:163], v[168:171], off
	v_cvt_f32_i32_e32 v177, v123
	v_cvt_f32_i32_e32 v176, v122
	v_cvt_f32_i32_e32 v171, v121
	v_cvt_f32_i32_e32 v170, v120
	v_cvt_f32_i32_e32 v173, v117
	v_cvt_f32_i32_e32 v172, v116
	v_cvt_f32_i32_e32 v169, v119
	v_pk_mul_f32 v[170:171], v[170:171], v[178:179]
	v_cvt_f32_i32_e32 v168, v118
	v_pk_mul_f32 v[178:179], v[170:171], s[10:11] op_sel_hi:[1,0]
	s_nop 0
	v_exp_f32_e32 v178, v178
	v_exp_f32_e32 v179, v179
	s_nop 0
	v_pk_add_f32 v[178:179], v[178:179], 1.0 op_sel_hi:[1,0]
	s_nop 0
	v_rcp_f32_e32 v178, v178
	v_rcp_f32_e32 v179, v179
	s_nop 0
	v_pk_mul_f32 v[170:171], v[170:171], v[178:179]
	v_pk_mul_f32 v[178:179], v[166:167], v[158:159] op_sel_hi:[1,0]
	v_pk_mul_f32 v[170:171], v[136:137], v[170:171]
	v_pk_mul_f32 v[176:177], v[176:177], v[178:179]
	s_nop 0
	v_pk_mul_f32 v[178:179], v[176:177], s[10:11] op_sel_hi:[1,0]
	s_nop 0
	v_exp_f32_e32 v178, v178
	v_exp_f32_e32 v179, v179
	s_nop 0
	v_pk_add_f32 v[178:179], v[178:179], 1.0 op_sel_hi:[1,0]
	s_nop 0
	v_rcp_f32_e32 v178, v178
	v_rcp_f32_e32 v179, v179
	s_nop 0
	v_pk_mul_f32 v[176:177], v[176:177], v[178:179]
	v_pk_mul_f32 v[178:179], v[160:161], v[158:159] op_sel_hi:[1,0]
	v_pk_mul_f32 v[176:177], v[138:139], v[176:177]
	v_pk_mul_f32 v[172:173], v[172:173], v[178:179]
	s_nop 0
	v_pk_mul_f32 v[178:179], v[172:173], s[10:11] op_sel_hi:[1,0]
	s_nop 0
	v_exp_f32_e32 v178, v178
	v_exp_f32_e32 v179, v179
	s_nop 0
	v_pk_add_f32 v[178:179], v[178:179], 1.0 op_sel_hi:[1,0]
	s_nop 0
	v_rcp_f32_e32 v178, v178
	v_rcp_f32_e32 v179, v179
	s_nop 0
	v_pk_mul_f32 v[172:173], v[172:173], v[178:179]
	v_pk_mul_f32 v[178:179], v[150:151], v[158:159] op_sel_hi:[1,0]
	v_pk_mul_f32 v[172:173], v[132:133], v[172:173]
	v_pk_mul_f32 v[168:169], v[168:169], v[178:179]
	s_nop 0
	v_pk_mul_f32 v[178:179], v[168:169], s[10:11] op_sel_hi:[1,0]
	s_nop 0
	v_exp_f32_e32 v178, v178
	v_exp_f32_e32 v179, v179
	s_nop 0
	v_pk_add_f32 v[178:179], v[178:179], 1.0 op_sel_hi:[1,0]
	s_nop 0
	v_rcp_f32_e32 v178, v178
	v_rcp_f32_e32 v179, v179
	s_nop 0
	v_pk_mul_f32 v[168:169], v[168:169], v[178:179]
	s_nop 0
	v_pk_mul_f32 v[178:179], v[134:135], v[168:169]
	v_cvt_pk_bf16_f32 v168, v170, v171
	v_cvt_pk_bf16_f32 v170, v172, v173
	v_mad_i64_i32 v[172:173], s[2:3], v174, s81, v[188:189]
	v_cvt_pk_bf16_f32 v169, v176, v177
	v_cvt_pk_bf16_f32 v171, v178, v179
	v_lshl_add_u64 v[180:181], v[172:173], 0, v[192:193]
	global_store_dwordx4 v[180:181], v[168:171], off
	ds_bpermute_b32 v168, v159, v209 offset:128
	v_cvt_f32_i32_e32 v173, v113
	v_cvt_f32_i32_e32 v172, v112
	v_cvt_f32_i32_e32 v171, v115
	v_cvt_f32_i32_e32 v170, v114
	s_waitcnt lgkmcnt(0)
; __device__ __forceinline__ unsigned cvt_pk_bf16(float lo, float hi) { f32x2_t v = {lo, hi}; bf16x2_t b = __builtin_convertvector(v, bf16x2_t); return __builtin_bit_cast(unsigned, b); }
; __device__ __forceinline__ float fast_rcp(float x) { return __builtin_amdgcn_rcpf(x); }
;     template <int KIND>
;     __device__ __forceinline__ void run(const f32x4 (&acc)[2][2][4][2], const Unit& u, int wr, int wc, int fr, int fq) const {
;     ...
;             for (int ai = 0; ai < 2; ++ai)
; #pragma unroll
;                 for (int m = 0; m < 4; ++m) { const int row = row0 + ai * HALF + m * 16; const float a = __shfl(ai ? sa_hi : sa_lo, 16 * m + fr);
;                     const f32x4 f0 = __builtin_convertvector(__builtin_bit_cast(i32x4, acc[ai][bj][m][0]), f32x4), f1 = __builtin_convertvector(__builtin_bit_cast(i32x4, acc[ai][bj][m][1]), f32x4);
;                     f32x2_t v[4] = {(f32x2_t){f0[0], f0[1]}, (f32x2_t){f0[2], f0[3]}, (f32x2_t){f1[0], f1[1]}, (f32x2_t){f1[2], f1[3]}};
; #pragma unroll
;                     for (int j = 0; j < 4; ++j) {
;                         v[j] = v[j] * (sc2[j] * (f32x2_t){a, a});
;                         if (KIND == 0 || KIND == 1 || KIND == 3) {
;                             const f32x2_t e = v[j] * (f32x2_t){-LOG2E, -LOG2E};
;                             const f32x2_t dn = (f32x2_t){__builtin_amdgcn_exp2f(e[0]), __builtin_amdgcn_exp2f(e[1])} + (f32x2_t){1.0f, 1.0f};
;                             const f32x2_t sg = (f32x2_t){fast_rcp(dn[0]), fast_rcp(dn[1])};
;                             if (KIND == 0) v[j] = v[j] * sg;
;                             else if (KIND == 3) v[j] = (v[j] * sg) * aux2[j];
;                             else { const f32x2_t f = __builtin_elementwise_fma((f32x2_t){1.0f, 1.0f} - aux2[j], sg, aux2[j]);
;                                 v[j] = (f32x2_t){fmaxf(__logf(f[0]), -60.0f), fmaxf(__logf(f[1]), -60.0f)}; }
;                         }
;                     }
;                     u32x4 w; w.x = cvt_pk_bf16(v[0][0], v[0][1]); w.y = cvt_pk_bf16(v[1][0], v[1][1]); w.z = cvt_pk_bf16(v[2][0], v[2][1]); w.w = cvt_pk_bf16(v[3][0], v[3][1]);
;                     *(u32x4*)(O + (size_t)row * NPROJ + col0 + bj * HALF) = w; }
	v_pk_mul_f32 v[182:183], v[164:165], v[168:169] op_sel_hi:[1,0]
	v_cvt_f32_i32_e32 v179, v109
	v_pk_mul_f32 v[172:173], v[172:173], v[182:183]
	v_cvt_f32_i32_e32 v178, v108
	v_pk_mul_f32 v[182:183], v[172:173], s[10:11] op_sel_hi:[1,0]
	v_cvt_f32_i32_e32 v177, v111
	v_exp_f32_e32 v182, v182
	v_exp_f32_e32 v183, v183
	v_cvt_f32_i32_e32 v176, v110
	ds_bpermute_b32 v174, v159, v208 offset:64
	v_pk_add_f32 v[182:183], v[182:183], 1.0 op_sel_hi:[1,0]
	s_nop 0
	v_rcp_f32_e32 v182, v182
	v_rcp_f32_e32 v183, v183
	s_waitcnt lgkmcnt(0)
	v_pk_mul_f32 v[196:197], v[164:165], v[174:175] op_sel_hi:[1,0]
	v_pk_mul_f32 v[172:173], v[172:173], v[182:183]
	v_pk_mul_f32 v[182:183], v[166:167], v[168:169] op_sel_hi:[1,0]
	v_pk_mul_f32 v[172:173], v[136:137], v[172:173]
	v_pk_mul_f32 v[170:171], v[170:171], v[182:183]
	s_nop 0
	v_pk_mul_f32 v[182:183], v[170:171], s[10:11] op_sel_hi:[1,0]
	s_nop 0
	v_exp_f32_e32 v182, v182
	v_exp_f32_e32 v183, v183
	s_nop 0
	v_pk_add_f32 v[182:183], v[182:183], 1.0 op_sel_hi:[1,0]
	s_nop 0
	v_rcp_f32_e32 v182, v182
	v_rcp_f32_e32 v183, v183
	s_nop 0
	v_pk_mul_f32 v[170:171], v[170:171], v[182:183]
	s_nop 0
	v_pk_mul_f32 v[182:183], v[138:139], v[170:171]
	v_pk_mul_f32 v[170:171], v[160:161], v[168:169] op_sel_hi:[1,0]
	s_nop 0
	v_pk_mul_f32 v[170:171], v[178:179], v[170:171]
	s_nop 0
	v_pk_mul_f32 v[178:179], v[170:171], s[10:11] op_sel_hi:[1,0]
	s_nop 0
	v_exp_f32_e32 v178, v178
	v_exp_f32_e32 v179, v179
	s_nop 0
	v_pk_add_f32 v[178:179], v[178:179], 1.0 op_sel_hi:[1,0]
	s_nop 0
	v_rcp_f32_e32 v178, v178
	v_rcp_f32_e32 v179, v179
	s_nop 0
	v_pk_mul_f32 v[170:171], v[170:171], v[178:179]
	s_nop 0
	v_pk_mul_f32 v[178:179], v[132:133], v[170:171]
	v_pk_mul_f32 v[170:171], v[150:151], v[168:169] op_sel_hi:[1,0]
	v_or_b32_e32 v169, 32, v175
	v_pk_mul_f32 v[170:171], v[176:177], v[170:171]
	s_nop 0
	v_pk_mul_f32 v[176:177], v[170:171], s[10:11] op_sel_hi:[1,0]
	s_nop 0
	v_exp_f32_e32 v176, v176
	v_exp_f32_e32 v177, v177
	s_nop 0
	v_pk_add_f32 v[176:177], v[176:177], 1.0 op_sel_hi:[1,0]
	s_nop 0
	v_rcp_f32_e32 v176, v176
	v_rcp_f32_e32 v177, v177
	s_nop 0
	v_pk_mul_f32 v[170:171], v[170:171], v[176:177]
	s_nop 0
	v_pk_mul_f32 v[176:177], v[134:135], v[170:171]
	v_cvt_pk_bf16_f32 v170, v172, v173
	v_cvt_pk_bf16_f32 v173, v176, v177
	v_mad_i64_i32 v[176:177], s[2:3], v169, s81, v[188:189]
	v_cvt_pk_bf16_f32 v171, v182, v183
	v_cvt_pk_bf16_f32 v172, v178, v179
	v_lshl_add_u64 v[182:183], v[176:177], 0, v[192:193]
	global_store_dwordx4 v[182:183], v[170:173], off
	ds_bpermute_b32 v170, v159, v209 offset:192
	v_cvt_f32_i32_e32 v177, v105
	v_cvt_f32_i32_e32 v176, v104
	v_cvt_f32_i32_e32 v173, v107
	v_cvt_f32_i32_e32 v172, v106
	s_waitcnt lgkmcnt(0)
	v_pk_mul_f32 v[186:187], v[164:165], v[170:171] op_sel_hi:[1,0]
	v_cvt_f32_i32_e32 v179, v103
	v_pk_mul_f32 v[176:177], v[176:177], v[186:187]
	v_cvt_f32_i32_e32 v178, v102
	v_pk_mul_f32 v[186:187], v[176:177], s[10:11] op_sel_hi:[1,0]
	v_or_b32_e32 v169, 48, v175
	v_exp_f32_e32 v186, v186
	v_exp_f32_e32 v187, v187
	s_nop 0
	v_pk_add_f32 v[186:187], v[186:187], 1.0 op_sel_hi:[1,0]
	s_nop 0
	v_rcp_f32_e32 v186, v186
	v_rcp_f32_e32 v187, v187
	s_nop 0
	v_pk_mul_f32 v[176:177], v[176:177], v[186:187]
	v_pk_mul_f32 v[186:187], v[166:167], v[170:171] op_sel_hi:[1,0]
	v_pk_mul_f32 v[176:177], v[136:137], v[176:177]
	v_pk_mul_f32 v[172:173], v[172:173], v[186:187]
	v_cvt_pk_bf16_f32 v176, v176, v177
	v_pk_mul_f32 v[186:187], v[172:173], s[10:11] op_sel_hi:[1,0]
	s_nop 0
	v_exp_f32_e32 v186, v186
	v_exp_f32_e32 v187, v187
	s_nop 0
	v_pk_add_f32 v[186:187], v[186:187], 1.0 op_sel_hi:[1,0]
	s_nop 0
	v_rcp_f32_e32 v186, v186
	v_rcp_f32_e32 v187, v187
	s_nop 0
	v_pk_mul_f32 v[172:173], v[172:173], v[186:187]
	v_pk_mul_f32 v[186:187], v[160:161], v[170:171] op_sel_hi:[1,0]
	v_pk_mul_f32 v[172:173], v[138:139], v[172:173]
	v_pk_mul_f32 v[184:185], v[184:185], v[186:187]
	v_cvt_pk_bf16_f32 v177, v172, v173
	v_pk_mul_f32 v[186:187], v[184:185], s[10:11] op_sel_hi:[1,0]
	v_mad_i64_i32 v[172:173], s[2:3], v169, s81, v[188:189]
	v_exp_f32_e32 v186, v186
	v_exp_f32_e32 v187, v187
	v_add_u32_e32 v169, 0x80, v175
	v_pk_add_f32 v[186:187], v[186:187], 1.0 op_sel_hi:[1,0]
	s_nop 0
	v_rcp_f32_e32 v186, v186
	v_rcp_f32_e32 v187, v187
	s_nop 0
	v_pk_mul_f32 v[184:185], v[184:185], v[186:187]
	v_pk_mul_f32 v[186:187], v[150:151], v[170:171] op_sel_hi:[1,0]
	v_pk_mul_f32 v[184:185], v[132:133], v[184:185]
	v_pk_mul_f32 v[178:179], v[178:179], v[186:187]
	s_nop 0
	v_pk_mul_f32 v[186:187], v[178:179], s[10:11] op_sel_hi:[1,0]
	s_nop 0
	v_exp_f32_e32 v186, v186
	v_exp_f32_e32 v187, v187
	s_nop 0
	v_pk_add_f32 v[186:187], v[186:187], 1.0 op_sel_hi:[1,0]
	s_nop 0
	v_rcp_f32_e32 v186, v186
	v_rcp_f32_e32 v187, v187
	s_nop 0
	v_pk_mul_f32 v[178:179], v[178:179], v[186:187]
	s_nop 0
	v_pk_mul_f32 v[186:187], v[134:135], v[178:179]
	v_cvt_pk_bf16_f32 v178, v184, v185
	v_lshl_add_u64 v[184:185], v[172:173], 0, v[192:193]
	ds_bpermute_b32 v172, v159, v208
	v_cvt_pk_bf16_f32 v179, v186, v187
	global_store_dwordx4 v[184:185], v[176:179], off
	v_cvt_f32_i32_e32 v187, v95
	v_cvt_f32_i32_e32 v186, v94
	v_cvt_f32_i32_e32 v179, v97
	v_cvt_f32_i32_e32 v178, v96
	s_waitcnt lgkmcnt(0)
; __device__ __forceinline__ unsigned cvt_pk_bf16(float lo, float hi) { f32x2_t v = {lo, hi}; bf16x2_t b = __builtin_convertvector(v, bf16x2_t); return __builtin_bit_cast(unsigned, b); }
; __device__ __forceinline__ float fast_rcp(float x) { return __builtin_amdgcn_rcpf(x); }
;     template <int KIND>
;     __device__ __forceinline__ void run(const f32x4 (&acc)[2][2][4][2], const Unit& u, int wr, int wc, int fr, int fq) const {
;     ...
;             for (int ai = 0; ai < 2; ++ai)
; #pragma unroll
;                 for (int m = 0; m < 4; ++m) { const int row = row0 + ai * HALF + m * 16; const float a = __shfl(ai ? sa_hi : sa_lo, 16 * m + fr);
;                     const f32x4 f0 = __builtin_convertvector(__builtin_bit_cast(i32x4, acc[ai][bj][m][0]), f32x4), f1 = __builtin_convertvector(__builtin_bit_cast(i32x4, acc[ai][bj][m][1]), f32x4);
;                     f32x2_t v[4] = {(f32x2_t){f0[0], f0[1]}, (f32x2_t){f0[2], f0[3]}, (f32x2_t){f1[0], f1[1]}, (f32x2_t){f1[2], f1[3]}};
; #pragma unroll
;                     for (int j = 0; j < 4; ++j) {
;                         v[j] = v[j] * (sc2[j] * (f32x2_t){a, a});
;                         if (KIND == 0 || KIND == 1 || KIND == 3) {
;                             const f32x2_t e = v[j] * (f32x2_t){-LOG2E, -LOG2E};
;                             const f32x2_t dn = (f32x2_t){__builtin_amdgcn_exp2f(e[0]), __builtin_amdgcn_exp2f(e[1])} + (f32x2_t){1.0f, 1.0f};
;                             const f32x2_t sg = (f32x2_t){fast_rcp(dn[0]), fast_rcp(dn[1])};
;                             if (KIND == 0) v[j] = v[j] * sg;
;                             else if (KIND == 3) v[j] = (v[j] * sg) * aux2[j];
;                             else { const f32x2_t f = __builtin_elementwise_fma((f32x2_t){1.0f, 1.0f} - aux2[j], sg, aux2[j]);
;                                 v[j] = (f32x2_t){fmaxf(__logf(f[0]), -60.0f), fmaxf(__logf(f[1]), -60.0f)}; }
;                         }
;                     }
;                     u32x4 w; w.x = cvt_pk_bf16(v[0][0], v[0][1]); w.y = cvt_pk_bf16(v[1][0], v[1][1]); w.z = cvt_pk_bf16(v[2][0], v[2][1]); w.w = cvt_pk_bf16(v[3][0], v[3][1]);
;                     *(u32x4*)(O + (size_t)row * NPROJ + col0 + bj * HALF) = w; }
	v_pk_mul_f32 v[194:195], v[164:165], v[172:173] op_sel_hi:[1,0]
	v_cvt_f32_i32_e32 v177, v99
	v_cvt_f32_i32_e32 v176, v98
	v_pk_mul_f32 v[178:179], v[178:179], v[194:195]
	s_nop 0
	v_pk_mul_f32 v[194:195], v[178:179], s[10:11] op_sel_hi:[1,0]
	s_nop 0
	v_exp_f32_e32 v194, v194
	v_exp_f32_e32 v195, v195
	s_nop 0
	v_pk_add_f32 v[194:195], v[194:195], 1.0 op_sel_hi:[1,0]
	s_nop 0
	v_rcp_f32_e32 v194, v194
	v_rcp_f32_e32 v195, v195
	s_nop 0
	v_pk_mul_f32 v[178:179], v[178:179], v[194:195]
	v_pk_mul_f32 v[194:195], v[166:167], v[172:173] op_sel_hi:[1,0]
	v_pk_mul_f32 v[178:179], v[136:137], v[178:179]
	v_pk_mul_f32 v[176:177], v[176:177], v[194:195]
	s_nop 0
	v_pk_mul_f32 v[194:195], v[176:177], s[10:11] op_sel_hi:[1,0]
	s_nop 0
	v_exp_f32_e32 v194, v194
	v_exp_f32_e32 v195, v195
	s_nop 0
	v_pk_add_f32 v[194:195], v[194:195], 1.0 op_sel_hi:[1,0]
	s_nop 0
	v_rcp_f32_e32 v194, v194
	v_rcp_f32_e32 v195, v195
	s_nop 0
	v_pk_mul_f32 v[176:177], v[176:177], v[194:195]
	s_nop 0
	v_pk_mul_f32 v[194:195], v[138:139], v[176:177]
	v_pk_mul_f32 v[176:177], v[160:161], v[172:173] op_sel_hi:[1,0]
	s_nop 0
	v_pk_mul_f32 v[176:177], v[190:191], v[176:177]
	s_nop 0
	v_pk_mul_f32 v[190:191], v[176:177], s[10:11] op_sel_hi:[1,0]
	s_nop 0
	v_exp_f32_e32 v190, v190
	v_exp_f32_e32 v191, v191
	s_nop 0
	v_pk_add_f32 v[190:191], v[190:191], 1.0 op_sel_hi:[1,0]
	s_nop 0
	v_rcp_f32_e32 v190, v190
	v_rcp_f32_e32 v191, v191
	s_nop 0
	v_pk_mul_f32 v[176:177], v[176:177], v[190:191]
	s_nop 0
	v_pk_mul_f32 v[190:191], v[132:133], v[176:177]
	v_pk_mul_f32 v[176:177], v[150:151], v[172:173] op_sel_hi:[1,0]
	s_nop 0
	v_pk_mul_f32 v[176:177], v[186:187], v[176:177]
	s_nop 0
	v_pk_mul_f32 v[186:187], v[176:177], s[10:11] op_sel_hi:[1,0]
	s_nop 0
	v_exp_f32_e32 v186, v186
	v_exp_f32_e32 v187, v187
	s_nop 0
	v_pk_add_f32 v[186:187], v[186:187], 1.0 op_sel_hi:[1,0]
	s_nop 0
	v_rcp_f32_e32 v186, v186
	v_rcp_f32_e32 v187, v187
	s_nop 0
	v_pk_mul_f32 v[176:177], v[176:177], v[186:187]
	s_nop 0
	v_pk_mul_f32 v[186:187], v[134:135], v[176:177]
	v_cvt_pk_bf16_f32 v176, v178, v179
	v_cvt_pk_bf16_f32 v179, v186, v187
	v_mad_i64_i32 v[186:187], s[2:3], v169, s81, v[188:189]
	v_cvt_pk_bf16_f32 v177, v194, v195
	v_cvt_pk_bf16_f32 v178, v190, v191
	v_lshl_add_u64 v[186:187], v[186:187], 0, v[192:193]
	global_store_dwordx4 v[186:187], v[176:179], off
	v_cvt_f32_i32_e32 v195, v85
	v_cvt_f32_i32_e32 v194, v84
	v_cvt_f32_i32_e32 v179, v89
	v_cvt_f32_i32_e32 v178, v88
	v_cvt_f32_i32_e32 v177, v91
	v_cvt_f32_i32_e32 v176, v90
	v_cvt_f32_i32_e32 v191, v87
	v_pk_mul_f32 v[178:179], v[178:179], v[196:197]
	v_cvt_f32_i32_e32 v190, v86
	v_pk_mul_f32 v[196:197], v[178:179], s[10:11] op_sel_hi:[1,0]
	v_add_u32_e32 v169, 0x90, v175
	v_exp_f32_e32 v196, v196
	v_exp_f32_e32 v197, v197
	s_nop 0
	v_pk_add_f32 v[196:197], v[196:197], 1.0 op_sel_hi:[1,0]
	s_nop 0
	v_rcp_f32_e32 v196, v196
	v_rcp_f32_e32 v197, v197
	s_nop 0
	v_pk_mul_f32 v[178:179], v[178:179], v[196:197]
	v_pk_mul_f32 v[196:197], v[166:167], v[174:175] op_sel_hi:[1,0]
	v_pk_mul_f32 v[178:179], v[136:137], v[178:179]
	v_pk_mul_f32 v[176:177], v[176:177], v[196:197]
	s_nop 0
	v_pk_mul_f32 v[196:197], v[176:177], s[10:11] op_sel_hi:[1,0]
	s_nop 0
	v_exp_f32_e32 v196, v196
	v_exp_f32_e32 v197, v197
	s_nop 0
	v_pk_add_f32 v[196:197], v[196:197], 1.0 op_sel_hi:[1,0]
	s_nop 0
	v_rcp_f32_e32 v196, v196
	v_rcp_f32_e32 v197, v197
	s_nop 0
	v_pk_mul_f32 v[176:177], v[176:177], v[196:197]
	s_nop 0
	v_pk_mul_f32 v[196:197], v[138:139], v[176:177]
	v_pk_mul_f32 v[176:177], v[160:161], v[174:175] op_sel_hi:[1,0]
	s_nop 0
	v_pk_mul_f32 v[176:177], v[194:195], v[176:177]
	s_nop 0
	v_pk_mul_f32 v[194:195], v[176:177], s[10:11] op_sel_hi:[1,0]
	s_nop 0
	v_exp_f32_e32 v194, v194
	v_exp_f32_e32 v195, v195
	s_nop 0
	v_pk_add_f32 v[194:195], v[194:195], 1.0 op_sel_hi:[1,0]
	s_nop 0
	v_rcp_f32_e32 v194, v194
	v_rcp_f32_e32 v195, v195
	s_nop 0
	v_pk_mul_f32 v[176:177], v[176:177], v[194:195]
	s_nop 0
	v_pk_mul_f32 v[194:195], v[132:133], v[176:177]
	v_pk_mul_f32 v[176:177], v[150:151], v[174:175] op_sel_hi:[1,0]
	s_nop 0
	v_pk_mul_f32 v[176:177], v[190:191], v[176:177]
	s_nop 0
	v_pk_mul_f32 v[190:191], v[176:177], s[10:11] op_sel_hi:[1,0]
	s_nop 0
	v_exp_f32_e32 v190, v190
	v_exp_f32_e32 v191, v191
	s_nop 0
	v_pk_add_f32 v[190:191], v[190:191], 1.0 op_sel_hi:[1,0]
	s_nop 0
	v_rcp_f32_e32 v190, v190
	v_rcp_f32_e32 v191, v191
	s_nop 0
	v_pk_mul_f32 v[176:177], v[176:177], v[190:191]
	s_nop 0
	v_pk_mul_f32 v[190:191], v[134:135], v[176:177]
	v_cvt_pk_bf16_f32 v176, v178, v179
	v_cvt_pk_bf16_f32 v179, v190, v191
	v_mad_i64_i32 v[190:191], s[2:3], v169, s81, v[188:189]
	v_cvt_pk_bf16_f32 v177, v196, v197
	v_cvt_pk_bf16_f32 v178, v194, v195
	v_lshl_add_u64 v[190:191], v[190:191], 0, v[192:193]
	global_store_dwordx4 v[190:191], v[176:179], off
	ds_bpermute_b32 v176, v159, v208 offset:128
	v_cvt_f32_i32_e32 v195, v81
	v_cvt_f32_i32_e32 v194, v80
	v_cvt_f32_i32_e32 v179, v83
	v_cvt_f32_i32_e32 v178, v82
	s_waitcnt lgkmcnt(0)
; __device__ __forceinline__ unsigned cvt_pk_bf16(float lo, float hi) { f32x2_t v = {lo, hi}; bf16x2_t b = __builtin_convertvector(v, bf16x2_t); return __builtin_bit_cast(unsigned, b); }
; __device__ __forceinline__ float fast_rcp(float x) { return __builtin_amdgcn_rcpf(x); }
;     template <int KIND>
;     __device__ __forceinline__ void run(const f32x4 (&acc)[2][2][4][2], const Unit& u, int wr, int wc, int fr, int fq) const {
;     ...
;             for (int ai = 0; ai < 2; ++ai)
; #pragma unroll
;                 for (int m = 0; m < 4; ++m) { const int row = row0 + ai * HALF + m * 16; const float a = __shfl(ai ? sa_hi : sa_lo, 16 * m + fr);
;                     const f32x4 f0 = __builtin_convertvector(__builtin_bit_cast(i32x4, acc[ai][bj][m][0]), f32x4), f1 = __builtin_convertvector(__builtin_bit_cast(i32x4, acc[ai][bj][m][1]), f32x4);
;                     f32x2_t v[4] = {(f32x2_t){f0[0], f0[1]}, (f32x2_t){f0[2], f0[3]}, (f32x2_t){f1[0], f1[1]}, (f32x2_t){f1[2], f1[3]}};
; #pragma unroll
;                     for (int j = 0; j < 4; ++j) {
;                         v[j] = v[j] * (sc2[j] * (f32x2_t){a, a});
;                         if (KIND == 0 || KIND == 1 || KIND == 3) {
;                             const f32x2_t e = v[j] * (f32x2_t){-LOG2E, -LOG2E};
;                             const f32x2_t dn = (f32x2_t){__builtin_amdgcn_exp2f(e[0]), __builtin_amdgcn_exp2f(e[1])} + (f32x2_t){1.0f, 1.0f};
;                             const f32x2_t sg = (f32x2_t){fast_rcp(dn[0]), fast_rcp(dn[1])};
;                             if (KIND == 0) v[j] = v[j] * sg;
;                             else if (KIND == 3) v[j] = (v[j] * sg) * aux2[j];
;                             else { const f32x2_t f = __builtin_elementwise_fma((f32x2_t){1.0f, 1.0f} - aux2[j], sg, aux2[j]);
;                                 v[j] = (f32x2_t){fmaxf(__logf(f[0]), -60.0f), fmaxf(__logf(f[1]), -60.0f)}; }
;                         }
;                     }
;                     u32x4 w; w.x = cvt_pk_bf16(v[0][0], v[0][1]); w.y = cvt_pk_bf16(v[1][0], v[1][1]); w.z = cvt_pk_bf16(v[2][0], v[2][1]); w.w = cvt_pk_bf16(v[3][0], v[3][1]);
;                     *(u32x4*)(O + (size_t)row * NPROJ + col0 + bj * HALF) = w; }
	v_pk_mul_f32 v[200:201], v[164:165], v[176:177] op_sel_hi:[1,0]
	v_cvt_f32_i32_e32 v197, v79
	v_pk_mul_f32 v[194:195], v[194:195], v[200:201]
	v_cvt_f32_i32_e32 v196, v78
	v_pk_mul_f32 v[200:201], v[194:195], s[10:11] op_sel_hi:[1,0]
	v_add_u32_e32 v169, 0xa0, v175
	v_exp_f32_e32 v200, v200
	v_exp_f32_e32 v201, v201
	s_nop 0
	v_pk_add_f32 v[200:201], v[200:201], 1.0 op_sel_hi:[1,0]
	s_nop 0
	v_rcp_f32_e32 v200, v200
	v_rcp_f32_e32 v201, v201
	s_nop 0
	v_pk_mul_f32 v[194:195], v[194:195], v[200:201]
	v_pk_mul_f32 v[200:201], v[166:167], v[176:177] op_sel_hi:[1,0]
	v_pk_mul_f32 v[194:195], v[136:137], v[194:195]
	v_pk_mul_f32 v[178:179], v[178:179], v[200:201]
	s_nop 0
	v_pk_mul_f32 v[200:201], v[178:179], s[10:11] op_sel_hi:[1,0]
	s_nop 0
	v_exp_f32_e32 v200, v200
	v_exp_f32_e32 v201, v201
	s_nop 0
	v_pk_add_f32 v[200:201], v[200:201], 1.0 op_sel_hi:[1,0]
	s_nop 0
	v_rcp_f32_e32 v200, v200
	v_rcp_f32_e32 v201, v201
	s_nop 0
	v_pk_mul_f32 v[178:179], v[178:179], v[200:201]
	v_pk_mul_f32 v[200:201], v[160:161], v[176:177] op_sel_hi:[1,0]
	v_pk_mul_f32 v[178:179], v[138:139], v[178:179]
	v_pk_mul_f32 v[198:199], v[198:199], v[200:201]
	s_nop 0
	v_pk_mul_f32 v[200:201], v[198:199], s[10:11] op_sel_hi:[1,0]
	s_nop 0
	v_exp_f32_e32 v200, v200
	v_exp_f32_e32 v201, v201
	s_nop 0
	v_pk_add_f32 v[200:201], v[200:201], 1.0 op_sel_hi:[1,0]
	s_nop 0
	v_rcp_f32_e32 v200, v200
	v_rcp_f32_e32 v201, v201
	s_nop 0
	v_pk_mul_f32 v[198:199], v[198:199], v[200:201]
	v_pk_mul_f32 v[200:201], v[150:151], v[176:177] op_sel_hi:[1,0]
	v_pk_mul_f32 v[198:199], v[132:133], v[198:199]
	v_pk_mul_f32 v[196:197], v[196:197], v[200:201]
	v_cvt_pk_bf16_f32 v198, v198, v199
	v_pk_mul_f32 v[200:201], v[196:197], s[10:11] op_sel_hi:[1,0]
	s_nop 0
	v_exp_f32_e32 v200, v200
	v_exp_f32_e32 v201, v201
	s_nop 0
	v_pk_add_f32 v[200:201], v[200:201], 1.0 op_sel_hi:[1,0]
	s_nop 0
	v_rcp_f32_e32 v200, v200
	v_rcp_f32_e32 v201, v201
	s_nop 0
	v_pk_mul_f32 v[196:197], v[196:197], v[200:201]
	s_nop 0
	v_pk_mul_f32 v[200:201], v[134:135], v[196:197]
	v_cvt_pk_bf16_f32 v197, v178, v179
	v_mad_i64_i32 v[178:179], s[2:3], v169, s81, v[188:189]
	v_cvt_pk_bf16_f32 v196, v194, v195
	v_lshl_add_u64 v[194:195], v[178:179], 0, v[192:193]
	ds_bpermute_b32 v178, v159, v208 offset:192
	v_cvt_pk_bf16_f32 v199, v200, v201
	global_store_dwordx4 v[194:195], v[196:199], off
	v_cvt_f32_i32_e32 v201, v71
	v_cvt_f32_i32_e32 v200, v70
	v_cvt_f32_i32_e32 v199, v73
	v_cvt_f32_i32_e32 v198, v72
	s_waitcnt lgkmcnt(0)
	v_pk_mul_f32 v[164:165], v[164:165], v[178:179] op_sel_hi:[1,0]
	v_cvt_f32_i32_e32 v197, v75
	v_cvt_f32_i32_e32 v196, v74
	v_pk_mul_f32 v[164:165], v[198:199], v[164:165]
	v_pk_mul_f32 v[160:161], v[160:161], v[178:179] op_sel_hi:[1,0]
	v_pk_mul_f32 v[198:199], v[164:165], s[10:11] op_sel_hi:[1,0]
	v_pk_mul_f32 v[160:161], v[202:203], v[160:161]
	v_exp_f32_e32 v198, v198
	v_exp_f32_e32 v199, v199
	v_add_u32_e32 v159, 0xb0, v175
	v_pk_add_f32 v[198:199], v[198:199], 1.0 op_sel_hi:[1,0]
	s_nop 0
	v_rcp_f32_e32 v198, v198
	v_rcp_f32_e32 v199, v199
	s_nop 0
	v_pk_mul_f32 v[164:165], v[164:165], v[198:199]
	s_nop 0
	v_pk_mul_f32 v[136:137], v[136:137], v[164:165]
	v_pk_mul_f32 v[164:165], v[166:167], v[178:179] op_sel_hi:[1,0]
	s_nop 0
	v_pk_mul_f32 v[164:165], v[196:197], v[164:165]
	s_nop 0
	v_pk_mul_f32 v[166:167], v[164:165], s[10:11] op_sel_hi:[1,0]
	s_nop 0
	v_exp_f32_e32 v166, v166
	v_exp_f32_e32 v167, v167
	s_nop 0
	v_pk_add_f32 v[166:167], v[166:167], 1.0 op_sel_hi:[1,0]
	s_nop 0
	v_rcp_f32_e32 v166, v166
	v_rcp_f32_e32 v167, v167
	s_nop 0
	v_pk_mul_f32 v[164:165], v[164:165], v[166:167]
	s_nop 0
	v_pk_mul_f32 v[138:139], v[138:139], v[164:165]
	v_pk_mul_f32 v[164:165], v[160:161], s[10:11] op_sel_hi:[1,0]
	s_nop 0
	v_exp_f32_e32 v164, v164
	v_exp_f32_e32 v165, v165
	s_nop 0
	v_pk_add_f32 v[164:165], v[164:165], 1.0 op_sel_hi:[1,0]
	s_nop 0
	v_rcp_f32_e32 v164, v164
	v_rcp_f32_e32 v165, v165
	s_nop 0
	v_pk_mul_f32 v[160:161], v[160:161], v[164:165]
	s_nop 0
	v_pk_mul_f32 v[160:161], v[132:133], v[160:161]
	v_pk_mul_f32 v[132:133], v[150:151], v[178:179] op_sel_hi:[1,0]
	s_nop 0
	v_pk_mul_f32 v[132:133], v[200:201], v[132:133]
	s_nop 0
	v_pk_mul_f32 v[150:151], v[132:133], s[10:11] op_sel_hi:[1,0]
	s_nop 0
	v_exp_f32_e32 v150, v150
	v_exp_f32_e32 v151, v151
	s_nop 0
	v_pk_add_f32 v[150:151], v[150:151], 1.0 op_sel_hi:[1,0]
	s_nop 0
	v_rcp_f32_e32 v150, v150
	v_rcp_f32_e32 v151, v151
	s_nop 0
	v_pk_mul_f32 v[132:133], v[132:133], v[150:151]
	s_nop 0
	v_pk_mul_f32 v[150:151], v[134:135], v[132:133]
	v_cvt_pk_bf16_f32 v132, v136, v137
	v_mad_i64_i32 v[136:137], s[2:3], v159, s81, v[188:189]
	v_cvt_pk_bf16_f32 v133, v138, v139
	v_cvt_pk_bf16_f32 v134, v160, v161
	v_cvt_pk_bf16_f32 v135, v150, v151
	v_lshl_add_u64 v[136:137], v[136:137], 0, v[192:193]
	global_store_dwordx4 v[136:137], v[132:135], off
	s_waitcnt vmcnt(8)
;     template <int KIND>
;     __device__ __forceinline__ void run(const f32x4 (&acc)[2][2][4][2], const Unit& u, int wr, int wc, int fr, int fq) const {
;     ...
;         for (int bj = 0; bj < 2; ++bj) {
;             f32x2_t sc2[4], aux2[4];
; #pragma unroll
;             for (int j = 0; j < 4; ++j) {
;                 const float k0 = (KIND == 4) ? (0.125f * LOG2E / 127.0f) : (1.0f / 127.0f);
;                 sc2[j] = (f32x2_t){wmax[col0 + bj * HALF + 2 * j] * k0, wmax[col0 + bj * HALF + 2 * j + 1] * k0};
;                 if (KIND == 1) aux2[j] = (f32x2_t){lb[col0 - C_HG + bj * HALF + 2 * j], lb[col0 - C_HG + bj * HALF + 2 * j + 1]};
;                 else if (KIND == 3) aux2[j] = (f32x2_t){gain[col0 - C_HGATE + bj * HALF + 2 * j], gain[col0 - C_HGATE + bj * HALF + 2 * j + 1]};
;                 else aux2[j] = (f32x2_t){0.f, 0.f};
;             }
; #pragma unroll
;             for (int ai = 0; ai < 2; ++ai)
; #pragma unroll
;                 for (int m = 0; m < 4; ++m) { const int row = row0 + ai * HALF + m * 16; const float a = __shfl(ai ? sa_hi : sa_lo, 16 * m + fr);
;                     const f32x4 f0 = __builtin_convertvector(__builtin_bit_cast(i32x4, acc[ai][bj][m][0]), f32x4), f1 = __builtin_convertvector(__builtin_bit_cast(i32x4, acc[ai][bj][m][1]), f32x4);
;                     f32x2_t v[4] = {(f32x2_t){f0[0], f0[1]}, (f32x2_t){f0[2], f0[3]}, (f32x2_t){f1[0], f1[1]}, (f32x2_t){f1[2], f1[3]}};
; #pragma unroll
;                     for (int j = 0; j < 4; ++j) {
;                         v[j] = v[j] * (sc2[j] * (f32x2_t){a, a});
;                         if (KIND == 0 || KIND == 1 || KIND == 3) {
;                             const f32x2_t e = v[j] * (f32x2_t){-LOG2E, -LOG2E};
;                             const f32x2_t dn = (f32x2_t){__builtin_amdgcn_exp2f(e[0]), __builtin_amdgcn_exp2f(e[1])} + (f32x2_t){1.0f, 1.0f};
;                             const f32x2_t sg = (f32x2_t){fast_rcp(dn[0]), fast_rcp(dn[1])};
;                             if (KIND == 0) v[j] = v[j] * sg;
;                             else if (KIND == 3) v[j] = (v[j] * sg) * aux2[j];
;                             else { const f32x2_t f = __builtin_elementwise_fma((f32x2_t){1.0f, 1.0f} - aux2[j], sg, aux2[j]);
;                                 v[j] = (f32x2_t){fmaxf(__logf(f[0]), -60.0f), fmaxf(__logf(f[1]), -60.0f)}; }
;                         }
;                     }
	s_nop 0
	v_mov_b32_e32 v196, v236
	v_mov_b32_e32 v197, v237
	v_mov_b32_e32 v198, v238
	v_mov_b32_e32 v199, v239
	v_mov_b32_e32 v164, v240
	v_mov_b32_e32 v165, v241
	v_mov_b32_e32 v166, v242
	v_mov_b32_e32 v167, v243
	v_mov_b32_e32 v136, v244
	v_mov_b32_e32 v137, v245
	v_mov_b32_e32 v138, v246
	v_mov_b32_e32 v139, v247
	v_mov_b32_e32 v132, v128
	v_mov_b32_e32 v133, v129
	v_mov_b32_e32 v134, v130
	v_mov_b32_e32 v135, v131
	v_mad_i64_i32 v[150:151], s[2:3], v159, s81, 0
	s_movk_i32 s2, 0xea00
	s_mov_b32 s3, -1
	v_cvt_f32_i32_e32 v189, v63
	v_cvt_f32_i32_e32 v188, v62
	v_cvt_f32_i32_e32 v193, v61
	v_cvt_f32_i32_e32 v192, v60
	v_pk_mul_f32 v[152:153], v[198:199], s[6:7] op_sel_hi:[1,0]
	v_pk_mul_f32 v[160:161], v[164:165], s[6:7] op_sel_hi:[1,0]
	v_pk_mul_f32 v[164:165], v[166:167], s[6:7] op_sel_hi:[1,0]
	v_pk_mul_f32 v[198:199], v[66:67], v[160:161] op_sel_hi:[0,1]
	v_pk_mul_f32 v[188:189], v[188:189], v[198:199]
	v_cvt_f32_i32_e32 v167, v65
	v_pk_mul_f32 v[198:199], v[188:189], s[10:11] op_sel_hi:[1,0]
	v_cvt_f32_i32_e32 v166, v64
	v_exp_f32_e32 v198, v198
	v_exp_f32_e32 v199, v199
	v_pk_mul_f32 v[156:157], v[196:197], s[6:7] op_sel_hi:[1,0]
	v_cvt_f32_i32_e32 v197, v59
	v_cvt_f32_i32_e32 v196, v58
	v_pk_add_f32 v[198:199], v[198:199], 1.0 op_sel_hi:[1,0]
	s_nop 0
	v_rcp_f32_e32 v198, v198
	v_rcp_f32_e32 v199, v199
	s_nop 0
	v_pk_mul_f32 v[188:189], v[188:189], v[198:199]
	v_pk_mul_f32 v[198:199], v[66:67], v[164:165] op_sel_hi:[0,1]
	v_pk_mul_f32 v[166:167], v[166:167], v[198:199]
	v_pk_mul_f32 v[188:189], v[136:137], v[188:189]
	v_pk_mul_f32 v[198:199], v[166:167], s[10:11] op_sel_hi:[1,0]
	s_nop 0
	v_exp_f32_e32 v198, v198
	v_exp_f32_e32 v199, v199
	s_nop 0
	v_pk_add_f32 v[198:199], v[198:199], 1.0 op_sel_hi:[1,0]
	s_nop 0
	v_rcp_f32_e32 v198, v198
	v_rcp_f32_e32 v199, v199
	s_nop 0
	v_pk_mul_f32 v[166:167], v[166:167], v[198:199]
	v_pk_mul_f32 v[198:199], v[66:67], v[156:157] op_sel_hi:[0,1]
	v_pk_mul_f32 v[196:197], v[196:197], v[198:199]
	v_pk_mul_f32 v[166:167], v[138:139], v[166:167]
	v_pk_mul_f32 v[198:199], v[196:197], s[10:11] op_sel_hi:[1,0]
	s_nop 0
	v_exp_f32_e32 v198, v198
	v_exp_f32_e32 v199, v199
	s_nop 0
	v_pk_add_f32 v[198:199], v[198:199], 1.0 op_sel_hi:[1,0]
	s_nop 0
	v_rcp_f32_e32 v198, v198
	v_rcp_f32_e32 v199, v199
	s_nop 0
	v_pk_mul_f32 v[196:197], v[196:197], v[198:199]
	v_pk_mul_f32 v[198:199], v[132:133], v[196:197]
	v_pk_mul_f32 v[196:197], v[66:67], v[152:153] op_sel_hi:[0,1]
	v_pk_mul_f32 v[192:193], v[192:193], v[196:197]
	v_cvt_pk_bf16_f32 v198, v198, v199
	v_pk_mul_f32 v[196:197], v[192:193], s[10:11] op_sel_hi:[1,0]
	s_nop 0
	v_exp_f32_e32 v196, v196
	v_exp_f32_e32 v197, v197
	s_nop 0
	v_pk_add_f32 v[196:197], v[196:197], 1.0 op_sel_hi:[1,0]
	s_nop 0
	v_rcp_f32_e32 v196, v196
	v_rcp_f32_e32 v197, v197
	s_nop 0
	v_pk_mul_f32 v[192:193], v[192:193], v[196:197]
	v_cvt_pk_bf16_f32 v197, v166, v167
	v_cvt_f32_i32_e32 v167, v55
	v_cvt_f32_i32_e32 v166, v54
	v_pk_mul_f32 v[192:193], v[134:135], v[192:193]
	v_cvt_pk_bf16_f32 v196, v188, v189
	v_cvt_pk_bf16_f32 v199, v192, v193
	global_store_dwordx4 v[162:163], v[196:199], off offset:256
	v_cvt_f32_i32_e32 v163, v57
	v_cvt_f32_i32_e32 v162, v56
	v_pk_mul_f32 v[196:197], v[158:159], v[160:161] op_sel_hi:[0,1]
	v_pk_mul_f32 v[166:167], v[166:167], v[196:197]
	v_cvt_f32_i32_e32 v193, v51
	v_pk_mul_f32 v[196:197], v[166:167], s[10:11] op_sel_hi:[1,0]
	v_cvt_f32_i32_e32 v192, v50
	v_exp_f32_e32 v196, v196
	v_exp_f32_e32 v197, v197
	v_cvt_f32_i32_e32 v189, v53
	v_cvt_f32_i32_e32 v188, v52
	v_pk_add_f32 v[196:197], v[196:197], 1.0 op_sel_hi:[1,0]
	s_nop 0
	v_rcp_f32_e32 v196, v196
	v_rcp_f32_e32 v197, v197
	s_nop 0
	v_pk_mul_f32 v[166:167], v[166:167], v[196:197]
	v_pk_mul_f32 v[196:197], v[158:159], v[164:165] op_sel_hi:[0,1]
	v_pk_mul_f32 v[162:163], v[162:163], v[196:197]
	v_pk_mul_f32 v[166:167], v[136:137], v[166:167]
	v_pk_mul_f32 v[196:197], v[162:163], s[10:11] op_sel_hi:[1,0]
	s_nop 0
	v_exp_f32_e32 v196, v196
	v_exp_f32_e32 v197, v197
	s_nop 0
	v_pk_add_f32 v[196:197], v[196:197], 1.0 op_sel_hi:[1,0]
	s_nop 0
	v_rcp_f32_e32 v196, v196
	v_rcp_f32_e32 v197, v197
	s_nop 0
	v_pk_mul_f32 v[162:163], v[162:163], v[196:197]
	v_pk_mul_f32 v[196:197], v[158:159], v[156:157] op_sel_hi:[0,1]
	v_pk_mul_f32 v[192:193], v[192:193], v[196:197]
	v_pk_mul_f32 v[158:159], v[158:159], v[152:153] op_sel_hi:[0,1]
	v_pk_mul_f32 v[196:197], v[192:193], s[10:11] op_sel_hi:[1,0]
	v_pk_mul_f32 v[158:159], v[188:189], v[158:159]
	v_exp_f32_e32 v196, v196
	v_exp_f32_e32 v197, v197
	v_pk_mul_f32 v[188:189], v[158:159], s[10:11] op_sel_hi:[1,0]
	v_pk_mul_f32 v[162:163], v[138:139], v[162:163]
	v_exp_f32_e32 v188, v188
	v_exp_f32_e32 v189, v189
	v_pk_add_f32 v[196:197], v[196:197], 1.0 op_sel_hi:[1,0]
	v_pk_add_f32 v[188:189], v[188:189], 1.0 op_sel_hi:[1,0]
	v_rcp_f32_e32 v196, v196
	v_rcp_f32_e32 v197, v197
	v_rcp_f32_e32 v188, v188
	v_rcp_f32_e32 v189, v189
	v_pk_mul_f32 v[192:193], v[192:193], v[196:197]
	v_cvt_pk_bf16_f32 v197, v162, v163
	v_cvt_f32_i32_e32 v163, v47
	v_cvt_f32_i32_e32 v162, v46
	v_pk_mul_f32 v[158:159], v[158:159], v[188:189]
	v_pk_mul_f32 v[188:189], v[168:169], v[160:161] op_sel_hi:[0,1]
	v_pk_mul_f32 v[158:159], v[134:135], v[158:159]
	v_pk_mul_f32 v[162:163], v[162:163], v[188:189]
	v_cvt_pk_bf16_f32 v199, v158, v159
	v_pk_mul_f32 v[188:189], v[162:163], s[10:11] op_sel_hi:[1,0]
	v_cvt_f32_i32_e32 v159, v49
	v_exp_f32_e32 v188, v188
	v_exp_f32_e32 v189, v189
	v_cvt_f32_i32_e32 v158, v48
	v_pk_mul_f32 v[192:193], v[132:133], v[192:193]
	v_cvt_pk_bf16_f32 v196, v166, v167
	v_pk_add_f32 v[188:189], v[188:189], 1.0 op_sel_hi:[1,0]
	v_cvt_pk_bf16_f32 v198, v192, v193
; __device__ __forceinline__ unsigned cvt_pk_bf16(float lo, float hi) { f32x2_t v = {lo, hi}; bf16x2_t b = __builtin_convertvector(v, bf16x2_t); return __builtin_bit_cast(unsigned, b); }
; __device__ __forceinline__ float fast_rcp(float x) { return __builtin_amdgcn_rcpf(x); }
;     template <int KIND>
;     __device__ __forceinline__ void run(const f32x4 (&acc)[2][2][4][2], const Unit& u, int wr, int wc, int fr, int fq) const {
;     ...
;             for (int ai = 0; ai < 2; ++ai)
; #pragma unroll
;                 for (int m = 0; m < 4; ++m) { const int row = row0 + ai * HALF + m * 16; const float a = __shfl(ai ? sa_hi : sa_lo, 16 * m + fr);
;                     const f32x4 f0 = __builtin_convertvector(__builtin_bit_cast(i32x4, acc[ai][bj][m][0]), f32x4), f1 = __builtin_convertvector(__builtin_bit_cast(i32x4, acc[ai][bj][m][1]), f32x4);
;                     f32x2_t v[4] = {(f32x2_t){f0[0], f0[1]}, (f32x2_t){f0[2], f0[3]}, (f32x2_t){f1[0], f1[1]}, (f32x2_t){f1[2], f1[3]}};
; #pragma unroll
;                     for (int j = 0; j < 4; ++j) {
;                         v[j] = v[j] * (sc2[j] * (f32x2_t){a, a});
;                         if (KIND == 0 || KIND == 1 || KIND == 3) {
;                             const f32x2_t e = v[j] * (f32x2_t){-LOG2E, -LOG2E};
;                             const f32x2_t dn = (f32x2_t){__builtin_amdgcn_exp2f(e[0]), __builtin_amdgcn_exp2f(e[1])} + (f32x2_t){1.0f, 1.0f};
;                             const f32x2_t sg = (f32x2_t){fast_rcp(dn[0]), fast_rcp(dn[1])};
;                             if (KIND == 0) v[j] = v[j] * sg;
;                             else if (KIND == 3) v[j] = (v[j] * sg) * aux2[j];
;                             else { const f32x2_t f = __builtin_elementwise_fma((f32x2_t){1.0f, 1.0f} - aux2[j], sg, aux2[j]);
;                                 v[j] = (f32x2_t){fmaxf(__logf(f[0]), -60.0f), fmaxf(__logf(f[1]), -60.0f)}; }
;                         }
;                     }
;                     u32x4 w; w.x = cvt_pk_bf16(v[0][0], v[0][1]); w.y = cvt_pk_bf16(v[1][0], v[1][1]); w.z = cvt_pk_bf16(v[2][0], v[2][1]); w.w = cvt_pk_bf16(v[3][0], v[3][1]);
;                     *(u32x4*)(O + (size_t)row * NPROJ + col0 + bj * HALF) = w; }
	v_rcp_f32_e32 v188, v188
	v_rcp_f32_e32 v189, v189
	v_cvt_f32_i32_e32 v167, v45
	v_cvt_f32_i32_e32 v166, v44
	global_store_dwordx4 v[180:181], v[196:199], off offset:256
	v_pk_mul_f32 v[162:163], v[162:163], v[188:189]
	v_pk_mul_f32 v[188:189], v[168:169], v[164:165] op_sel_hi:[0,1]
	v_pk_mul_f32 v[158:159], v[158:159], v[188:189]
	v_cvt_f32_i32_e32 v181, v43
	v_pk_mul_f32 v[188:189], v[158:159], s[10:11] op_sel_hi:[1,0]
	v_cvt_f32_i32_e32 v180, v42
	v_exp_f32_e32 v188, v188
	v_exp_f32_e32 v189, v189
	v_pk_mul_f32 v[162:163], v[136:137], v[162:163]
	v_pk_add_f32 v[188:189], v[188:189], 1.0 op_sel_hi:[1,0]
	s_nop 0
	v_rcp_f32_e32 v188, v188
	v_rcp_f32_e32 v189, v189
	s_nop 0
	v_pk_mul_f32 v[158:159], v[158:159], v[188:189]
	v_pk_mul_f32 v[188:189], v[168:169], v[156:157] op_sel_hi:[0,1]
	v_pk_mul_f32 v[168:169], v[168:169], v[152:153] op_sel_hi:[0,1]
	v_pk_mul_f32 v[166:167], v[166:167], v[168:169]
	v_pk_mul_f32 v[180:181], v[180:181], v[188:189]
	v_pk_mul_f32 v[168:169], v[166:167], s[10:11] op_sel_hi:[1,0]
	v_pk_mul_f32 v[188:189], v[180:181], s[10:11] op_sel_hi:[1,0]
	v_exp_f32_e32 v168, v168
	v_exp_f32_e32 v169, v169
	v_exp_f32_e32 v188, v188
	v_exp_f32_e32 v189, v189
	v_pk_mul_f32 v[158:159], v[138:139], v[158:159]
	v_pk_add_f32 v[168:169], v[168:169], 1.0 op_sel_hi:[1,0]
	v_pk_add_f32 v[188:189], v[188:189], 1.0 op_sel_hi:[1,0]
	v_rcp_f32_e32 v168, v168
	v_rcp_f32_e32 v169, v169
	v_rcp_f32_e32 v188, v188
	v_rcp_f32_e32 v189, v189
	v_pk_mul_f32 v[166:167], v[166:167], v[168:169]
	v_pk_mul_f32 v[180:181], v[180:181], v[188:189]
	v_pk_mul_f32 v[188:189], v[134:135], v[166:167]
	v_cvt_pk_bf16_f32 v166, v162, v163
	v_cvt_f32_i32_e32 v163, v39
	v_cvt_f32_i32_e32 v162, v38
	v_pk_mul_f32 v[180:181], v[132:133], v[180:181]
	v_cvt_pk_bf16_f32 v167, v158, v159
	v_cvt_pk_bf16_f32 v168, v180, v181
	v_pk_mul_f32 v[180:181], v[170:171], v[160:161] op_sel_hi:[0,1]
	v_pk_mul_f32 v[162:163], v[162:163], v[180:181]
	v_cvt_f32_i32_e32 v159, v41
	v_pk_mul_f32 v[180:181], v[162:163], s[10:11] op_sel_hi:[1,0]
	v_cvt_f32_i32_e32 v158, v40
	v_exp_f32_e32 v180, v180
	v_exp_f32_e32 v181, v181
	v_cvt_pk_bf16_f32 v169, v188, v189
	global_store_dwordx4 v[182:183], v[166:169], off offset:256
	v_pk_add_f32 v[180:181], v[180:181], 1.0 op_sel_hi:[1,0]
	s_nop 0
	v_rcp_f32_e32 v180, v180
	v_rcp_f32_e32 v181, v181
	v_cvt_f32_i32_e32 v167, v37
	v_cvt_f32_i32_e32 v166, v36
	v_cvt_f32_i32_e32 v169, v35
	v_pk_mul_f32 v[162:163], v[162:163], v[180:181]
	v_pk_mul_f32 v[180:181], v[170:171], v[164:165] op_sel_hi:[0,1]
	v_pk_mul_f32 v[158:159], v[158:159], v[180:181]
	v_cvt_f32_i32_e32 v168, v34
	v_pk_mul_f32 v[180:181], v[158:159], s[10:11] op_sel_hi:[1,0]
	v_pk_mul_f32 v[162:163], v[136:137], v[162:163]
	v_exp_f32_e32 v180, v180
	v_exp_f32_e32 v181, v181
	s_nop 0
	v_pk_add_f32 v[180:181], v[180:181], 1.0 op_sel_hi:[1,0]
	s_nop 0
	v_rcp_f32_e32 v180, v180
	v_rcp_f32_e32 v181, v181
	s_nop 0
	v_pk_mul_f32 v[158:159], v[158:159], v[180:181]
	v_pk_mul_f32 v[180:181], v[170:171], v[156:157] op_sel_hi:[0,1]
	v_pk_mul_f32 v[170:171], v[170:171], v[152:153] op_sel_hi:[0,1]
	v_pk_mul_f32 v[166:167], v[166:167], v[170:171]
	v_pk_mul_f32 v[168:169], v[168:169], v[180:181]
	v_pk_mul_f32 v[170:171], v[166:167], s[10:11] op_sel_hi:[1,0]
	v_pk_mul_f32 v[180:181], v[168:169], s[10:11] op_sel_hi:[1,0]
	v_exp_f32_e32 v170, v170
	v_exp_f32_e32 v171, v171
	v_exp_f32_e32 v180, v180
	v_exp_f32_e32 v181, v181
	v_pk_mul_f32 v[158:159], v[138:139], v[158:159]
	v_pk_add_f32 v[170:171], v[170:171], 1.0 op_sel_hi:[1,0]
	v_pk_add_f32 v[180:181], v[180:181], 1.0 op_sel_hi:[1,0]
	v_rcp_f32_e32 v170, v170
	v_rcp_f32_e32 v171, v171
	v_rcp_f32_e32 v180, v180
	v_rcp_f32_e32 v181, v181
	v_pk_mul_f32 v[166:167], v[166:167], v[170:171]
	s_nop 0
	v_pk_mul_f32 v[170:171], v[134:135], v[166:167]
	v_cvt_pk_bf16_f32 v166, v162, v163
	v_cvt_f32_i32_e32 v163, v31
	v_cvt_f32_i32_e32 v162, v30
	v_pk_mul_f32 v[168:169], v[168:169], v[180:181]
	v_cvt_pk_bf16_f32 v167, v158, v159
	v_pk_mul_f32 v[168:169], v[132:133], v[168:169]
	v_cvt_f32_i32_e32 v159, v33
	v_cvt_pk_bf16_f32 v168, v168, v169
	v_cvt_pk_bf16_f32 v169, v170, v171
	v_pk_mul_f32 v[170:171], v[172:173], v[160:161] op_sel_hi:[0,1]
	v_pk_mul_f32 v[162:163], v[162:163], v[170:171]
	v_cvt_f32_i32_e32 v158, v32
	v_pk_mul_f32 v[170:171], v[162:163], s[10:11] op_sel_hi:[1,0]
	global_store_dwordx4 v[184:185], v[166:169], off offset:256
	v_exp_f32_e32 v170, v170
	v_exp_f32_e32 v171, v171
	v_cvt_f32_i32_e32 v169, v27
	v_cvt_f32_i32_e32 v168, v26
	v_cvt_f32_i32_e32 v167, v29
	v_pk_add_f32 v[170:171], v[170:171], 1.0 op_sel_hi:[1,0]
	v_cvt_f32_i32_e32 v166, v28
	v_rcp_f32_e32 v170, v170
	v_rcp_f32_e32 v171, v171
	s_nop 0
	v_pk_mul_f32 v[162:163], v[162:163], v[170:171]
	v_pk_mul_f32 v[170:171], v[172:173], v[164:165] op_sel_hi:[0,1]
	v_pk_mul_f32 v[158:159], v[158:159], v[170:171]
	v_pk_mul_f32 v[162:163], v[136:137], v[162:163]
	v_pk_mul_f32 v[170:171], v[158:159], s[10:11] op_sel_hi:[1,0]
	s_nop 0
	v_exp_f32_e32 v170, v170
	v_exp_f32_e32 v171, v171
	s_nop 0
	v_pk_add_f32 v[170:171], v[170:171], 1.0 op_sel_hi:[1,0]
	s_nop 0
	v_rcp_f32_e32 v170, v170
	v_rcp_f32_e32 v171, v171
	s_nop 0
	v_pk_mul_f32 v[158:159], v[158:159], v[170:171]
	v_pk_mul_f32 v[170:171], v[172:173], v[156:157] op_sel_hi:[0,1]
	v_pk_mul_f32 v[168:169], v[168:169], v[170:171]
	v_pk_mul_f32 v[158:159], v[138:139], v[158:159]
	v_pk_mul_f32 v[170:171], v[168:169], s[10:11] op_sel_hi:[1,0]
	s_nop 0
	v_exp_f32_e32 v170, v170
	v_exp_f32_e32 v171, v171
	s_nop 0
	v_pk_add_f32 v[170:171], v[170:171], 1.0 op_sel_hi:[1,0]
	s_nop 0
	v_rcp_f32_e32 v170, v170
	v_rcp_f32_e32 v171, v171
	s_nop 0
; __device__ __forceinline__ unsigned cvt_pk_bf16(float lo, float hi) { f32x2_t v = {lo, hi}; bf16x2_t b = __builtin_convertvector(v, bf16x2_t); return __builtin_bit_cast(unsigned, b); }
; __device__ __forceinline__ float fast_rcp(float x) { return __builtin_amdgcn_rcpf(x); }
;     template <int KIND>
;     __device__ __forceinline__ void run(const f32x4 (&acc)[2][2][4][2], const Unit& u, int wr, int wc, int fr, int fq) const {
;     ...
;             for (int ai = 0; ai < 2; ++ai)
; #pragma unroll
;                 for (int m = 0; m < 4; ++m) { const int row = row0 + ai * HALF + m * 16; const float a = __shfl(ai ? sa_hi : sa_lo, 16 * m + fr);
;                     const f32x4 f0 = __builtin_convertvector(__builtin_bit_cast(i32x4, acc[ai][bj][m][0]), f32x4), f1 = __builtin_convertvector(__builtin_bit_cast(i32x4, acc[ai][bj][m][1]), f32x4);
;                     f32x2_t v[4] = {(f32x2_t){f0[0], f0[1]}, (f32x2_t){f0[2], f0[3]}, (f32x2_t){f1[0], f1[1]}, (f32x2_t){f1[2], f1[3]}};
; #pragma unroll
;                     for (int j = 0; j < 4; ++j) {
;                         v[j] = v[j] * (sc2[j] * (f32x2_t){a, a});
;                         if (KIND == 0 || KIND == 1 || KIND == 3) {
;                             const f32x2_t e = v[j] * (f32x2_t){-LOG2E, -LOG2E};
;                             const f32x2_t dn = (f32x2_t){__builtin_amdgcn_exp2f(e[0]), __builtin_amdgcn_exp2f(e[1])} + (f32x2_t){1.0f, 1.0f};
;                             const f32x2_t sg = (f32x2_t){fast_rcp(dn[0]), fast_rcp(dn[1])};
;                             if (KIND == 0) v[j] = v[j] * sg;
;                             else if (KIND == 3) v[j] = (v[j] * sg) * aux2[j];
;                             else { const f32x2_t f = __builtin_elementwise_fma((f32x2_t){1.0f, 1.0f} - aux2[j], sg, aux2[j]);
;                                 v[j] = (f32x2_t){fmaxf(__logf(f[0]), -60.0f), fmaxf(__logf(f[1]), -60.0f)}; }
;                         }
;                     }
;                     u32x4 w; w.x = cvt_pk_bf16(v[0][0], v[0][1]); w.y = cvt_pk_bf16(v[1][0], v[1][1]); w.z = cvt_pk_bf16(v[2][0], v[2][1]); w.w = cvt_pk_bf16(v[3][0], v[3][1]);
;                     *(u32x4*)(O + (size_t)row * NPROJ + col0 + bj * HALF) = w; }
	v_pk_mul_f32 v[168:169], v[168:169], v[170:171]
	v_pk_mul_f32 v[170:171], v[172:173], v[152:153] op_sel_hi:[0,1]
	v_pk_mul_f32 v[166:167], v[166:167], v[170:171]
	v_pk_mul_f32 v[168:169], v[132:133], v[168:169]
	v_pk_mul_f32 v[170:171], v[166:167], s[10:11] op_sel_hi:[1,0]
	v_cvt_pk_bf16_f32 v168, v168, v169
	v_exp_f32_e32 v170, v170
	v_exp_f32_e32 v171, v171
	s_nop 0
	v_pk_add_f32 v[170:171], v[170:171], 1.0 op_sel_hi:[1,0]
	s_nop 0
	v_rcp_f32_e32 v170, v170
	v_rcp_f32_e32 v171, v171
	s_nop 0
	v_pk_mul_f32 v[166:167], v[166:167], v[170:171]
	s_nop 0
	v_pk_mul_f32 v[170:171], v[134:135], v[166:167]
	v_cvt_pk_bf16_f32 v166, v162, v163
	v_cvt_f32_i32_e32 v163, v23
	v_cvt_f32_i32_e32 v162, v22
	v_cvt_pk_bf16_f32 v169, v170, v171
	v_pk_mul_f32 v[170:171], v[174:175], v[160:161] op_sel_hi:[0,1]
	v_cvt_pk_bf16_f32 v167, v158, v159
	v_pk_mul_f32 v[162:163], v[162:163], v[170:171]
	v_cvt_f32_i32_e32 v159, v25
	v_pk_mul_f32 v[170:171], v[162:163], s[10:11] op_sel_hi:[1,0]
	v_cvt_f32_i32_e32 v158, v24
	v_exp_f32_e32 v170, v170
	v_exp_f32_e32 v171, v171
	global_store_dwordx4 v[186:187], v[166:169], off offset:256
	v_pk_add_f32 v[170:171], v[170:171], 1.0 op_sel_hi:[1,0]
	s_nop 0
	v_rcp_f32_e32 v170, v170
	v_rcp_f32_e32 v171, v171
	v_cvt_f32_i32_e32 v169, v19
	v_cvt_f32_i32_e32 v168, v18
	v_cvt_f32_i32_e32 v167, v21
	v_pk_mul_f32 v[162:163], v[162:163], v[170:171]
	v_pk_mul_f32 v[170:171], v[174:175], v[164:165] op_sel_hi:[0,1]
	v_pk_mul_f32 v[158:159], v[158:159], v[170:171]
	v_cvt_f32_i32_e32 v166, v20
	v_pk_mul_f32 v[170:171], v[158:159], s[10:11] op_sel_hi:[1,0]
	v_pk_mul_f32 v[162:163], v[136:137], v[162:163]
	v_exp_f32_e32 v170, v170
	v_exp_f32_e32 v171, v171
	s_nop 0
	v_pk_add_f32 v[170:171], v[170:171], 1.0 op_sel_hi:[1,0]
	s_nop 0
	v_rcp_f32_e32 v170, v170
	v_rcp_f32_e32 v171, v171
	s_nop 0
	v_pk_mul_f32 v[158:159], v[158:159], v[170:171]
	v_pk_mul_f32 v[170:171], v[174:175], v[156:157] op_sel_hi:[0,1]
	v_pk_mul_f32 v[168:169], v[168:169], v[170:171]
	v_pk_mul_f32 v[158:159], v[138:139], v[158:159]
	v_pk_mul_f32 v[170:171], v[168:169], s[10:11] op_sel_hi:[1,0]
	s_nop 0
	v_exp_f32_e32 v170, v170
	v_exp_f32_e32 v171, v171
	s_nop 0
	v_pk_add_f32 v[170:171], v[170:171], 1.0 op_sel_hi:[1,0]
	s_nop 0
	v_rcp_f32_e32 v170, v170
	v_rcp_f32_e32 v171, v171
	s_nop 0
	v_pk_mul_f32 v[168:169], v[168:169], v[170:171]
	v_pk_mul_f32 v[170:171], v[174:175], v[152:153] op_sel_hi:[0,1]
	v_pk_mul_f32 v[166:167], v[166:167], v[170:171]
	v_pk_mul_f32 v[168:169], v[132:133], v[168:169]
	v_pk_mul_f32 v[170:171], v[166:167], s[10:11] op_sel_hi:[1,0]
	v_cvt_pk_bf16_f32 v168, v168, v169
	v_exp_f32_e32 v170, v170
	v_exp_f32_e32 v171, v171
	s_nop 0
	v_pk_add_f32 v[170:171], v[170:171], 1.0 op_sel_hi:[1,0]
	s_nop 0
	v_rcp_f32_e32 v170, v170
	v_rcp_f32_e32 v171, v171
	s_nop 0
	v_pk_mul_f32 v[166:167], v[166:167], v[170:171]
	s_nop 0
	v_pk_mul_f32 v[170:171], v[134:135], v[166:167]
	v_cvt_pk_bf16_f32 v166, v162, v163
	v_cvt_f32_i32_e32 v163, v15
	v_cvt_f32_i32_e32 v162, v14
	v_cvt_pk_bf16_f32 v169, v170, v171
	v_pk_mul_f32 v[170:171], v[176:177], v[160:161] op_sel_hi:[0,1]
	v_cvt_pk_bf16_f32 v167, v158, v159
	v_pk_mul_f32 v[162:163], v[162:163], v[170:171]
	v_cvt_f32_i32_e32 v159, v17
	v_pk_mul_f32 v[170:171], v[162:163], s[10:11] op_sel_hi:[1,0]
	v_cvt_f32_i32_e32 v158, v16
	v_exp_f32_e32 v170, v170
	v_exp_f32_e32 v171, v171
	global_store_dwordx4 v[190:191], v[166:169], off offset:256
	v_pk_mul_f32 v[160:161], v[178:179], v[160:161] op_sel_hi:[0,1]
	v_pk_add_f32 v[170:171], v[170:171], 1.0 op_sel_hi:[1,0]
	s_nop 0
	v_rcp_f32_e32 v170, v170
	v_rcp_f32_e32 v171, v171
	v_cvt_f32_i32_e32 v169, v11
	v_cvt_f32_i32_e32 v168, v10
	v_cvt_f32_i32_e32 v167, v13
	v_pk_mul_f32 v[162:163], v[162:163], v[170:171]
; __device__ __forceinline__ unsigned cvt_pk_bf16(float lo, float hi) { f32x2_t v = {lo, hi}; bf16x2_t b = __builtin_convertvector(v, bf16x2_t); return __builtin_bit_cast(unsigned, b); }
; __device__ __forceinline__ float fast_rcp(float x) { return __builtin_amdgcn_rcpf(x); }
;     template <int KIND>
;     __device__ __forceinline__ void run(const f32x4 (&acc)[2][2][4][2], const Unit& u, int wr, int wc, int fr, int fq) const {
;     ...
;             for (int ai = 0; ai < 2; ++ai)
; #pragma unroll
;                 for (int m = 0; m < 4; ++m) { const int row = row0 + ai * HALF + m * 16; const float a = __shfl(ai ? sa_hi : sa_lo, 16 * m + fr);
;                     const f32x4 f0 = __builtin_convertvector(__builtin_bit_cast(i32x4, acc[ai][bj][m][0]), f32x4), f1 = __builtin_convertvector(__builtin_bit_cast(i32x4, acc[ai][bj][m][1]), f32x4);
;                     f32x2_t v[4] = {(f32x2_t){f0[0], f0[1]}, (f32x2_t){f0[2], f0[3]}, (f32x2_t){f1[0], f1[1]}, (f32x2_t){f1[2], f1[3]}};
; #pragma unroll
;                     for (int j = 0; j < 4; ++j) {
;                         v[j] = v[j] * (sc2[j] * (f32x2_t){a, a});
;                         if (KIND == 0 || KIND == 1 || KIND == 3) {
;                             const f32x2_t e = v[j] * (f32x2_t){-LOG2E, -LOG2E};
;                             const f32x2_t dn = (f32x2_t){__builtin_amdgcn_exp2f(e[0]), __builtin_amdgcn_exp2f(e[1])} + (f32x2_t){1.0f, 1.0f};
;                             const f32x2_t sg = (f32x2_t){fast_rcp(dn[0]), fast_rcp(dn[1])};
;                             if (KIND == 0) v[j] = v[j] * sg;
;                             else if (KIND == 3) v[j] = (v[j] * sg) * aux2[j];
;                             else { const f32x2_t f = __builtin_elementwise_fma((f32x2_t){1.0f, 1.0f} - aux2[j], sg, aux2[j]);
;                                 v[j] = (f32x2_t){fmaxf(__logf(f[0]), -60.0f), fmaxf(__logf(f[1]), -60.0f)}; }
;                         }
;                     }
;                     u32x4 w; w.x = cvt_pk_bf16(v[0][0], v[0][1]); w.y = cvt_pk_bf16(v[1][0], v[1][1]); w.z = cvt_pk_bf16(v[2][0], v[2][1]); w.w = cvt_pk_bf16(v[3][0], v[3][1]);
;                     *(u32x4*)(O + (size_t)row * NPROJ + col0 + bj * HALF) = w; }
	v_pk_mul_f32 v[170:171], v[176:177], v[164:165] op_sel_hi:[0,1]
	v_pk_mul_f32 v[158:159], v[158:159], v[170:171]
	v_cvt_f32_i32_e32 v166, v12
	v_pk_mul_f32 v[170:171], v[158:159], s[10:11] op_sel_hi:[1,0]
	v_pk_mul_f32 v[162:163], v[136:137], v[162:163]
	v_exp_f32_e32 v170, v170
	v_exp_f32_e32 v171, v171
	s_nop 0
	v_pk_add_f32 v[170:171], v[170:171], 1.0 op_sel_hi:[1,0]
	s_nop 0
	v_rcp_f32_e32 v170, v170
	v_rcp_f32_e32 v171, v171
	s_nop 0
	v_pk_mul_f32 v[158:159], v[158:159], v[170:171]
	v_pk_mul_f32 v[170:171], v[176:177], v[156:157] op_sel_hi:[0,1]
	v_pk_mul_f32 v[168:169], v[168:169], v[170:171]
	v_pk_mul_f32 v[158:159], v[138:139], v[158:159]
	v_pk_mul_f32 v[170:171], v[168:169], s[10:11] op_sel_hi:[1,0]
	v_pk_mul_f32 v[156:157], v[178:179], v[156:157] op_sel_hi:[0,1]
	v_exp_f32_e32 v170, v170
	v_exp_f32_e32 v171, v171
	s_nop 0
	v_pk_add_f32 v[170:171], v[170:171], 1.0 op_sel_hi:[1,0]
	s_nop 0
	v_rcp_f32_e32 v170, v170
	v_rcp_f32_e32 v171, v171
	s_nop 0
	v_pk_mul_f32 v[168:169], v[168:169], v[170:171]
	v_pk_mul_f32 v[170:171], v[176:177], v[152:153] op_sel_hi:[0,1]
	v_pk_mul_f32 v[166:167], v[166:167], v[170:171]
	v_pk_mul_f32 v[168:169], v[132:133], v[168:169]
	v_pk_mul_f32 v[170:171], v[166:167], s[10:11] op_sel_hi:[1,0]
	v_cvt_pk_bf16_f32 v168, v168, v169
	v_exp_f32_e32 v170, v170
	v_exp_f32_e32 v171, v171
	v_pk_mul_f32 v[152:153], v[178:179], v[152:153] op_sel_hi:[0,1]
	v_pk_add_f32 v[170:171], v[170:171], 1.0 op_sel_hi:[1,0]
	s_nop 0
	v_rcp_f32_e32 v170, v170
	v_rcp_f32_e32 v171, v171
	s_nop 0
	v_pk_mul_f32 v[166:167], v[166:167], v[170:171]
	s_nop 0
	v_pk_mul_f32 v[170:171], v[134:135], v[166:167]
	v_cvt_pk_bf16_f32 v166, v162, v163
	v_cvt_f32_i32_e32 v163, v7
	v_cvt_f32_i32_e32 v162, v6
	v_cvt_pk_bf16_f32 v167, v158, v159
	v_cvt_f32_i32_e32 v159, v9
	v_cvt_f32_i32_e32 v158, v8
	v_pk_mul_f32 v[160:161], v[162:163], v[160:161]
	v_cvt_pk_bf16_f32 v169, v170, v171
	v_pk_mul_f32 v[162:163], v[160:161], s[10:11] op_sel_hi:[1,0]
	global_store_dwordx4 v[194:195], v[166:169], off offset:256
	v_exp_f32_e32 v162, v162
	v_exp_f32_e32 v163, v163
	v_cvt_f32_i32_e32 v169, v3
	v_cvt_f32_i32_e32 v168, v2
	v_cvt_f32_i32_e32 v167, v5
	v_pk_add_f32 v[162:163], v[162:163], 1.0 op_sel_hi:[1,0]
	v_cvt_f32_i32_e32 v166, v4
	v_rcp_f32_e32 v162, v162
	v_rcp_f32_e32 v163, v163
	v_pk_mul_f32 v[156:157], v[168:169], v[156:157]
	v_pk_mul_f32 v[152:153], v[166:167], v[152:153]
	v_pk_mul_f32 v[160:161], v[160:161], v[162:163]
	s_nop 0
	v_pk_mul_f32 v[136:137], v[136:137], v[160:161]
	v_pk_mul_f32 v[160:161], v[178:179], v[164:165] op_sel_hi:[0,1]
	v_pk_mul_f32 v[158:159], v[158:159], v[160:161]
	s_nop 0
	v_pk_mul_f32 v[160:161], v[158:159], s[10:11] op_sel_hi:[1,0]
	s_nop 0
	v_exp_f32_e32 v160, v160
	v_exp_f32_e32 v161, v161
	s_nop 0
	v_pk_add_f32 v[160:161], v[160:161], 1.0 op_sel_hi:[1,0]
	s_nop 0
	v_rcp_f32_e32 v160, v160
	v_rcp_f32_e32 v161, v161
	s_nop 0
	v_pk_mul_f32 v[158:159], v[158:159], v[160:161]
	s_nop 0
	v_pk_mul_f32 v[138:139], v[138:139], v[158:159]
	v_pk_mul_f32 v[158:159], v[156:157], s[10:11] op_sel_hi:[1,0]
	s_nop 0
	v_exp_f32_e32 v158, v158
	v_exp_f32_e32 v159, v159
	s_nop 0
	v_pk_add_f32 v[158:159], v[158:159], 1.0 op_sel_hi:[1,0]
	s_nop 0
	v_rcp_f32_e32 v158, v158
	v_rcp_f32_e32 v159, v159
	s_nop 0
	v_pk_mul_f32 v[156:157], v[156:157], v[158:159]
	s_nop 0
	v_pk_mul_f32 v[132:133], v[132:133], v[156:157]
	v_pk_mul_f32 v[156:157], v[152:153], s[10:11] op_sel_hi:[1,0]
	s_nop 0
	v_exp_f32_e32 v156, v156
	v_exp_f32_e32 v157, v157
	s_nop 0
	v_pk_add_f32 v[156:157], v[156:157], 1.0 op_sel_hi:[1,0]
	s_nop 0
	v_rcp_f32_e32 v156, v156
	v_rcp_f32_e32 v157, v157
	s_nop 0
	v_pk_mul_f32 v[152:153], v[152:153], v[156:157]
	s_nop 0
	v_pk_mul_f32 v[134:135], v[134:135], v[152:153]

;     template <int KIND>
;     __device__ __forceinline__ void run(const f32x4 (&acc)[2][2][4][2], const Unit& u, int wr, int wc, int fr, int fq) const {
;     ...
;         for (int bj = 0; bj < 2; ++bj) {
;             f32x2_t sc2[4], aux2[4];
; #pragma unroll
;             for (int j = 0; j < 4; ++j) {
;                 const float k0 = (KIND == 4) ? (0.125f * LOG2E / 127.0f) : (1.0f / 127.0f);
;                 sc2[j] = (f32x2_t){wmax[col0 + bj * HALF + 2 * j] * k0, wmax[col0 + bj * HALF + 2 * j + 1] * k0};
;                 if (KIND == 1) aux2[j] = (f32x2_t){lb[col0 - C_HG + bj * HALF + 2 * j], lb[col0 - C_HG + bj * HALF + 2 * j + 1]};
;                 else if (KIND == 3) aux2[j] = (f32x2_t){gain[col0 - C_HGATE + bj * HALF + 2 * j], gain[col0 - C_HGATE + bj * HALF + 2 * j + 1]};
;                 else aux2[j] = (f32x2_t){0.f, 0.f};
;             }
; #pragma unroll
;             for (int ai = 0; ai < 2; ++ai)
; #pragma unroll
;                 for (int m = 0; m < 4; ++m) { const int row = row0 + ai * HALF + m * 16; const float a = __shfl(ai ? sa_hi : sa_lo, 16 * m + fr);
;                     const f32x4 f0 = __builtin_convertvector(__builtin_bit_cast(i32x4, acc[ai][bj][m][0]), f32x4), f1 = __builtin_convertvector(__builtin_bit_cast(i32x4, acc[ai][bj][m][1]), f32x4);
;                     f32x2_t v[4] = {(f32x2_t){f0[0], f0[1]}, (f32x2_t){f0[2], f0[3]}, (f32x2_t){f1[0], f1[1]}, (f32x2_t){f1[2], f1[3]}};
; #pragma unroll
;                     for (int j = 0; j < 4; ++j) {
;                         v[j] = v[j] * (sc2[j] * (f32x2_t){a, a});
;                         if (KIND == 0 || KIND == 1 || KIND == 3) {
;                             const f32x2_t e = v[j] * (f32x2_t){-LOG2E, -LOG2E};
;                             const f32x2_t dn = (f32x2_t){__builtin_amdgcn_exp2f(e[0]), __builtin_amdgcn_exp2f(e[1])} + (f32x2_t){1.0f, 1.0f};
;                             const f32x2_t sg = (f32x2_t){fast_rcp(dn[0]), fast_rcp(dn[1])};
;                             if (KIND == 0) v[j] = v[j] * sg;
;                             else if (KIND == 3) v[j] = (v[j] * sg) * aux2[j];
;                             else { const f32x2_t f = __builtin_elementwise_fma((f32x2_t){1.0f, 1.0f} - aux2[j], sg, aux2[j]);
;                                 v[j] = (f32x2_t){fmaxf(__logf(f[0]), -60.0f), fmaxf(__logf(f[1]), -60.0f)}; }
.LBB0_224:
	s_andn2_b64 vcc, exec, s[0:1]
	s_cbranch_vccnz .LBB0_226
	s_mov_b32 s8, 0x3c010204
	s_waitcnt vmcnt(0)
	v_pk_mul_f32 v[188:189], v[154:155], s[8:9] op_sel_hi:[1,0]
	v_lshl_add_u64 v[154:155], v[146:147], 2, s[70:71]
	global_load_dwordx4 v[132:135], v[154:155], off offset:-2032
	global_load_dwordx4 v[136:139], v[154:155], off offset:-2048
	global_load_dwordx2 v[150:151], v[148:149], off offset:24
	global_load_dwordx4 v[156:159], v[148:149], off offset:8
	ds_bpermute_b32 v66, v210, v209
	v_cvt_f32_i32_e32 v161, v129
	v_cvt_f32_i32_e32 v160, v128
	s_mov_b32 s10, 0xbfb8aa3b
	s_mov_b32 s2, 0x800000
	s_waitcnt lgkmcnt(0)
	v_pk_mul_f32 v[166:167], v[188:189], v[66:67] op_sel_hi:[1,0]
	v_cvt_f32_i32_e32 v165, v131
	v_pk_mul_f32 v[160:161], v[160:161], v[166:167]
	v_cvt_f32_i32_e32 v164, v130
	v_pk_mul_f32 v[160:161], v[160:161], s[10:11] op_sel_hi:[1,0]
	s_mov_b32 s3, 0x3f317217
	v_exp_f32_e32 v160, v160
	v_exp_f32_e32 v161, v161
	s_mov_b32 s6, 0x7f800000
	v_mov_b64_e32 v[204:205], s[14:15]
	v_cvt_f32_i32_e32 v185, v97
	v_pk_add_f32 v[160:161], v[160:161], 1.0 op_sel_hi:[1,0]
	v_cvt_f32_i32_e32 v184, v96
	v_rcp_f32_e32 v160, v160
	v_rcp_f32_e32 v161, v161
	s_waitcnt vmcnt(3)
	v_pk_add_f32 v[194:195], v[132:133], 1.0 op_sel_hi:[1,0] neg_lo:[1,0] neg_hi:[1,0]
	s_waitcnt vmcnt(2)
	v_pk_add_f32 v[190:191], v[136:137], 1.0 op_sel_hi:[1,0] neg_lo:[1,0] neg_hi:[1,0]
	v_pk_add_f32 v[192:193], v[138:139], 1.0 op_sel_hi:[1,0] neg_lo:[1,0] neg_hi:[1,0]
	v_pk_fma_f32 v[160:161], v[190:191], v[160:161], v[136:137]
	s_waitcnt vmcnt(0)
	global_load_dwordx4 v[236:239], v[148:149], off offset:528
	global_load_dwordx4 v[240:243], v[148:149], off offset:512
	global_load_dwordx4 v[128:131], v[154:155], off offset:-1520
	global_load_dwordx4 v[244:247], v[154:155], off offset:-1536
	v_pk_mul_f32 v[180:181], v[156:157], s[8:9] op_sel_hi:[1,0]
	v_cmp_gt_f32_e32 vcc, s2, v160
	v_pk_mul_f32 v[166:167], v[180:181], v[66:67] op_sel_hi:[1,0]
	v_pk_mul_f32 v[170:171], v[158:159], s[8:9] op_sel_hi:[1,0]
	v_cndmask_b32_e64 v162, 0, 32, vcc
	v_ldexp_f32 v160, v160, v162
	v_log_f32_e32 v160, v160
	v_pk_mul_f32 v[164:165], v[164:165], v[166:167]
	v_cvt_f32_i32_e32 v159, v125
	v_pk_mul_f32 v[164:165], v[164:165], s[10:11] op_sel_hi:[1,0]
	v_mul_f32_e32 v162, 0x3f317217, v160
	v_fma_f32 v162, v160, s3, -v162
	v_fmac_f32_e32 v162, 0x3377d1cf, v160
	v_fmac_f32_e32 v162, 0x3f317217, v160
	v_cmp_lt_f32_e64 s[38:39], |v160|, s6
	v_exp_f32_e32 v164, v164
	v_exp_f32_e32 v165, v165
	v_cndmask_b32_e64 v160, v160, v162, s[38:39]
	v_cndmask_b32_e32 v162, 0, v224, vcc
	v_cmp_gt_f32_e32 vcc, s2, v161
	v_sub_f32_e32 v160, v160, v162
	v_pk_add_f32 v[164:165], v[164:165], 1.0 op_sel_hi:[1,0]
	v_cndmask_b32_e64 v162, 0, 32, vcc
	v_ldexp_f32 v161, v161, v162
	v_log_f32_e32 v161, v161
	v_rcp_f32_e32 v164, v164
	v_rcp_f32_e32 v165, v165
	v_cvt_f32_i32_e32 v158, v124
	v_mul_f32_e32 v162, 0x3f317217, v161
	v_fma_f32 v162, v161, s3, -v162
	v_fmac_f32_e32 v162, 0x3377d1cf, v161
	v_fmac_f32_e32 v162, 0x3f317217, v161
	v_cmp_lt_f32_e64 s[38:39], |v161|, s6
	v_pk_fma_f32 v[164:165], v[192:193], v[164:165], v[138:139]
	v_pk_mul_f32 v[166:167], v[170:171], v[66:67] op_sel_hi:[1,0]
	v_cndmask_b32_e64 v161, v161, v162, s[38:39]
	v_cndmask_b32_e32 v162, 0, v224, vcc
	v_cmp_gt_f32_e32 vcc, s2, v164
	v_sub_f32_e32 v161, v161, v162
	v_pk_mul_f32 v[158:159], v[158:159], v[166:167]
	v_cndmask_b32_e64 v162, 0, 32, vcc
	v_ldexp_f32 v162, v164, v162
	v_log_f32_e32 v162, v162
	v_pk_mul_f32 v[158:159], v[158:159], s[10:11] op_sel_hi:[1,0]
	v_cvt_f32_i32_e32 v157, v127
	v_exp_f32_e32 v158, v158
	v_mul_f32_e32 v164, 0x3f317217, v162
	v_fma_f32 v164, v162, s3, -v164
	v_fmac_f32_e32 v164, 0x3377d1cf, v162
	v_fmac_f32_e32 v164, 0x3f317217, v162
	v_cmp_lt_f32_e64 s[38:39], |v162|, s6
	v_exp_f32_e32 v159, v159
	v_cvt_f32_i32_e32 v156, v126
	v_cndmask_b32_e64 v162, v162, v164, s[38:39]
	v_cndmask_b32_e32 v164, 0, v224, vcc
	v_cmp_gt_f32_e32 vcc, s2, v165
	v_sub_f32_e32 v162, v162, v164
	v_pk_add_f32 v[158:159], v[158:159], 1.0 op_sel_hi:[1,0]
	v_cndmask_b32_e64 v164, 0, 32, vcc
	v_ldexp_f32 v164, v165, v164
	v_log_f32_e32 v164, v164
	v_rcp_f32_e32 v158, v158
	v_rcp_f32_e32 v159, v159
	v_pk_mul_f32 v[150:151], v[150:151], s[8:9] op_sel_hi:[1,0]
	v_mul_f32_e32 v165, 0x3f317217, v164
	v_fma_f32 v165, v164, s3, -v165
	v_fmac_f32_e32 v165, 0x3377d1cf, v164
	v_fmac_f32_e32 v165, 0x3f317217, v164
	v_cmp_lt_f32_e64 s[38:39], |v164|, s6
	v_pk_fma_f32 v[158:159], v[194:195], v[158:159], v[132:133]
	v_pk_add_f32 v[206:207], v[134:135], 1.0 op_sel_hi:[1,0] neg_lo:[1,0] neg_hi:[1,0]
	v_cndmask_b32_e64 v164, v164, v165, s[38:39]
	v_cndmask_b32_e32 v165, 0, v224, vcc
	v_cmp_gt_f32_e32 vcc, s2, v158
	v_sub_f32_e32 v164, v164, v165
	v_max_f32_e32 v160, 0xc2700000, v160
	v_cndmask_b32_e64 v165, 0, 32, vcc
	v_ldexp_f32 v158, v158, v165
	v_log_f32_e32 v158, v158
	v_max_f32_e32 v161, 0xc2700000, v161
	v_max_f32_e32 v162, 0xc2700000, v162
	v_max_f32_e32 v164, 0xc2700000, v164
	v_mul_f32_e32 v165, 0x3f317217, v158
	v_fma_f32 v165, v158, s3, -v165
	v_fmac_f32_e32 v165, 0x3377d1cf, v158
	v_fmac_f32_e32 v165, 0x3f317217, v158
	v_cmp_lt_f32_e64 s[38:39], |v158|, s6
	s_nop 1
	v_cndmask_b32_e64 v158, v158, v165, s[38:39]
	v_cndmask_b32_e32 v165, 0, v224, vcc
	v_sub_f32_e32 v158, v158, v165
	v_cmp_gt_f32_e32 vcc, s2, v159
	v_max_f32_e32 v165, 0xc2700000, v158
	s_nop 0
	v_cndmask_b32_e64 v158, 0, 32, vcc
	v_ldexp_f32 v158, v159, v158
	v_log_f32_e32 v158, v158
	s_nop 0
	v_mul_f32_e32 v159, 0x3f317217, v158
	v_fma_f32 v159, v158, s3, -v159
	v_fmac_f32_e32 v159, 0x3377d1cf, v158
	v_fmac_f32_e32 v159, 0x3f317217, v158
	v_cmp_lt_f32_e64 s[38:39], |v158|, s6
; __device__ __forceinline__ unsigned cvt_pk_bf16(float lo, float hi) { f32x2_t v = {lo, hi}; bf16x2_t b = __builtin_convertvector(v, bf16x2_t); return __builtin_bit_cast(unsigned, b); }
; __device__ __forceinline__ float fast_rcp(float x) { return __builtin_amdgcn_rcpf(x); }
;     template <int KIND>
;     __device__ __forceinline__ void run(const f32x4 (&acc)[2][2][4][2], const Unit& u, int wr, int wc, int fr, int fq) const {
;     ...
;             for (int ai = 0; ai < 2; ++ai)
; #pragma unroll
;                 for (int m = 0; m < 4; ++m) { const int row = row0 + ai * HALF + m * 16; const float a = __shfl(ai ? sa_hi : sa_lo, 16 * m + fr);
;                     const f32x4 f0 = __builtin_convertvector(__builtin_bit_cast(i32x4, acc[ai][bj][m][0]), f32x4), f1 = __builtin_convertvector(__builtin_bit_cast(i32x4, acc[ai][bj][m][1]), f32x4);
;                     f32x2_t v[4] = {(f32x2_t){f0[0], f0[1]}, (f32x2_t){f0[2], f0[3]}, (f32x2_t){f1[0], f1[1]}, (f32x2_t){f1[2], f1[3]}};
; #pragma unroll
;                     for (int j = 0; j < 4; ++j) {
;                         v[j] = v[j] * (sc2[j] * (f32x2_t){a, a});
;                         if (KIND == 0 || KIND == 1 || KIND == 3) {
;                             const f32x2_t e = v[j] * (f32x2_t){-LOG2E, -LOG2E};
;                             const f32x2_t dn = (f32x2_t){__builtin_amdgcn_exp2f(e[0]), __builtin_amdgcn_exp2f(e[1])} + (f32x2_t){1.0f, 1.0f};
;                             const f32x2_t sg = (f32x2_t){fast_rcp(dn[0]), fast_rcp(dn[1])};
;                             if (KIND == 0) v[j] = v[j] * sg;
;                             else if (KIND == 3) v[j] = (v[j] * sg) * aux2[j];
;                             else { const f32x2_t f = __builtin_elementwise_fma((f32x2_t){1.0f, 1.0f} - aux2[j], sg, aux2[j]);
;                                 v[j] = (f32x2_t){fmaxf(__logf(f[0]), -60.0f), fmaxf(__logf(f[1]), -60.0f)}; }
;                         }
;                     }
;                     u32x4 w; w.x = cvt_pk_bf16(v[0][0], v[0][1]); w.y = cvt_pk_bf16(v[1][0], v[1][1]); w.z = cvt_pk_bf16(v[2][0], v[2][1]); w.w = cvt_pk_bf16(v[3][0], v[3][1]);
;                     *(u32x4*)(O + (size_t)row * NPROJ + col0 + bj * HALF) = w; }
	s_nop 1
	v_cndmask_b32_e64 v158, v158, v159, s[38:39]
	v_cndmask_b32_e32 v159, 0, v224, vcc
	v_sub_f32_e32 v158, v158, v159
	v_max_f32_e32 v166, 0xc2700000, v158
	v_pk_mul_f32 v[158:159], v[150:151], v[66:67] op_sel_hi:[1,0]
	s_nop 0
	v_pk_mul_f32 v[156:157], v[156:157], v[158:159]
	s_nop 0
	v_pk_mul_f32 v[156:157], v[156:157], s[10:11] op_sel_hi:[1,0]
	s_nop 0
	v_exp_f32_e32 v156, v156
	v_exp_f32_e32 v157, v157
	s_nop 0
	v_pk_add_f32 v[156:157], v[156:157], 1.0 op_sel_hi:[1,0]
	s_nop 0
	v_rcp_f32_e32 v156, v156
	v_rcp_f32_e32 v157, v157
	s_nop 0
	v_pk_fma_f32 v[156:157], v[206:207], v[156:157], v[134:135]
	s_nop 0
	v_cmp_gt_f32_e32 vcc, s2, v156
	s_nop 1
	v_cndmask_b32_e64 v158, 0, 32, vcc
	v_ldexp_f32 v156, v156, v158
	v_log_f32_e32 v156, v156
	s_nop 0
	v_mul_f32_e32 v158, 0x3f317217, v156
	v_fma_f32 v158, v156, s3, -v158
	v_fmac_f32_e32 v158, 0x3377d1cf, v156
	v_fmac_f32_e32 v158, 0x3f317217, v156
	v_cmp_lt_f32_e64 s[38:39], |v156|, s6
	s_nop 1
	v_cndmask_b32_e64 v156, v156, v158, s[38:39]
	v_cndmask_b32_e32 v158, 0, v224, vcc
	v_sub_f32_e32 v156, v156, v158
	v_cmp_gt_f32_e32 vcc, s2, v157
	v_max_f32_e32 v159, 0xc2700000, v156
	v_cvt_pk_bf16_f32 v158, v165, v166
	v_cndmask_b32_e64 v156, 0, 32, vcc
	v_ldexp_f32 v156, v157, v156
	v_log_f32_e32 v156, v156
	v_cvt_f32_i32_e32 v166, v120
	v_cvt_f32_i32_e32 v165, v123
	v_mul_f32_e32 v157, 0x3f317217, v156
	v_fma_f32 v157, v156, s3, -v157
	v_fmac_f32_e32 v157, 0x3377d1cf, v156
	v_fmac_f32_e32 v157, 0x3f317217, v156
	v_cmp_lt_f32_e64 s[38:39], |v156|, s6
	s_nop 1
	v_cndmask_b32_e64 v156, v156, v157, s[38:39]
	v_cndmask_b32_e32 v157, 0, v224, vcc
	v_sub_f32_e32 v156, v156, v157
	v_max_f32_e32 v167, 0xc2700000, v156
	v_cvt_pk_bf16_f32 v156, v160, v161
	v_mad_i64_i32 v[160:161], s[0:1], v175, s81, v[204:205]
	v_cvt_pk_bf16_f32 v157, v162, v164
	v_cvt_pk_bf16_f32 v159, v159, v167
	v_lshl_add_u64 v[172:173], v[160:161], 0, v[152:153]
	global_store_dwordx4 v[172:173], v[156:159], off
	ds_bpermute_b32 v156, v210, v209 offset:64
	v_cvt_f32_i32_e32 v167, v121
	v_cvt_f32_i32_e32 v164, v122
	v_cvt_f32_i32_e32 v161, v117
	v_cvt_f32_i32_e32 v160, v116
	s_waitcnt lgkmcnt(0)
	v_pk_mul_f32 v[174:175], v[188:189], v[156:157] op_sel_hi:[1,0]
	v_cvt_f32_i32_e32 v159, v119
	v_pk_mul_f32 v[166:167], v[166:167], v[174:175]
	v_cvt_f32_i32_e32 v158, v118
	v_pk_mul_f32 v[166:167], v[166:167], s[10:11] op_sel_hi:[1,0]
	s_nop 0
	v_exp_f32_e32 v166, v166
	v_exp_f32_e32 v167, v167
	s_nop 0
	v_pk_add_f32 v[166:167], v[166:167], 1.0 op_sel_hi:[1,0]
	s_nop 0
	v_rcp_f32_e32 v166, v166
	v_rcp_f32_e32 v167, v167
	s_nop 0
	v_pk_fma_f32 v[166:167], v[190:191], v[166:167], v[136:137]
	s_nop 0
	v_cmp_gt_f32_e32 vcc, s2, v166
	s_nop 1
	v_cndmask_b32_e64 v157, 0, 32, vcc
	v_ldexp_f32 v157, v166, v157
	v_log_f32_e32 v157, v157
	s_nop 0
	v_mul_f32_e32 v162, 0x3f317217, v157
	v_fma_f32 v162, v157, s3, -v162
	v_fmac_f32_e32 v162, 0x3377d1cf, v157
	v_fmac_f32_e32 v162, 0x3f317217, v157
	v_cmp_lt_f32_e64 s[38:39], |v157|, s6
	s_nop 1
	v_cndmask_b32_e64 v157, v157, v162, s[38:39]
	v_cndmask_b32_e32 v162, 0, v224, vcc
	v_cmp_gt_f32_e32 vcc, s2, v167
	v_sub_f32_e32 v157, v157, v162
	v_max_f32_e32 v157, 0xc2700000, v157
	v_cndmask_b32_e64 v162, 0, 32, vcc
	v_ldexp_f32 v162, v167, v162
	v_log_f32_e32 v162, v162
	s_nop 0
	v_mul_f32_e32 v166, 0x3f317217, v162
	v_fma_f32 v166, v162, s3, -v166
	v_fmac_f32_e32 v166, 0x3377d1cf, v162
	v_fmac_f32_e32 v166, 0x3f317217, v162
	v_cmp_lt_f32_e64 s[38:39], |v162|, s6
	s_nop 1
	v_cndmask_b32_e64 v162, v162, v166, s[38:39]
	v_cndmask_b32_e32 v166, 0, v224, vcc
	v_sub_f32_e32 v162, v162, v166
	v_pk_mul_f32 v[166:167], v[180:181], v[156:157] op_sel_hi:[1,0]
	v_max_f32_e32 v162, 0xc2700000, v162
	v_pk_mul_f32 v[164:165], v[164:165], v[166:167]
	s_nop 0
	v_pk_mul_f32 v[164:165], v[164:165], s[10:11] op_sel_hi:[1,0]
	s_nop 0
	v_exp_f32_e32 v164, v164
	v_exp_f32_e32 v165, v165
	s_nop 0
	v_pk_add_f32 v[164:165], v[164:165], 1.0 op_sel_hi:[1,0]
	s_nop 0
	v_rcp_f32_e32 v164, v164
	v_rcp_f32_e32 v165, v165
	s_nop 0
	v_pk_fma_f32 v[164:165], v[192:193], v[164:165], v[138:139]
	s_nop 0
	v_cmp_gt_f32_e32 vcc, s2, v164
	s_nop 1
	v_cndmask_b32_e64 v166, 0, 32, vcc
	v_ldexp_f32 v164, v164, v166
	v_log_f32_e32 v164, v164
	s_nop 0
	v_mul_f32_e32 v166, 0x3f317217, v164
	v_fma_f32 v166, v164, s3, -v166
	v_fmac_f32_e32 v166, 0x3377d1cf, v164
	v_fmac_f32_e32 v166, 0x3f317217, v164
	v_cmp_lt_f32_e64 s[38:39], |v164|, s6
	s_nop 1
	v_cndmask_b32_e64 v164, v164, v166, s[38:39]
	v_cndmask_b32_e32 v166, 0, v224, vcc
	v_sub_f32_e32 v164, v164, v166
	v_cmp_gt_f32_e32 vcc, s2, v165
	v_max_f32_e32 v166, 0xc2700000, v164
	s_nop 0
	v_cndmask_b32_e64 v164, 0, 32, vcc
	v_ldexp_f32 v164, v165, v164
	v_log_f32_e32 v164, v164
	s_nop 0
	v_mul_f32_e32 v165, 0x3f317217, v164
	v_fma_f32 v165, v164, s3, -v165
	v_fmac_f32_e32 v165, 0x3377d1cf, v164
	v_fmac_f32_e32 v165, 0x3f317217, v164
	v_cmp_lt_f32_e64 s[38:39], |v164|, s6
	s_nop 1
	v_cndmask_b32_e64 v164, v164, v165, s[38:39]
	v_cndmask_b32_e32 v165, 0, v224, vcc
	v_sub_f32_e32 v164, v164, v165
	v_max_f32_e32 v167, 0xc2700000, v164
	v_pk_mul_f32 v[164:165], v[170:171], v[156:157] op_sel_hi:[1,0]
	s_nop 0
	v_pk_mul_f32 v[160:161], v[160:161], v[164:165]
	s_nop 0
	v_pk_mul_f32 v[160:161], v[160:161], s[10:11] op_sel_hi:[1,0]
	s_nop 0
	v_exp_f32_e32 v160, v160
	v_exp_f32_e32 v161, v161
	s_nop 0
	v_pk_add_f32 v[160:161], v[160:161], 1.0 op_sel_hi:[1,0]
	s_nop 0
	v_rcp_f32_e32 v160, v160
	v_rcp_f32_e32 v161, v161
	s_nop 0
	v_pk_fma_f32 v[160:161], v[194:195], v[160:161], v[132:133]
	s_nop 0
	v_cmp_gt_f32_e32 vcc, s2, v160
	s_nop 1
	v_cndmask_b32_e64 v164, 0, 32, vcc
	v_ldexp_f32 v160, v160, v164
; __device__ __forceinline__ unsigned cvt_pk_bf16(float lo, float hi) { f32x2_t v = {lo, hi}; bf16x2_t b = __builtin_convertvector(v, bf16x2_t); return __builtin_bit_cast(unsigned, b); }
; __device__ __forceinline__ float fast_rcp(float x) { return __builtin_amdgcn_rcpf(x); }
;     template <int KIND>
;     __device__ __forceinline__ void run(const f32x4 (&acc)[2][2][4][2], const Unit& u, int wr, int wc, int fr, int fq) const {
;     ...
;             for (int ai = 0; ai < 2; ++ai)
; #pragma unroll
;                 for (int m = 0; m < 4; ++m) { const int row = row0 + ai * HALF + m * 16; const float a = __shfl(ai ? sa_hi : sa_lo, 16 * m + fr);
;                     const f32x4 f0 = __builtin_convertvector(__builtin_bit_cast(i32x4, acc[ai][bj][m][0]), f32x4), f1 = __builtin_convertvector(__builtin_bit_cast(i32x4, acc[ai][bj][m][1]), f32x4);
;                     f32x2_t v[4] = {(f32x2_t){f0[0], f0[1]}, (f32x2_t){f0[2], f0[3]}, (f32x2_t){f1[0], f1[1]}, (f32x2_t){f1[2], f1[3]}};
; #pragma unroll
;                     for (int j = 0; j < 4; ++j) {
;                         v[j] = v[j] * (sc2[j] * (f32x2_t){a, a});
;                         if (KIND == 0 || KIND == 1 || KIND == 3) {
;                             const f32x2_t e = v[j] * (f32x2_t){-LOG2E, -LOG2E};
;                             const f32x2_t dn = (f32x2_t){__builtin_amdgcn_exp2f(e[0]), __builtin_amdgcn_exp2f(e[1])} + (f32x2_t){1.0f, 1.0f};
;                             const f32x2_t sg = (f32x2_t){fast_rcp(dn[0]), fast_rcp(dn[1])};
;                             if (KIND == 0) v[j] = v[j] * sg;
;                             else if (KIND == 3) v[j] = (v[j] * sg) * aux2[j];
;                             else { const f32x2_t f = __builtin_elementwise_fma((f32x2_t){1.0f, 1.0f} - aux2[j], sg, aux2[j]);
;                                 v[j] = (f32x2_t){fmaxf(__logf(f[0]), -60.0f), fmaxf(__logf(f[1]), -60.0f)}; }
;                         }
;                     }
;                     u32x4 w; w.x = cvt_pk_bf16(v[0][0], v[0][1]); w.y = cvt_pk_bf16(v[1][0], v[1][1]); w.z = cvt_pk_bf16(v[2][0], v[2][1]); w.w = cvt_pk_bf16(v[3][0], v[3][1]);
;                     *(u32x4*)(O + (size_t)row * NPROJ + col0 + bj * HALF) = w; }
	v_log_f32_e32 v160, v160
	s_nop 0
	v_mul_f32_e32 v164, 0x3f317217, v160
	v_fma_f32 v164, v160, s3, -v164
	v_fmac_f32_e32 v164, 0x3377d1cf, v160
	v_fmac_f32_e32 v164, 0x3f317217, v160
	v_cmp_lt_f32_e64 s[38:39], |v160|, s6
	s_nop 1
	v_cndmask_b32_e64 v160, v160, v164, s[38:39]
	v_cndmask_b32_e32 v164, 0, v224, vcc
	v_sub_f32_e32 v160, v160, v164
	v_cmp_gt_f32_e32 vcc, s2, v161
	v_max_f32_e32 v164, 0xc2700000, v160
	s_nop 0
	v_cndmask_b32_e64 v160, 0, 32, vcc
	v_ldexp_f32 v160, v161, v160
	v_log_f32_e32 v160, v160
	s_nop 0
	v_mul_f32_e32 v161, 0x3f317217, v160
	v_fma_f32 v161, v160, s3, -v161
	v_fmac_f32_e32 v161, 0x3377d1cf, v160
	v_fmac_f32_e32 v161, 0x3f317217, v160
	v_cmp_lt_f32_e64 s[38:39], |v160|, s6
	s_nop 1
	v_cndmask_b32_e64 v160, v160, v161, s[38:39]
	v_cndmask_b32_e32 v161, 0, v224, vcc
	v_sub_f32_e32 v160, v160, v161
	v_max_f32_e32 v165, 0xc2700000, v160
	v_pk_mul_f32 v[160:161], v[150:151], v[156:157] op_sel_hi:[1,0]
	s_nop 0
	v_pk_mul_f32 v[158:159], v[158:159], v[160:161]
	s_nop 0
	v_pk_mul_f32 v[158:159], v[158:159], s[10:11] op_sel_hi:[1,0]
	s_nop 0
	v_exp_f32_e32 v158, v158
	v_exp_f32_e32 v159, v159
	s_nop 0
	v_pk_add_f32 v[158:159], v[158:159], 1.0 op_sel_hi:[1,0]
	s_nop 0
	v_rcp_f32_e32 v158, v158
	v_rcp_f32_e32 v159, v159
	s_nop 0
	v_pk_fma_f32 v[158:159], v[206:207], v[158:159], v[134:135]
	s_nop 0
	v_cmp_gt_f32_e32 vcc, s2, v158
	s_nop 1
	v_cndmask_b32_e64 v160, 0, 32, vcc
	v_ldexp_f32 v158, v158, v160
	v_log_f32_e32 v158, v158
	s_nop 0
	v_mul_f32_e32 v160, 0x3f317217, v158
	v_fma_f32 v160, v158, s3, -v160
	v_fmac_f32_e32 v160, 0x3377d1cf, v158
	v_fmac_f32_e32 v160, 0x3f317217, v158
	v_cmp_lt_f32_e64 s[38:39], |v158|, s6
	s_nop 1
	v_cndmask_b32_e64 v158, v158, v160, s[38:39]
	v_cndmask_b32_e32 v160, 0, v224, vcc
	v_sub_f32_e32 v158, v158, v160
	v_cmp_gt_f32_e32 vcc, s2, v159
	v_max_f32_e32 v161, 0xc2700000, v158
	v_cvt_pk_bf16_f32 v160, v164, v165
	v_cndmask_b32_e64 v158, 0, 32, vcc
	v_ldexp_f32 v158, v159, v158
	v_log_f32_e32 v158, v158
	v_cvt_f32_i32_e32 v165, v115
	v_cvt_f32_i32_e32 v164, v114
	v_mul_f32_e32 v159, 0x3f317217, v158
	v_fma_f32 v159, v158, s3, -v159
	v_fmac_f32_e32 v159, 0x3377d1cf, v158
	v_fmac_f32_e32 v159, 0x3f317217, v158
	v_cmp_lt_f32_e64 s[38:39], |v158|, s6
	s_nop 1
	v_cndmask_b32_e64 v158, v158, v159, s[38:39]
	v_cndmask_b32_e32 v159, 0, v224, vcc
	v_sub_f32_e32 v158, v158, v159
	v_max_f32_e32 v168, 0xc2700000, v158
	v_cvt_pk_bf16_f32 v158, v157, v162
	v_mad_i64_i32 v[162:163], s[0:1], v163, s81, v[204:205]
	v_cvt_pk_bf16_f32 v159, v166, v167
	v_cvt_pk_bf16_f32 v161, v161, v168
	v_lshl_add_u64 v[174:175], v[162:163], 0, v[152:153]
	global_store_dwordx4 v[174:175], v[158:161], off
	ds_bpermute_b32 v158, v210, v209 offset:128
	v_cvt_f32_i32_e32 v167, v113
	v_cvt_f32_i32_e32 v166, v112
	v_cvt_f32_i32_e32 v163, v109
	v_cvt_f32_i32_e32 v162, v108
	s_waitcnt lgkmcnt(0)
	v_pk_mul_f32 v[178:179], v[188:189], v[158:159] op_sel_hi:[1,0]
	v_cvt_f32_i32_e32 v161, v111
	v_pk_mul_f32 v[166:167], v[166:167], v[178:179]
	v_cvt_f32_i32_e32 v160, v110
	v_pk_mul_f32 v[166:167], v[166:167], s[10:11] op_sel_hi:[1,0]
	v_cvt_f32_i32_e32 v179, v105
	v_exp_f32_e32 v166, v166
	v_exp_f32_e32 v167, v167
	v_cvt_f32_i32_e32 v178, v104
	v_pk_add_f32 v[166:167], v[166:167], 1.0 op_sel_hi:[1,0]
	s_nop 0
	v_rcp_f32_e32 v166, v166
	v_rcp_f32_e32 v167, v167
	s_nop 0
	v_pk_fma_f32 v[166:167], v[190:191], v[166:167], v[136:137]
	s_nop 0
	v_cmp_gt_f32_e32 vcc, s2, v166
	s_nop 1
	v_cndmask_b32_e64 v157, 0, 32, vcc
	v_ldexp_f32 v157, v166, v157
	v_log_f32_e32 v157, v157
	s_nop 0
	v_mul_f32_e32 v159, 0x3f317217, v157
	v_fma_f32 v159, v157, s3, -v159
	v_fmac_f32_e32 v159, 0x3377d1cf, v157
	v_fmac_f32_e32 v159, 0x3f317217, v157
	v_cmp_lt_f32_e64 s[38:39], |v157|, s6
	s_nop 1
	v_cndmask_b32_e64 v157, v157, v159, s[38:39]
	v_cndmask_b32_e32 v159, 0, v224, vcc
	v_cmp_gt_f32_e32 vcc, s2, v167
	v_sub_f32_e32 v157, v157, v159
	v_max_f32_e32 v157, 0xc2700000, v157
	v_cndmask_b32_e64 v159, 0, 32, vcc
	v_ldexp_f32 v159, v167, v159
	v_log_f32_e32 v159, v159
	s_nop 0
	v_mul_f32_e32 v166, 0x3f317217, v159
	v_fma_f32 v166, v159, s3, -v166
	v_fmac_f32_e32 v166, 0x3377d1cf, v159
	v_fmac_f32_e32 v166, 0x3f317217, v159
	v_cmp_lt_f32_e64 s[38:39], |v159|, s6
	s_nop 1
	v_cndmask_b32_e64 v159, v159, v166, s[38:39]
	v_cndmask_b32_e32 v166, 0, v224, vcc
	v_sub_f32_e32 v159, v159, v166
	v_max_f32_e32 v159, 0xc2700000, v159
	v_pk_mul_f32 v[166:167], v[180:181], v[158:159] op_sel_hi:[1,0]
	s_nop 0
	v_pk_mul_f32 v[164:165], v[164:165], v[166:167]
	s_nop 0
	v_pk_mul_f32 v[164:165], v[164:165], s[10:11] op_sel_hi:[1,0]
	s_nop 0
	v_exp_f32_e32 v164, v164
	v_exp_f32_e32 v165, v165
	s_nop 0
	v_pk_add_f32 v[164:165], v[164:165], 1.0 op_sel_hi:[1,0]
	s_nop 0
	v_rcp_f32_e32 v164, v164
	v_rcp_f32_e32 v165, v165
	s_nop 0
	v_pk_fma_f32 v[164:165], v[192:193], v[164:165], v[138:139]
	s_nop 0
	v_cmp_gt_f32_e32 vcc, s2, v164
	s_nop 1
	v_cndmask_b32_e64 v166, 0, 32, vcc
	v_ldexp_f32 v164, v164, v166
	v_log_f32_e32 v164, v164
	s_nop 0
	v_mul_f32_e32 v166, 0x3f317217, v164
	v_fma_f32 v166, v164, s3, -v166
	v_fmac_f32_e32 v166, 0x3377d1cf, v164
	v_fmac_f32_e32 v166, 0x3f317217, v164
	v_cmp_lt_f32_e64 s[38:39], |v164|, s6
	s_nop 1
	v_cndmask_b32_e64 v164, v164, v166, s[38:39]
	v_cndmask_b32_e32 v166, 0, v224, vcc
	v_sub_f32_e32 v164, v164, v166
	v_cmp_gt_f32_e32 vcc, s2, v165
	v_max_f32_e32 v166, 0xc2700000, v164
	s_nop 0
	v_cndmask_b32_e64 v164, 0, 32, vcc
	v_ldexp_f32 v164, v165, v164
	v_log_f32_e32 v164, v164
	s_nop 0
	v_mul_f32_e32 v165, 0x3f317217, v164
	v_fma_f32 v165, v164, s3, -v165
	v_fmac_f32_e32 v165, 0x3377d1cf, v164
	v_fmac_f32_e32 v165, 0x3f317217, v164
; __device__ __forceinline__ unsigned cvt_pk_bf16(float lo, float hi) { f32x2_t v = {lo, hi}; bf16x2_t b = __builtin_convertvector(v, bf16x2_t); return __builtin_bit_cast(unsigned, b); }
; __device__ __forceinline__ float fast_rcp(float x) { return __builtin_amdgcn_rcpf(x); }
;     template <int KIND>
;     __device__ __forceinline__ void run(const f32x4 (&acc)[2][2][4][2], const Unit& u, int wr, int wc, int fr, int fq) const {
;     ...
;             for (int ai = 0; ai < 2; ++ai)
; #pragma unroll
;                 for (int m = 0; m < 4; ++m) { const int row = row0 + ai * HALF + m * 16; const float a = __shfl(ai ? sa_hi : sa_lo, 16 * m + fr);
;                     const f32x4 f0 = __builtin_convertvector(__builtin_bit_cast(i32x4, acc[ai][bj][m][0]), f32x4), f1 = __builtin_convertvector(__builtin_bit_cast(i32x4, acc[ai][bj][m][1]), f32x4);
;                     f32x2_t v[4] = {(f32x2_t){f0[0], f0[1]}, (f32x2_t){f0[2], f0[3]}, (f32x2_t){f1[0], f1[1]}, (f32x2_t){f1[2], f1[3]}};
; #pragma unroll
;                     for (int j = 0; j < 4; ++j) {
;                         v[j] = v[j] * (sc2[j] * (f32x2_t){a, a});
;                         if (KIND == 0 || KIND == 1 || KIND == 3) {
;                             const f32x2_t e = v[j] * (f32x2_t){-LOG2E, -LOG2E};
;                             const f32x2_t dn = (f32x2_t){__builtin_amdgcn_exp2f(e[0]), __builtin_amdgcn_exp2f(e[1])} + (f32x2_t){1.0f, 1.0f};
;                             const f32x2_t sg = (f32x2_t){fast_rcp(dn[0]), fast_rcp(dn[1])};
;                             if (KIND == 0) v[j] = v[j] * sg;
;                             else if (KIND == 3) v[j] = (v[j] * sg) * aux2[j];
;                             else { const f32x2_t f = __builtin_elementwise_fma((f32x2_t){1.0f, 1.0f} - aux2[j], sg, aux2[j]);
;                                 v[j] = (f32x2_t){fmaxf(__logf(f[0]), -60.0f), fmaxf(__logf(f[1]), -60.0f)}; }
;                         }
;                     }
;                     u32x4 w; w.x = cvt_pk_bf16(v[0][0], v[0][1]); w.y = cvt_pk_bf16(v[1][0], v[1][1]); w.z = cvt_pk_bf16(v[2][0], v[2][1]); w.w = cvt_pk_bf16(v[3][0], v[3][1]);
;                     *(u32x4*)(O + (size_t)row * NPROJ + col0 + bj * HALF) = w; }
	v_cmp_lt_f32_e64 s[38:39], |v164|, s6
	s_nop 1
	v_cndmask_b32_e64 v164, v164, v165, s[38:39]
	v_cndmask_b32_e32 v165, 0, v224, vcc
	v_sub_f32_e32 v164, v164, v165
	v_max_f32_e32 v167, 0xc2700000, v164
	v_pk_mul_f32 v[164:165], v[170:171], v[158:159] op_sel_hi:[1,0]
	s_nop 0
	v_pk_mul_f32 v[162:163], v[162:163], v[164:165]
	s_nop 0
	v_pk_mul_f32 v[162:163], v[162:163], s[10:11] op_sel_hi:[1,0]
	s_nop 0
	v_exp_f32_e32 v162, v162
	v_exp_f32_e32 v163, v163
	s_nop 0
	v_pk_add_f32 v[162:163], v[162:163], 1.0 op_sel_hi:[1,0]
	s_nop 0
	v_rcp_f32_e32 v162, v162
	v_rcp_f32_e32 v163, v163
	s_nop 0
	v_pk_fma_f32 v[162:163], v[194:195], v[162:163], v[132:133]
	s_nop 0
	v_cmp_gt_f32_e32 vcc, s2, v162
	s_nop 1
	v_cndmask_b32_e64 v164, 0, 32, vcc
	v_ldexp_f32 v162, v162, v164
	v_log_f32_e32 v162, v162
	s_nop 0
	v_mul_f32_e32 v164, 0x3f317217, v162
	v_fma_f32 v164, v162, s3, -v164
	v_fmac_f32_e32 v164, 0x3377d1cf, v162
	v_fmac_f32_e32 v164, 0x3f317217, v162
	v_cmp_lt_f32_e64 s[38:39], |v162|, s6
	s_nop 1
	v_cndmask_b32_e64 v162, v162, v164, s[38:39]
	v_cndmask_b32_e32 v164, 0, v224, vcc
	v_sub_f32_e32 v162, v162, v164
	v_cmp_gt_f32_e32 vcc, s2, v163
	v_max_f32_e32 v164, 0xc2700000, v162
	s_nop 0
	v_cndmask_b32_e64 v162, 0, 32, vcc
	v_ldexp_f32 v162, v163, v162
	v_log_f32_e32 v162, v162
	s_nop 0
	v_mul_f32_e32 v163, 0x3f317217, v162
	v_fma_f32 v163, v162, s3, -v163
	v_fmac_f32_e32 v163, 0x3377d1cf, v162
	v_fmac_f32_e32 v163, 0x3f317217, v162
	v_cmp_lt_f32_e64 s[38:39], |v162|, s6
	s_nop 1
	v_cndmask_b32_e64 v162, v162, v163, s[38:39]
	v_cndmask_b32_e32 v163, 0, v224, vcc
	v_sub_f32_e32 v162, v162, v163
	v_max_f32_e32 v165, 0xc2700000, v162
	v_pk_mul_f32 v[162:163], v[150:151], v[158:159] op_sel_hi:[1,0]
	s_nop 0
	v_pk_mul_f32 v[160:161], v[160:161], v[162:163]
	s_nop 0
	v_pk_mul_f32 v[160:161], v[160:161], s[10:11] op_sel_hi:[1,0]
	s_nop 0
	v_exp_f32_e32 v160, v160
	v_exp_f32_e32 v161, v161
	s_nop 0
	v_pk_add_f32 v[160:161], v[160:161], 1.0 op_sel_hi:[1,0]
	s_nop 0
	v_rcp_f32_e32 v160, v160
	v_rcp_f32_e32 v161, v161
	s_nop 0
	v_pk_fma_f32 v[160:161], v[206:207], v[160:161], v[134:135]
	s_nop 0
	v_cmp_gt_f32_e32 vcc, s2, v160
	s_nop 1
	v_cndmask_b32_e64 v162, 0, 32, vcc
	v_ldexp_f32 v160, v160, v162
	v_log_f32_e32 v160, v160
	s_nop 0
	v_mul_f32_e32 v162, 0x3f317217, v160
	v_fma_f32 v162, v160, s3, -v162
	v_fmac_f32_e32 v162, 0x3377d1cf, v160
	v_fmac_f32_e32 v162, 0x3f317217, v160
	v_cmp_lt_f32_e64 s[38:39], |v160|, s6
	s_nop 1
	v_cndmask_b32_e64 v160, v160, v162, s[38:39]
	v_cndmask_b32_e32 v162, 0, v224, vcc
	v_sub_f32_e32 v160, v160, v162
	v_cmp_gt_f32_e32 vcc, s2, v161
	v_max_f32_e32 v163, 0xc2700000, v160
	v_cvt_pk_bf16_f32 v162, v164, v165
	v_cndmask_b32_e64 v160, 0, 32, vcc
	v_ldexp_f32 v160, v161, v160
	v_log_f32_e32 v160, v160
	v_mad_i64_i32 v[164:165], s[0:1], v177, s81, v[204:205]
	v_lshl_add_u64 v[176:177], v[164:165], 0, v[152:153]
	v_mul_f32_e32 v161, 0x3f317217, v160
	v_fma_f32 v161, v160, s3, -v161
	v_fmac_f32_e32 v161, 0x3377d1cf, v160
	v_fmac_f32_e32 v161, 0x3f317217, v160
	v_cmp_lt_f32_e64 s[38:39], |v160|, s6
	v_cvt_f32_i32_e32 v165, v101
	v_cvt_f32_i32_e32 v164, v100
	v_cndmask_b32_e64 v160, v160, v161, s[38:39]
	v_cndmask_b32_e32 v161, 0, v224, vcc
	v_sub_f32_e32 v160, v160, v161
	v_max_f32_e32 v168, 0xc2700000, v160
	v_cvt_pk_bf16_f32 v160, v157, v159
	v_cvt_pk_bf16_f32 v161, v166, v167
	v_cvt_pk_bf16_f32 v163, v163, v168
	global_store_dwordx4 v[176:177], v[160:163], off
	ds_bpermute_b32 v160, v210, v209 offset:192
	v_cvt_f32_i32_e32 v167, v107
	v_cvt_f32_i32_e32 v166, v106
	v_cvt_f32_i32_e32 v163, v103
	v_cvt_f32_i32_e32 v162, v102
	s_waitcnt lgkmcnt(0)
	v_pk_mul_f32 v[182:183], v[188:189], v[160:161] op_sel_hi:[1,0]
	v_cvt_f32_i32_e32 v209, v71
	v_pk_mul_f32 v[178:179], v[178:179], v[182:183]
	v_cvt_f32_i32_e32 v183, v99
	v_pk_mul_f32 v[178:179], v[178:179], s[10:11] op_sel_hi:[1,0]
	v_cvt_f32_i32_e32 v182, v98
	v_exp_f32_e32 v178, v178
	v_exp_f32_e32 v179, v179
	s_nop 0
	v_pk_add_f32 v[178:179], v[178:179], 1.0 op_sel_hi:[1,0]
	s_nop 0
	v_rcp_f32_e32 v178, v178
	v_rcp_f32_e32 v179, v179
	s_nop 0
	v_pk_fma_f32 v[178:179], v[190:191], v[178:179], v[136:137]
	s_nop 0
	v_cmp_gt_f32_e32 vcc, s2, v178
	s_nop 1
	v_cndmask_b32_e64 v157, 0, 32, vcc
	v_ldexp_f32 v157, v178, v157
	v_log_f32_e32 v157, v157
	s_nop 0
	v_mul_f32_e32 v159, 0x3f317217, v157
	v_fma_f32 v159, v157, s3, -v159
	v_fmac_f32_e32 v159, 0x3377d1cf, v157
	v_fmac_f32_e32 v159, 0x3f317217, v157
	v_cmp_lt_f32_e64 s[38:39], |v157|, s6
	s_nop 1
	v_cndmask_b32_e64 v157, v157, v159, s[38:39]
	v_cndmask_b32_e32 v159, 0, v224, vcc
	v_cmp_gt_f32_e32 vcc, s2, v179
	v_sub_f32_e32 v157, v157, v159
	v_max_f32_e32 v157, 0xc2700000, v157
	v_cndmask_b32_e64 v159, 0, 32, vcc
	v_ldexp_f32 v159, v179, v159
	v_log_f32_e32 v159, v159
	s_nop 0
	v_mul_f32_e32 v161, 0x3f317217, v159
	v_fma_f32 v161, v159, s3, -v161
	v_fmac_f32_e32 v161, 0x3377d1cf, v159
	v_fmac_f32_e32 v161, 0x3f317217, v159
	v_cmp_lt_f32_e64 s[38:39], |v159|, s6
	s_nop 1
	v_cndmask_b32_e64 v159, v159, v161, s[38:39]
	v_cndmask_b32_e32 v161, 0, v224, vcc
	v_pk_mul_f32 v[178:179], v[180:181], v[160:161] op_sel_hi:[1,0]
	v_sub_f32_e32 v159, v159, v161
	v_pk_mul_f32 v[166:167], v[166:167], v[178:179]
	v_max_f32_e32 v159, 0xc2700000, v159
	v_pk_mul_f32 v[166:167], v[166:167], s[10:11] op_sel_hi:[1,0]
	s_nop 0
	v_exp_f32_e32 v166, v166
	v_exp_f32_e32 v167, v167
	s_nop 0
	v_pk_add_f32 v[166:167], v[166:167], 1.0 op_sel_hi:[1,0]
	s_nop 0
	v_rcp_f32_e32 v166, v166
	v_rcp_f32_e32 v167, v167
	s_nop 0
	v_pk_fma_f32 v[166:167], v[192:193], v[166:167], v[138:139]
	s_nop 0
	v_cmp_gt_f32_e32 vcc, s2, v166
	s_nop 1
	v_cndmask_b32_e64 v161, 0, 32, vcc
; __device__ __forceinline__ unsigned cvt_pk_bf16(float lo, float hi) { f32x2_t v = {lo, hi}; bf16x2_t b = __builtin_convertvector(v, bf16x2_t); return __builtin_bit_cast(unsigned, b); }
; __device__ __forceinline__ float fast_rcp(float x) { return __builtin_amdgcn_rcpf(x); }
;     template <int KIND>
;     __device__ __forceinline__ void run(const f32x4 (&acc)[2][2][4][2], const Unit& u, int wr, int wc, int fr, int fq) const {
;     ...
;             for (int ai = 0; ai < 2; ++ai)
; #pragma unroll
;                 for (int m = 0; m < 4; ++m) { const int row = row0 + ai * HALF + m * 16; const float a = __shfl(ai ? sa_hi : sa_lo, 16 * m + fr);
;                     const f32x4 f0 = __builtin_convertvector(__builtin_bit_cast(i32x4, acc[ai][bj][m][0]), f32x4), f1 = __builtin_convertvector(__builtin_bit_cast(i32x4, acc[ai][bj][m][1]), f32x4);
;                     f32x2_t v[4] = {(f32x2_t){f0[0], f0[1]}, (f32x2_t){f0[2], f0[3]}, (f32x2_t){f1[0], f1[1]}, (f32x2_t){f1[2], f1[3]}};
; #pragma unroll
;                     for (int j = 0; j < 4; ++j) {
;                         v[j] = v[j] * (sc2[j] * (f32x2_t){a, a});
;                         if (KIND == 0 || KIND == 1 || KIND == 3) {
;                             const f32x2_t e = v[j] * (f32x2_t){-LOG2E, -LOG2E};
;                             const f32x2_t dn = (f32x2_t){__builtin_amdgcn_exp2f(e[0]), __builtin_amdgcn_exp2f(e[1])} + (f32x2_t){1.0f, 1.0f};
;                             const f32x2_t sg = (f32x2_t){fast_rcp(dn[0]), fast_rcp(dn[1])};
;                             if (KIND == 0) v[j] = v[j] * sg;
;                             else if (KIND == 3) v[j] = (v[j] * sg) * aux2[j];
;                             else { const f32x2_t f = __builtin_elementwise_fma((f32x2_t){1.0f, 1.0f} - aux2[j], sg, aux2[j]);
;                                 v[j] = (f32x2_t){fmaxf(__logf(f[0]), -60.0f), fmaxf(__logf(f[1]), -60.0f)}; }
;                         }
;                     }
;                     u32x4 w; w.x = cvt_pk_bf16(v[0][0], v[0][1]); w.y = cvt_pk_bf16(v[1][0], v[1][1]); w.z = cvt_pk_bf16(v[2][0], v[2][1]); w.w = cvt_pk_bf16(v[3][0], v[3][1]);
;                     *(u32x4*)(O + (size_t)row * NPROJ + col0 + bj * HALF) = w; }
	v_ldexp_f32 v161, v166, v161
	v_log_f32_e32 v161, v161
	s_nop 0
	v_mul_f32_e32 v166, 0x3f317217, v161
	v_fma_f32 v166, v161, s3, -v166
	v_fmac_f32_e32 v166, 0x3377d1cf, v161
	v_fmac_f32_e32 v166, 0x3f317217, v161
	v_cmp_lt_f32_e64 s[38:39], |v161|, s6
	s_nop 1
	v_cndmask_b32_e64 v161, v161, v166, s[38:39]
	v_cndmask_b32_e32 v166, 0, v224, vcc
	v_cmp_gt_f32_e32 vcc, s2, v167
	v_sub_f32_e32 v161, v161, v166
	v_max_f32_e32 v161, 0xc2700000, v161
	v_cndmask_b32_e64 v166, 0, 32, vcc
	v_ldexp_f32 v166, v167, v166
	v_log_f32_e32 v166, v166
	s_nop 0
	v_mul_f32_e32 v167, 0x3f317217, v166
	v_fma_f32 v167, v166, s3, -v167
	v_fmac_f32_e32 v167, 0x3377d1cf, v166
	v_fmac_f32_e32 v167, 0x3f317217, v166
	v_cmp_lt_f32_e64 s[38:39], |v166|, s6
	s_nop 1
	v_cndmask_b32_e64 v166, v166, v167, s[38:39]
	v_cndmask_b32_e32 v167, 0, v224, vcc
	v_sub_f32_e32 v166, v166, v167
	v_max_f32_e32 v168, 0xc2700000, v166
	v_pk_mul_f32 v[166:167], v[170:171], v[160:161] op_sel_hi:[1,0]
	s_nop 0
	v_pk_mul_f32 v[164:165], v[164:165], v[166:167]
	s_nop 0
	v_pk_mul_f32 v[164:165], v[164:165], s[10:11] op_sel_hi:[1,0]
	s_nop 0
	v_exp_f32_e32 v164, v164
	v_exp_f32_e32 v165, v165
	s_nop 0
	v_pk_add_f32 v[164:165], v[164:165], 1.0 op_sel_hi:[1,0]
	s_nop 0
	v_rcp_f32_e32 v164, v164
	v_rcp_f32_e32 v165, v165
	s_nop 0
	v_pk_fma_f32 v[164:165], v[194:195], v[164:165], v[132:133]
	s_nop 0
	v_cmp_gt_f32_e32 vcc, s2, v164
	s_nop 1
	v_cndmask_b32_e64 v166, 0, 32, vcc
	v_ldexp_f32 v164, v164, v166
	v_log_f32_e32 v164, v164
	s_nop 0
	v_mul_f32_e32 v166, 0x3f317217, v164
	v_fma_f32 v166, v164, s3, -v166
	v_fmac_f32_e32 v166, 0x3377d1cf, v164
	v_fmac_f32_e32 v166, 0x3f317217, v164
	v_cmp_lt_f32_e64 s[38:39], |v164|, s6
	s_nop 1
	v_cndmask_b32_e64 v164, v164, v166, s[38:39]
	v_cndmask_b32_e32 v166, 0, v224, vcc
	v_sub_f32_e32 v164, v164, v166
	v_cmp_gt_f32_e32 vcc, s2, v165
	v_max_f32_e32 v166, 0xc2700000, v164
	s_nop 0
	v_cndmask_b32_e64 v164, 0, 32, vcc
	v_ldexp_f32 v164, v165, v164
	v_log_f32_e32 v164, v164
	s_nop 0
	v_mul_f32_e32 v165, 0x3f317217, v164
	v_fma_f32 v165, v164, s3, -v165
	v_fmac_f32_e32 v165, 0x3377d1cf, v164
	v_fmac_f32_e32 v165, 0x3f317217, v164
	v_cmp_lt_f32_e64 s[38:39], |v164|, s6
	s_nop 1
	v_cndmask_b32_e64 v164, v164, v165, s[38:39]
	v_cndmask_b32_e32 v165, 0, v224, vcc
	v_sub_f32_e32 v164, v164, v165
	v_max_f32_e32 v167, 0xc2700000, v164
	v_pk_mul_f32 v[164:165], v[150:151], v[160:161] op_sel_hi:[1,0]
	s_nop 0
	v_pk_mul_f32 v[162:163], v[162:163], v[164:165]
	s_nop 0
	v_pk_mul_f32 v[162:163], v[162:163], s[10:11] op_sel_hi:[1,0]
	s_nop 0
	v_exp_f32_e32 v162, v162
	v_exp_f32_e32 v163, v163
	s_nop 0
	v_pk_add_f32 v[162:163], v[162:163], 1.0 op_sel_hi:[1,0]
	s_nop 0
	v_rcp_f32_e32 v162, v162
	v_rcp_f32_e32 v163, v163
	s_nop 0
	v_pk_fma_f32 v[162:163], v[206:207], v[162:163], v[134:135]
	s_nop 0
	v_cmp_gt_f32_e32 vcc, s2, v162
	s_nop 1
	v_cndmask_b32_e64 v164, 0, 32, vcc
	v_ldexp_f32 v162, v162, v164
	v_log_f32_e32 v162, v162
	s_nop 0
	v_mul_f32_e32 v164, 0x3f317217, v162
	v_fma_f32 v164, v162, s3, -v164
	v_fmac_f32_e32 v164, 0x3377d1cf, v162
	v_fmac_f32_e32 v164, 0x3f317217, v162
	v_cmp_lt_f32_e64 s[38:39], |v162|, s6
	s_nop 1
	v_cndmask_b32_e64 v162, v162, v164, s[38:39]
	v_cndmask_b32_e32 v164, 0, v224, vcc
	v_sub_f32_e32 v162, v162, v164
	v_cmp_gt_f32_e32 vcc, s2, v163
	v_max_f32_e32 v165, 0xc2700000, v162
	v_cvt_pk_bf16_f32 v164, v166, v167
	v_cndmask_b32_e64 v162, 0, 32, vcc
	v_ldexp_f32 v162, v163, v162
	v_log_f32_e32 v162, v162
	v_mad_i64_i32 v[166:167], s[0:1], v187, s81, v[204:205]
	v_cvt_f32_i32_e32 v187, v77
	v_mul_f32_e32 v163, 0x3f317217, v162
	v_fma_f32 v163, v162, s3, -v163
	v_fmac_f32_e32 v163, 0x3377d1cf, v162
	v_fmac_f32_e32 v163, 0x3f317217, v162
	v_cmp_lt_f32_e64 s[38:39], |v162|, s6
	s_nop 1
	v_cndmask_b32_e64 v162, v162, v163, s[38:39]
	v_cndmask_b32_e32 v163, 0, v224, vcc
	v_sub_f32_e32 v162, v162, v163
	v_max_f32_e32 v178, 0xc2700000, v162
	v_cvt_pk_bf16_f32 v162, v157, v159
	v_cvt_pk_bf16_f32 v163, v161, v168
	v_cvt_pk_bf16_f32 v165, v165, v178
	v_lshl_add_u64 v[178:179], v[166:167], 0, v[152:153]
	global_store_dwordx4 v[178:179], v[162:165], off
	ds_bpermute_b32 v162, v210, v208
	v_cvt_f32_i32_e32 v167, v93
	v_cvt_f32_i32_e32 v166, v92
	v_cvt_f32_i32_e32 v165, v95
	v_cvt_f32_i32_e32 v164, v94
	s_waitcnt lgkmcnt(0)
; __device__ __forceinline__ unsigned cvt_pk_bf16(float lo, float hi) { f32x2_t v = {lo, hi}; bf16x2_t b = __builtin_convertvector(v, bf16x2_t); return __builtin_bit_cast(unsigned, b); }
; __device__ __forceinline__ float fast_rcp(float x) { return __builtin_amdgcn_rcpf(x); }
;     template <int KIND>
;     __device__ __forceinline__ void run(const f32x4 (&acc)[2][2][4][2], const Unit& u, int wr, int wc, int fr, int fq) const {
;     ...
;             for (int ai = 0; ai < 2; ++ai)
; #pragma unroll
;                 for (int m = 0; m < 4; ++m) { const int row = row0 + ai * HALF + m * 16; const float a = __shfl(ai ? sa_hi : sa_lo, 16 * m + fr);
;                     const f32x4 f0 = __builtin_convertvector(__builtin_bit_cast(i32x4, acc[ai][bj][m][0]), f32x4), f1 = __builtin_convertvector(__builtin_bit_cast(i32x4, acc[ai][bj][m][1]), f32x4);
;                     f32x2_t v[4] = {(f32x2_t){f0[0], f0[1]}, (f32x2_t){f0[2], f0[3]}, (f32x2_t){f1[0], f1[1]}, (f32x2_t){f1[2], f1[3]}};
; #pragma unroll
;                     for (int j = 0; j < 4; ++j) {
;                         v[j] = v[j] * (sc2[j] * (f32x2_t){a, a});
;                         if (KIND == 0 || KIND == 1 || KIND == 3) {
;                             const f32x2_t e = v[j] * (f32x2_t){-LOG2E, -LOG2E};
;                             const f32x2_t dn = (f32x2_t){__builtin_amdgcn_exp2f(e[0]), __builtin_amdgcn_exp2f(e[1])} + (f32x2_t){1.0f, 1.0f};
;                             const f32x2_t sg = (f32x2_t){fast_rcp(dn[0]), fast_rcp(dn[1])};
;                             if (KIND == 0) v[j] = v[j] * sg;
;                             else if (KIND == 3) v[j] = (v[j] * sg) * aux2[j];
;                             else { const f32x2_t f = __builtin_elementwise_fma((f32x2_t){1.0f, 1.0f} - aux2[j], sg, aux2[j]);
;                                 v[j] = (f32x2_t){fmaxf(__logf(f[0]), -60.0f), fmaxf(__logf(f[1]), -60.0f)}; }
;                         }
;                     }
;                     u32x4 w; w.x = cvt_pk_bf16(v[0][0], v[0][1]); w.y = cvt_pk_bf16(v[1][0], v[1][1]); w.z = cvt_pk_bf16(v[2][0], v[2][1]); w.w = cvt_pk_bf16(v[3][0], v[3][1]);
;                     *(u32x4*)(O + (size_t)row * NPROJ + col0 + bj * HALF) = w; }
	v_pk_mul_f32 v[196:197], v[188:189], v[162:163] op_sel_hi:[1,0]
	s_nop 0
	v_pk_mul_f32 v[184:185], v[184:185], v[196:197]
	v_cvt_f32_i32_e32 v197, v89
	v_pk_mul_f32 v[184:185], v[184:185], s[10:11] op_sel_hi:[1,0]
	v_cvt_f32_i32_e32 v196, v88
	v_exp_f32_e32 v184, v184
	v_exp_f32_e32 v185, v185
	s_nop 0
	v_pk_add_f32 v[184:185], v[184:185], 1.0 op_sel_hi:[1,0]
	s_nop 0
	v_rcp_f32_e32 v184, v184
	v_rcp_f32_e32 v185, v185
	s_nop 0
	v_pk_fma_f32 v[184:185], v[190:191], v[184:185], v[136:137]
	s_nop 0
	v_cmp_gt_f32_e32 vcc, s2, v184
	s_nop 1
	v_cndmask_b32_e64 v157, 0, 32, vcc
	v_ldexp_f32 v157, v184, v157
	v_log_f32_e32 v157, v157
	s_nop 0
	v_mul_f32_e32 v159, 0x3f317217, v157
	v_fma_f32 v159, v157, s3, -v159
	v_fmac_f32_e32 v159, 0x3377d1cf, v157
	v_fmac_f32_e32 v159, 0x3f317217, v157
	v_cmp_lt_f32_e64 s[38:39], |v157|, s6
	s_nop 1
	v_cndmask_b32_e64 v157, v157, v159, s[38:39]
	v_cndmask_b32_e32 v159, 0, v224, vcc
	v_cmp_gt_f32_e32 vcc, s2, v185
	v_sub_f32_e32 v157, v157, v159
	v_max_f32_e32 v157, 0xc2700000, v157
	v_cndmask_b32_e64 v159, 0, 32, vcc
	v_ldexp_f32 v159, v185, v159
	v_pk_mul_f32 v[184:185], v[180:181], v[162:163] op_sel_hi:[1,0]
	v_log_f32_e32 v159, v159
	v_pk_mul_f32 v[182:183], v[182:183], v[184:185]
	v_cvt_f32_i32_e32 v185, v91
	v_pk_mul_f32 v[182:183], v[182:183], s[10:11] op_sel_hi:[1,0]
	v_mul_f32_e32 v161, 0x3f317217, v159
	v_exp_f32_e32 v182, v182
	v_exp_f32_e32 v183, v183
	v_fma_f32 v161, v159, s3, -v161
	v_fmac_f32_e32 v161, 0x3377d1cf, v159
	v_fmac_f32_e32 v161, 0x3f317217, v159
	v_pk_add_f32 v[182:183], v[182:183], 1.0 op_sel_hi:[1,0]
	v_cmp_lt_f32_e64 s[38:39], |v159|, s6
	v_rcp_f32_e32 v182, v182
	v_rcp_f32_e32 v183, v183
	v_cndmask_b32_e64 v159, v159, v161, s[38:39]
	v_cndmask_b32_e32 v161, 0, v224, vcc
	v_sub_f32_e32 v159, v159, v161
	v_pk_fma_f32 v[182:183], v[192:193], v[182:183], v[138:139]
	v_max_f32_e32 v159, 0xc2700000, v159
	v_cmp_gt_f32_e32 vcc, s2, v182
	v_cvt_f32_i32_e32 v184, v90
	s_nop 0
	v_cndmask_b32_e64 v161, 0, 32, vcc
	v_ldexp_f32 v161, v182, v161
	v_log_f32_e32 v161, v161
	s_nop 0
	v_mul_f32_e32 v163, 0x3f317217, v161
	v_fma_f32 v163, v161, s3, -v163
	v_fmac_f32_e32 v163, 0x3377d1cf, v161
	v_fmac_f32_e32 v163, 0x3f317217, v161
	v_cmp_lt_f32_e64 s[38:39], |v161|, s6
	s_nop 1
	v_cndmask_b32_e64 v161, v161, v163, s[38:39]
	v_cndmask_b32_e32 v163, 0, v224, vcc
	v_cmp_gt_f32_e32 vcc, s2, v183
	v_sub_f32_e32 v161, v161, v163
	v_max_f32_e32 v161, 0xc2700000, v161
	v_cndmask_b32_e64 v163, 0, 32, vcc
	v_ldexp_f32 v163, v183, v163
	v_log_f32_e32 v163, v163
	s_nop 0
	v_mul_f32_e32 v168, 0x3f317217, v163
	v_fma_f32 v168, v163, s3, -v168
	v_fmac_f32_e32 v168, 0x3377d1cf, v163
	v_fmac_f32_e32 v168, 0x3f317217, v163
	v_cmp_lt_f32_e64 s[38:39], |v163|, s6
	s_nop 1
	v_cndmask_b32_e64 v163, v163, v168, s[38:39]
	v_cndmask_b32_e32 v168, 0, v224, vcc
	v_sub_f32_e32 v163, v163, v168
	v_max_f32_e32 v163, 0xc2700000, v163
	v_pk_mul_f32 v[182:183], v[170:171], v[162:163] op_sel_hi:[1,0]
	s_nop 0
	v_pk_mul_f32 v[166:167], v[166:167], v[182:183]
	s_nop 0
	v_pk_mul_f32 v[166:167], v[166:167], s[10:11] op_sel_hi:[1,0]
	s_nop 0
	v_exp_f32_e32 v166, v166
	v_exp_f32_e32 v167, v167
	s_nop 0
	v_pk_add_f32 v[166:167], v[166:167], 1.0 op_sel_hi:[1,0]
	s_nop 0
	v_rcp_f32_e32 v166, v166
	v_rcp_f32_e32 v167, v167
	s_nop 0
	v_pk_fma_f32 v[166:167], v[194:195], v[166:167], v[132:133]
	s_nop 0
	v_cmp_gt_f32_e32 vcc, s2, v166
	s_nop 1
	v_cndmask_b32_e64 v168, 0, 32, vcc
	v_ldexp_f32 v166, v166, v168
	v_log_f32_e32 v166, v166
	s_nop 0
	v_mul_f32_e32 v168, 0x3f317217, v166
	v_fma_f32 v168, v166, s3, -v168
	v_fmac_f32_e32 v168, 0x3377d1cf, v166
	v_fmac_f32_e32 v168, 0x3f317217, v166
	v_cmp_lt_f32_e64 s[38:39], |v166|, s6
	s_nop 1
	v_cndmask_b32_e64 v166, v166, v168, s[38:39]
	v_cndmask_b32_e32 v168, 0, v224, vcc
	v_sub_f32_e32 v166, v166, v168
	v_cmp_gt_f32_e32 vcc, s2, v167
	v_max_f32_e32 v168, 0xc2700000, v166
	s_nop 0
	v_cndmask_b32_e64 v166, 0, 32, vcc
	v_ldexp_f32 v166, v167, v166
	v_log_f32_e32 v166, v166
	s_nop 0
	v_mul_f32_e32 v167, 0x3f317217, v166
	v_fma_f32 v167, v166, s3, -v167
	v_fmac_f32_e32 v167, 0x3377d1cf, v166
	v_fmac_f32_e32 v167, 0x3f317217, v166
	v_cmp_lt_f32_e64 s[38:39], |v166|, s6
	s_nop 1
	v_cndmask_b32_e64 v166, v166, v167, s[38:39]
	v_cndmask_b32_e32 v167, 0, v224, vcc
	v_sub_f32_e32 v166, v166, v167
	v_max_f32_e32 v182, 0xc2700000, v166
	v_pk_mul_f32 v[166:167], v[150:151], v[162:163] op_sel_hi:[1,0]
	s_nop 0
	v_pk_mul_f32 v[164:165], v[164:165], v[166:167]
	s_nop 0
	v_pk_mul_f32 v[164:165], v[164:165], s[10:11] op_sel_hi:[1,0]
	s_nop 0
	v_exp_f32_e32 v164, v164
	v_exp_f32_e32 v165, v165
	s_nop 0
	v_pk_add_f32 v[164:165], v[164:165], 1.0 op_sel_hi:[1,0]
	s_nop 0
	v_rcp_f32_e32 v164, v164
	v_rcp_f32_e32 v165, v165
	s_nop 0
	v_pk_fma_f32 v[164:165], v[206:207], v[164:165], v[134:135]
	s_nop 0
	v_cmp_gt_f32_e32 vcc, s2, v164
	s_nop 1
	v_cndmask_b32_e64 v166, 0, 32, vcc
	v_ldexp_f32 v164, v164, v166
	v_log_f32_e32 v164, v164
	s_nop 0
	v_mul_f32_e32 v166, 0x3f317217, v164
	v_fma_f32 v166, v164, s3, -v166
	v_fmac_f32_e32 v166, 0x3377d1cf, v164
	v_fmac_f32_e32 v166, 0x3f317217, v164
	v_cmp_lt_f32_e64 s[38:39], |v164|, s6
	s_nop 1
	v_cndmask_b32_e64 v164, v164, v166, s[38:39]
	v_cndmask_b32_e32 v166, 0, v224, vcc
	v_sub_f32_e32 v164, v164, v166
	v_cmp_gt_f32_e32 vcc, s2, v165
	v_max_f32_e32 v167, 0xc2700000, v164
	v_cvt_pk_bf16_f32 v166, v168, v182
	v_cndmask_b32_e64 v164, 0, 32, vcc
	v_ldexp_f32 v164, v165, v164
	v_log_f32_e32 v164, v164
	v_mad_i64_i32 v[168:169], s[0:1], v169, s81, v[204:205]
	v_mul_f32_e32 v165, 0x3f317217, v164
	v_fma_f32 v165, v164, s3, -v165
	v_fmac_f32_e32 v165, 0x3377d1cf, v164
	v_fmac_f32_e32 v165, 0x3f317217, v164
	v_cmp_lt_f32_e64 s[38:39], |v164|, s6
	s_nop 1
	v_cndmask_b32_e64 v164, v164, v165, s[38:39]
	v_cndmask_b32_e32 v165, 0, v224, vcc
	v_sub_f32_e32 v164, v164, v165
	v_max_f32_e32 v183, 0xc2700000, v164
	v_cvt_pk_bf16_f32 v164, v157, v159
	v_cvt_pk_bf16_f32 v165, v161, v163
	v_cvt_pk_bf16_f32 v167, v167, v183
	v_lshl_add_u64 v[182:183], v[168:169], 0, v[152:153]
	global_store_dwordx4 v[182:183], v[164:167], off
	ds_bpermute_b32 v164, v210, v208 offset:64
	v_cvt_f32_i32_e32 v169, v85
	v_cvt_f32_i32_e32 v168, v84
	v_cvt_f32_i32_e32 v167, v87
	v_cvt_f32_i32_e32 v166, v86
	s_waitcnt lgkmcnt(0)
; __device__ __forceinline__ unsigned cvt_pk_bf16(float lo, float hi) { f32x2_t v = {lo, hi}; bf16x2_t b = __builtin_convertvector(v, bf16x2_t); return __builtin_bit_cast(unsigned, b); }
; __device__ __forceinline__ float fast_rcp(float x) { return __builtin_amdgcn_rcpf(x); }
;     template <int KIND>
;     __device__ __forceinline__ void run(const f32x4 (&acc)[2][2][4][2], const Unit& u, int wr, int wc, int fr, int fq) const {
;     ...
;             for (int ai = 0; ai < 2; ++ai)
; #pragma unroll
;                 for (int m = 0; m < 4; ++m) { const int row = row0 + ai * HALF + m * 16; const float a = __shfl(ai ? sa_hi : sa_lo, 16 * m + fr);
;                     const f32x4 f0 = __builtin_convertvector(__builtin_bit_cast(i32x4, acc[ai][bj][m][0]), f32x4), f1 = __builtin_convertvector(__builtin_bit_cast(i32x4, acc[ai][bj][m][1]), f32x4);
;                     f32x2_t v[4] = {(f32x2_t){f0[0], f0[1]}, (f32x2_t){f0[2], f0[3]}, (f32x2_t){f1[0], f1[1]}, (f32x2_t){f1[2], f1[3]}};
; #pragma unroll
;                     for (int j = 0; j < 4; ++j) {
;                         v[j] = v[j] * (sc2[j] * (f32x2_t){a, a});
;                         if (KIND == 0 || KIND == 1 || KIND == 3) {
;                             const f32x2_t e = v[j] * (f32x2_t){-LOG2E, -LOG2E};
;                             const f32x2_t dn = (f32x2_t){__builtin_amdgcn_exp2f(e[0]), __builtin_amdgcn_exp2f(e[1])} + (f32x2_t){1.0f, 1.0f};
;                             const f32x2_t sg = (f32x2_t){fast_rcp(dn[0]), fast_rcp(dn[1])};
;                             if (KIND == 0) v[j] = v[j] * sg;
;                             else if (KIND == 3) v[j] = (v[j] * sg) * aux2[j];
;                             else { const f32x2_t f = __builtin_elementwise_fma((f32x2_t){1.0f, 1.0f} - aux2[j], sg, aux2[j]);
;                                 v[j] = (f32x2_t){fmaxf(__logf(f[0]), -60.0f), fmaxf(__logf(f[1]), -60.0f)}; }
;                         }
;                     }
;                     u32x4 w; w.x = cvt_pk_bf16(v[0][0], v[0][1]); w.y = cvt_pk_bf16(v[1][0], v[1][1]); w.z = cvt_pk_bf16(v[2][0], v[2][1]); w.w = cvt_pk_bf16(v[3][0], v[3][1]);
;                     *(u32x4*)(O + (size_t)row * NPROJ + col0 + bj * HALF) = w; }
	v_pk_mul_f32 v[198:199], v[188:189], v[164:165] op_sel_hi:[1,0]
	s_nop 0
	v_pk_mul_f32 v[196:197], v[196:197], v[198:199]
	v_cvt_f32_i32_e32 v199, v81
	v_pk_mul_f32 v[196:197], v[196:197], s[10:11] op_sel_hi:[1,0]
	v_cvt_f32_i32_e32 v198, v80
	v_exp_f32_e32 v196, v196
	v_exp_f32_e32 v197, v197
	s_nop 0
	v_pk_add_f32 v[196:197], v[196:197], 1.0 op_sel_hi:[1,0]
	s_nop 0
	v_rcp_f32_e32 v196, v196
	v_rcp_f32_e32 v197, v197
	s_nop 0
	v_pk_fma_f32 v[196:197], v[190:191], v[196:197], v[136:137]
	s_nop 0
	v_cmp_gt_f32_e32 vcc, s2, v196
	s_nop 1
	v_cndmask_b32_e64 v157, 0, 32, vcc
	v_ldexp_f32 v157, v196, v157
	v_log_f32_e32 v157, v157
	s_nop 0
	v_mul_f32_e32 v159, 0x3f317217, v157
	v_fma_f32 v159, v157, s3, -v159
	v_fmac_f32_e32 v159, 0x3377d1cf, v157
	v_fmac_f32_e32 v159, 0x3f317217, v157
	v_cmp_lt_f32_e64 s[38:39], |v157|, s6
	s_nop 1
	v_cndmask_b32_e64 v157, v157, v159, s[38:39]
	v_cndmask_b32_e32 v159, 0, v224, vcc
	v_cmp_gt_f32_e32 vcc, s2, v197
	v_sub_f32_e32 v157, v157, v159
	v_max_f32_e32 v157, 0xc2700000, v157
	v_cndmask_b32_e64 v159, 0, 32, vcc
	v_ldexp_f32 v159, v197, v159
	v_pk_mul_f32 v[196:197], v[180:181], v[164:165] op_sel_hi:[1,0]
	v_log_f32_e32 v159, v159
	v_pk_mul_f32 v[184:185], v[184:185], v[196:197]
	v_cvt_f32_i32_e32 v197, v83
	v_pk_mul_f32 v[184:185], v[184:185], s[10:11] op_sel_hi:[1,0]
	v_mul_f32_e32 v161, 0x3f317217, v159
	v_exp_f32_e32 v184, v184
	v_exp_f32_e32 v185, v185
	v_fma_f32 v161, v159, s3, -v161
	v_fmac_f32_e32 v161, 0x3377d1cf, v159
	v_fmac_f32_e32 v161, 0x3f317217, v159
	v_pk_add_f32 v[184:185], v[184:185], 1.0 op_sel_hi:[1,0]
	v_cmp_lt_f32_e64 s[38:39], |v159|, s6
	v_rcp_f32_e32 v184, v184
	v_rcp_f32_e32 v185, v185
	v_cndmask_b32_e64 v159, v159, v161, s[38:39]
	v_cndmask_b32_e32 v161, 0, v224, vcc
	v_sub_f32_e32 v159, v159, v161
	v_pk_fma_f32 v[184:185], v[192:193], v[184:185], v[138:139]
	v_max_f32_e32 v159, 0xc2700000, v159
	v_cmp_gt_f32_e32 vcc, s2, v184
	v_cvt_f32_i32_e32 v196, v82
	s_nop 0
	v_cndmask_b32_e64 v161, 0, 32, vcc
	v_ldexp_f32 v161, v184, v161
	v_log_f32_e32 v161, v161
	s_nop 0
	v_mul_f32_e32 v163, 0x3f317217, v161
	v_fma_f32 v163, v161, s3, -v163
	v_fmac_f32_e32 v163, 0x3377d1cf, v161
	v_fmac_f32_e32 v163, 0x3f317217, v161
	v_cmp_lt_f32_e64 s[38:39], |v161|, s6
	s_nop 1
	v_cndmask_b32_e64 v161, v161, v163, s[38:39]
	v_cndmask_b32_e32 v163, 0, v224, vcc
	v_cmp_gt_f32_e32 vcc, s2, v185
	v_sub_f32_e32 v161, v161, v163
	v_max_f32_e32 v161, 0xc2700000, v161
	v_cndmask_b32_e64 v163, 0, 32, vcc
	v_ldexp_f32 v163, v185, v163
	v_log_f32_e32 v163, v163
	s_nop 0
	v_mul_f32_e32 v165, 0x3f317217, v163
	v_fma_f32 v165, v163, s3, -v165
	v_fmac_f32_e32 v165, 0x3377d1cf, v163
	v_fmac_f32_e32 v165, 0x3f317217, v163
	v_cmp_lt_f32_e64 s[38:39], |v163|, s6
	s_nop 1
	v_cndmask_b32_e64 v163, v163, v165, s[38:39]
	v_cndmask_b32_e32 v165, 0, v224, vcc
	v_pk_mul_f32 v[184:185], v[170:171], v[164:165] op_sel_hi:[1,0]
	v_sub_f32_e32 v163, v163, v165
	v_pk_mul_f32 v[168:169], v[168:169], v[184:185]
	v_max_f32_e32 v163, 0xc2700000, v163
	v_pk_mul_f32 v[168:169], v[168:169], s[10:11] op_sel_hi:[1,0]
	s_nop 0
	v_exp_f32_e32 v168, v168
	v_exp_f32_e32 v169, v169
	s_nop 0
	v_pk_add_f32 v[168:169], v[168:169], 1.0 op_sel_hi:[1,0]
	s_nop 0
	v_rcp_f32_e32 v168, v168
	v_rcp_f32_e32 v169, v169
	s_nop 0
	v_pk_fma_f32 v[168:169], v[194:195], v[168:169], v[132:133]
	s_nop 0
	v_cmp_gt_f32_e32 vcc, s2, v168
	s_nop 1
	v_cndmask_b32_e64 v165, 0, 32, vcc
	v_ldexp_f32 v165, v168, v165
	v_log_f32_e32 v165, v165
	s_nop 0
	v_mul_f32_e32 v168, 0x3f317217, v165
	v_fma_f32 v168, v165, s3, -v168
	v_fmac_f32_e32 v168, 0x3377d1cf, v165
	v_fmac_f32_e32 v168, 0x3f317217, v165
	v_cmp_lt_f32_e64 s[38:39], |v165|, s6
	s_nop 1
	v_cndmask_b32_e64 v165, v165, v168, s[38:39]
	v_cndmask_b32_e32 v168, 0, v224, vcc
	v_cmp_gt_f32_e32 vcc, s2, v169
	v_sub_f32_e32 v165, v165, v168
	v_max_f32_e32 v165, 0xc2700000, v165
	v_cndmask_b32_e64 v168, 0, 32, vcc
	v_ldexp_f32 v168, v169, v168
	v_log_f32_e32 v168, v168
	s_nop 0
	v_mul_f32_e32 v169, 0x3f317217, v168
	v_fma_f32 v169, v168, s3, -v169
	v_fmac_f32_e32 v169, 0x3377d1cf, v168
	v_fmac_f32_e32 v169, 0x3f317217, v168
	v_cmp_lt_f32_e64 s[38:39], |v168|, s6
	s_nop 1
	v_cndmask_b32_e64 v168, v168, v169, s[38:39]
	v_cndmask_b32_e32 v169, 0, v224, vcc
	v_sub_f32_e32 v168, v168, v169
	v_max_f32_e32 v184, 0xc2700000, v168
	v_pk_mul_f32 v[168:169], v[150:151], v[164:165] op_sel_hi:[1,0]
	s_nop 0
	v_pk_mul_f32 v[166:167], v[166:167], v[168:169]
	s_nop 0
	v_pk_mul_f32 v[166:167], v[166:167], s[10:11] op_sel_hi:[1,0]
	s_nop 0
	v_exp_f32_e32 v166, v166
	v_exp_f32_e32 v167, v167
	s_nop 0
	v_pk_add_f32 v[166:167], v[166:167], 1.0 op_sel_hi:[1,0]
	s_nop 0
	v_rcp_f32_e32 v166, v166
	v_rcp_f32_e32 v167, v167
	s_nop 0
	v_pk_fma_f32 v[166:167], v[206:207], v[166:167], v[134:135]
	s_nop 0
	v_cmp_gt_f32_e32 vcc, s2, v166
	s_nop 1
	v_cndmask_b32_e64 v168, 0, 32, vcc
	v_ldexp_f32 v166, v166, v168
	v_log_f32_e32 v166, v166
	s_nop 0
	v_mul_f32_e32 v168, 0x3f317217, v166
	v_fma_f32 v168, v166, s3, -v168
	v_fmac_f32_e32 v168, 0x3377d1cf, v166
	v_fmac_f32_e32 v168, 0x3f317217, v166
	v_cmp_lt_f32_e64 s[38:39], |v166|, s6
	s_nop 1
	v_cndmask_b32_e64 v166, v166, v168, s[38:39]
	v_cndmask_b32_e32 v168, 0, v224, vcc
	v_sub_f32_e32 v166, v166, v168
	v_cmp_gt_f32_e32 vcc, s2, v167
	v_max_f32_e32 v169, 0xc2700000, v166
	v_cvt_pk_bf16_f32 v168, v165, v184
	v_cndmask_b32_e64 v166, 0, 32, vcc
	v_ldexp_f32 v166, v167, v166
	v_log_f32_e32 v166, v166
	s_nop 0
	v_mul_f32_e32 v167, 0x3f317217, v166
	v_fma_f32 v167, v166, s3, -v167
	v_fmac_f32_e32 v167, 0x3377d1cf, v166
	v_fmac_f32_e32 v167, 0x3f317217, v166
	v_cmp_lt_f32_e64 s[38:39], |v166|, s6
	s_nop 1
	v_cndmask_b32_e64 v166, v166, v167, s[38:39]
	v_cndmask_b32_e32 v167, 0, v224, vcc
	v_sub_f32_e32 v166, v166, v167
	v_max_f32_e32 v185, 0xc2700000, v166
	v_cvt_pk_bf16_f32 v169, v169, v185
	v_mad_i64_i32 v[184:185], s[0:1], v186, s81, v[204:205]
	v_cvt_pk_bf16_f32 v166, v157, v159
	v_cvt_pk_bf16_f32 v167, v161, v163
	v_lshl_add_u64 v[184:185], v[184:185], 0, v[152:153]
	global_store_dwordx4 v[184:185], v[166:169], off
	ds_bpermute_b32 v166, v210, v208 offset:128
	v_cvt_f32_i32_e32 v186, v76
	v_cvt_f32_i32_e32 v169, v79
	v_cvt_f32_i32_e32 v168, v78
	s_waitcnt lgkmcnt(0)
; __device__ __forceinline__ unsigned cvt_pk_bf16(float lo, float hi) { f32x2_t v = {lo, hi}; bf16x2_t b = __builtin_convertvector(v, bf16x2_t); return __builtin_bit_cast(unsigned, b); }
; __device__ __forceinline__ float fast_rcp(float x) { return __builtin_amdgcn_rcpf(x); }
;     template <int KIND>
;     __device__ __forceinline__ void run(const f32x4 (&acc)[2][2][4][2], const Unit& u, int wr, int wc, int fr, int fq) const {
;     ...
;             for (int ai = 0; ai < 2; ++ai)
; #pragma unroll
;                 for (int m = 0; m < 4; ++m) { const int row = row0 + ai * HALF + m * 16; const float a = __shfl(ai ? sa_hi : sa_lo, 16 * m + fr);
;                     const f32x4 f0 = __builtin_convertvector(__builtin_bit_cast(i32x4, acc[ai][bj][m][0]), f32x4), f1 = __builtin_convertvector(__builtin_bit_cast(i32x4, acc[ai][bj][m][1]), f32x4);
;                     f32x2_t v[4] = {(f32x2_t){f0[0], f0[1]}, (f32x2_t){f0[2], f0[3]}, (f32x2_t){f1[0], f1[1]}, (f32x2_t){f1[2], f1[3]}};
; #pragma unroll
;                     for (int j = 0; j < 4; ++j) {
;                         v[j] = v[j] * (sc2[j] * (f32x2_t){a, a});
;                         if (KIND == 0 || KIND == 1 || KIND == 3) {
;                             const f32x2_t e = v[j] * (f32x2_t){-LOG2E, -LOG2E};
;                             const f32x2_t dn = (f32x2_t){__builtin_amdgcn_exp2f(e[0]), __builtin_amdgcn_exp2f(e[1])} + (f32x2_t){1.0f, 1.0f};
;                             const f32x2_t sg = (f32x2_t){fast_rcp(dn[0]), fast_rcp(dn[1])};
;                             if (KIND == 0) v[j] = v[j] * sg;
;                             else if (KIND == 3) v[j] = (v[j] * sg) * aux2[j];
;                             else { const f32x2_t f = __builtin_elementwise_fma((f32x2_t){1.0f, 1.0f} - aux2[j], sg, aux2[j]);
;                                 v[j] = (f32x2_t){fmaxf(__logf(f[0]), -60.0f), fmaxf(__logf(f[1]), -60.0f)}; }
;                         }
;                     }
;                     u32x4 w; w.x = cvt_pk_bf16(v[0][0], v[0][1]); w.y = cvt_pk_bf16(v[1][0], v[1][1]); w.z = cvt_pk_bf16(v[2][0], v[2][1]); w.w = cvt_pk_bf16(v[3][0], v[3][1]);
;                     *(u32x4*)(O + (size_t)row * NPROJ + col0 + bj * HALF) = w; }
	v_pk_mul_f32 v[200:201], v[188:189], v[166:167] op_sel_hi:[1,0]
	s_nop 0
	v_pk_mul_f32 v[198:199], v[198:199], v[200:201]
	s_nop 0
	v_pk_mul_f32 v[198:199], v[198:199], s[10:11] op_sel_hi:[1,0]
	s_nop 0
	v_exp_f32_e32 v198, v198
	v_exp_f32_e32 v199, v199
	s_nop 0
	v_pk_add_f32 v[198:199], v[198:199], 1.0 op_sel_hi:[1,0]
	s_nop 0
	v_rcp_f32_e32 v198, v198
	v_rcp_f32_e32 v199, v199
	s_nop 0
	v_pk_fma_f32 v[198:199], v[190:191], v[198:199], v[136:137]
	s_nop 0
	v_cmp_gt_f32_e32 vcc, s2, v198
	s_nop 1
	v_cndmask_b32_e64 v157, 0, 32, vcc
	v_ldexp_f32 v157, v198, v157
	v_log_f32_e32 v157, v157
	s_nop 0
	v_mul_f32_e32 v159, 0x3f317217, v157
	v_fma_f32 v159, v157, s3, -v159
	v_fmac_f32_e32 v159, 0x3377d1cf, v157
	v_fmac_f32_e32 v159, 0x3f317217, v157
	v_cmp_lt_f32_e64 s[38:39], |v157|, s6
	s_nop 1
	v_cndmask_b32_e64 v157, v157, v159, s[38:39]
	v_cndmask_b32_e32 v159, 0, v224, vcc
	v_cmp_gt_f32_e32 vcc, s2, v199
	v_sub_f32_e32 v157, v157, v159
	v_max_f32_e32 v157, 0xc2700000, v157
	v_cndmask_b32_e64 v159, 0, 32, vcc
	v_ldexp_f32 v159, v199, v159
	v_pk_mul_f32 v[198:199], v[180:181], v[166:167] op_sel_hi:[1,0]
	v_log_f32_e32 v159, v159
	v_pk_mul_f32 v[196:197], v[196:197], v[198:199]
	v_mul_f32_e32 v161, 0x3f317217, v159
	v_pk_mul_f32 v[196:197], v[196:197], s[10:11] op_sel_hi:[1,0]
	v_fma_f32 v161, v159, s3, -v161
	v_exp_f32_e32 v196, v196
	v_exp_f32_e32 v197, v197
	v_fmac_f32_e32 v161, 0x3377d1cf, v159
	v_fmac_f32_e32 v161, 0x3f317217, v159
	v_cmp_lt_f32_e64 s[38:39], |v159|, s6
	v_pk_add_f32 v[196:197], v[196:197], 1.0 op_sel_hi:[1,0]
	s_nop 0
	v_rcp_f32_e32 v196, v196
	v_rcp_f32_e32 v197, v197
	v_cndmask_b32_e64 v159, v159, v161, s[38:39]
	v_cndmask_b32_e32 v161, 0, v224, vcc
	v_sub_f32_e32 v159, v159, v161
	v_pk_fma_f32 v[196:197], v[192:193], v[196:197], v[138:139]
	v_max_f32_e32 v159, 0xc2700000, v159
	v_cmp_gt_f32_e32 vcc, s2, v196
	s_nop 1
	v_cndmask_b32_e64 v161, 0, 32, vcc
	v_ldexp_f32 v161, v196, v161
	v_log_f32_e32 v161, v161
	s_nop 0
	v_mul_f32_e32 v163, 0x3f317217, v161
	v_fma_f32 v163, v161, s3, -v163
	v_fmac_f32_e32 v163, 0x3377d1cf, v161
	v_fmac_f32_e32 v163, 0x3f317217, v161
	v_cmp_lt_f32_e64 s[38:39], |v161|, s6
	s_nop 1
	v_cndmask_b32_e64 v161, v161, v163, s[38:39]
	v_cndmask_b32_e32 v163, 0, v224, vcc
	v_cmp_gt_f32_e32 vcc, s2, v197
	v_sub_f32_e32 v161, v161, v163
	v_max_f32_e32 v161, 0xc2700000, v161
	v_cndmask_b32_e64 v163, 0, 32, vcc
	v_ldexp_f32 v163, v197, v163
	v_pk_mul_f32 v[196:197], v[170:171], v[166:167] op_sel_hi:[1,0]
	v_log_f32_e32 v163, v163
	v_pk_mul_f32 v[186:187], v[186:187], v[196:197]
	v_cvt_pk_bf16_f32 v196, v157, v159
	v_pk_mul_f32 v[186:187], v[186:187], s[10:11] op_sel_hi:[1,0]
	v_mul_f32_e32 v165, 0x3f317217, v163
	v_exp_f32_e32 v186, v186
	v_exp_f32_e32 v187, v187
	v_fma_f32 v165, v163, s3, -v165
	v_fmac_f32_e32 v165, 0x3377d1cf, v163
	v_fmac_f32_e32 v165, 0x3f317217, v163
	v_pk_add_f32 v[186:187], v[186:187], 1.0 op_sel_hi:[1,0]
	v_cmp_lt_f32_e64 s[38:39], |v163|, s6
	v_rcp_f32_e32 v186, v186
	v_rcp_f32_e32 v187, v187
	v_cndmask_b32_e64 v163, v163, v165, s[38:39]
	v_cndmask_b32_e32 v165, 0, v224, vcc
	v_sub_f32_e32 v163, v163, v165
	v_pk_fma_f32 v[186:187], v[194:195], v[186:187], v[132:133]
	v_max_f32_e32 v163, 0xc2700000, v163
	v_cmp_gt_f32_e32 vcc, s2, v186
	v_cvt_pk_bf16_f32 v197, v161, v163
	s_nop 0
	v_cndmask_b32_e64 v165, 0, 32, vcc
	v_ldexp_f32 v165, v186, v165
	v_log_f32_e32 v165, v165
	s_nop 0
	v_mul_f32_e32 v167, 0x3f317217, v165
	v_fma_f32 v167, v165, s3, -v167
	v_fmac_f32_e32 v167, 0x3377d1cf, v165
	v_fmac_f32_e32 v167, 0x3f317217, v165
	v_cmp_lt_f32_e64 s[38:39], |v165|, s6
	s_nop 1
	v_cndmask_b32_e64 v165, v165, v167, s[38:39]
	v_cndmask_b32_e32 v167, 0, v224, vcc
	v_cmp_gt_f32_e32 vcc, s2, v187
	v_sub_f32_e32 v165, v165, v167
	v_max_f32_e32 v165, 0xc2700000, v165
	v_cndmask_b32_e64 v167, 0, 32, vcc
	v_ldexp_f32 v167, v187, v167
	v_log_f32_e32 v167, v167
	s_nop 0
	v_mul_f32_e32 v186, 0x3f317217, v167
	v_fma_f32 v186, v167, s3, -v186
	v_fmac_f32_e32 v186, 0x3377d1cf, v167
	v_fmac_f32_e32 v186, 0x3f317217, v167
	v_cmp_lt_f32_e64 s[38:39], |v167|, s6
	s_nop 1
	v_cndmask_b32_e64 v167, v167, v186, s[38:39]
	v_cndmask_b32_e32 v186, 0, v224, vcc
	v_sub_f32_e32 v167, v167, v186
	v_max_f32_e32 v167, 0xc2700000, v167
	v_pk_mul_f32 v[186:187], v[150:151], v[166:167] op_sel_hi:[1,0]
	v_cvt_pk_bf16_f32 v198, v165, v167
	v_pk_mul_f32 v[168:169], v[168:169], v[186:187]
	s_nop 0
	v_pk_mul_f32 v[168:169], v[168:169], s[10:11] op_sel_hi:[1,0]
	s_nop 0
	v_exp_f32_e32 v168, v168
	v_exp_f32_e32 v169, v169
	s_nop 0
	v_pk_add_f32 v[168:169], v[168:169], 1.0 op_sel_hi:[1,0]
	s_nop 0
	v_rcp_f32_e32 v168, v168
	v_rcp_f32_e32 v169, v169
	s_nop 0
	v_pk_fma_f32 v[168:169], v[206:207], v[168:169], v[134:135]
	s_nop 0
	v_cmp_gt_f32_e32 vcc, s2, v168
	s_nop 1
	v_cndmask_b32_e64 v186, 0, 32, vcc
	v_ldexp_f32 v168, v168, v186
	v_log_f32_e32 v168, v168
	s_nop 0
	v_mul_f32_e32 v186, 0x3f317217, v168
	v_fma_f32 v186, v168, s3, -v186
	v_fmac_f32_e32 v186, 0x3377d1cf, v168
	v_fmac_f32_e32 v186, 0x3f317217, v168
	v_cmp_lt_f32_e64 s[38:39], |v168|, s6
	s_nop 1
	v_cndmask_b32_e64 v168, v168, v186, s[38:39]
	v_cndmask_b32_e32 v186, 0, v224, vcc
	v_cmp_gt_f32_e32 vcc, s2, v169
	v_sub_f32_e32 v168, v168, v186
	v_max_f32_e32 v168, 0xc2700000, v168
	v_cndmask_b32_e64 v186, 0, 32, vcc
	v_ldexp_f32 v169, v169, v186
	v_log_f32_e32 v169, v169
	s_nop 0
	v_mul_f32_e32 v186, 0x3f317217, v169
	v_fma_f32 v186, v169, s3, -v186
	v_fmac_f32_e32 v186, 0x3377d1cf, v169
	v_fmac_f32_e32 v186, 0x3f317217, v169
	v_cmp_lt_f32_e64 s[38:39], |v169|, s6
	s_nop 1
	v_cndmask_b32_e64 v169, v169, v186, s[38:39]
	v_cndmask_b32_e32 v186, 0, v224, vcc
	v_sub_f32_e32 v169, v169, v186
	v_max_f32_e32 v169, 0xc2700000, v169
	v_cvt_pk_bf16_f32 v199, v168, v169
	v_mad_i64_i32 v[168:169], s[0:1], v211, s81, v[204:205]
	v_lshl_add_u64 v[186:187], v[168:169], 0, v[152:153]
	ds_bpermute_b32 v168, v210, v208 offset:192
	global_store_dwordx4 v[186:187], v[196:199], off
	v_cvt_f32_i32_e32 v211, v69
	v_cvt_f32_i32_e32 v210, v68
	v_cvt_f32_i32_e32 v199, v73
	v_cvt_f32_i32_e32 v198, v72
	s_waitcnt lgkmcnt(0)
; __device__ __forceinline__ unsigned cvt_pk_bf16(float lo, float hi) { f32x2_t v = {lo, hi}; bf16x2_t b = __builtin_convertvector(v, bf16x2_t); return __builtin_bit_cast(unsigned, b); }
; __device__ __forceinline__ float fast_rcp(float x) { return __builtin_amdgcn_rcpf(x); }
;     template <int KIND>
;     __device__ __forceinline__ void run(const f32x4 (&acc)[2][2][4][2], const Unit& u, int wr, int wc, int fr, int fq) const {
;     ...
;             for (int ai = 0; ai < 2; ++ai)
; #pragma unroll
;                 for (int m = 0; m < 4; ++m) { const int row = row0 + ai * HALF + m * 16; const float a = __shfl(ai ? sa_hi : sa_lo, 16 * m + fr);
;                     const f32x4 f0 = __builtin_convertvector(__builtin_bit_cast(i32x4, acc[ai][bj][m][0]), f32x4), f1 = __builtin_convertvector(__builtin_bit_cast(i32x4, acc[ai][bj][m][1]), f32x4);
;                     f32x2_t v[4] = {(f32x2_t){f0[0], f0[1]}, (f32x2_t){f0[2], f0[3]}, (f32x2_t){f1[0], f1[1]}, (f32x2_t){f1[2], f1[3]}};
; #pragma unroll
;                     for (int j = 0; j < 4; ++j) {
;                         v[j] = v[j] * (sc2[j] * (f32x2_t){a, a});
;                         if (KIND == 0 || KIND == 1 || KIND == 3) {
;                             const f32x2_t e = v[j] * (f32x2_t){-LOG2E, -LOG2E};
;                             const f32x2_t dn = (f32x2_t){__builtin_amdgcn_exp2f(e[0]), __builtin_amdgcn_exp2f(e[1])} + (f32x2_t){1.0f, 1.0f};
;                             const f32x2_t sg = (f32x2_t){fast_rcp(dn[0]), fast_rcp(dn[1])};
;                             if (KIND == 0) v[j] = v[j] * sg;
;                             else if (KIND == 3) v[j] = (v[j] * sg) * aux2[j];
;                             else { const f32x2_t f = __builtin_elementwise_fma((f32x2_t){1.0f, 1.0f} - aux2[j], sg, aux2[j]);
;                                 v[j] = (f32x2_t){fmaxf(__logf(f[0]), -60.0f), fmaxf(__logf(f[1]), -60.0f)}; }
;                         }
;                     }
;                     u32x4 w; w.x = cvt_pk_bf16(v[0][0], v[0][1]); w.y = cvt_pk_bf16(v[1][0], v[1][1]); w.z = cvt_pk_bf16(v[2][0], v[2][1]); w.w = cvt_pk_bf16(v[3][0], v[3][1]);
;                     *(u32x4*)(O + (size_t)row * NPROJ + col0 + bj * HALF) = w; }
	v_pk_mul_f32 v[188:189], v[188:189], v[168:169] op_sel_hi:[1,0]
	v_cvt_f32_i32_e32 v197, v75
	v_cvt_f32_i32_e32 v196, v74
	v_pk_mul_f32 v[188:189], v[198:199], v[188:189]
	v_cvt_f32_i32_e32 v208, v70
	v_pk_mul_f32 v[188:189], v[188:189], s[10:11] op_sel_hi:[1,0]
	v_cvt_f32_i32_e32 v199, v55
	v_exp_f32_e32 v188, v188
	v_exp_f32_e32 v189, v189
	v_cvt_f32_i32_e32 v198, v54
	v_pk_add_f32 v[188:189], v[188:189], 1.0 op_sel_hi:[1,0]
	s_nop 0
	v_rcp_f32_e32 v188, v188
	v_rcp_f32_e32 v189, v189
	s_nop 0
	v_pk_fma_f32 v[136:137], v[190:191], v[188:189], v[136:137]
	s_nop 0
	v_cmp_gt_f32_e32 vcc, s2, v136
	s_nop 1
	v_cndmask_b32_e64 v157, 0, 32, vcc
	v_ldexp_f32 v136, v136, v157
	v_log_f32_e32 v136, v136
	s_nop 0
	v_mul_f32_e32 v157, 0x3f317217, v136
	v_fma_f32 v157, v136, s3, -v157
	v_fmac_f32_e32 v157, 0x3377d1cf, v136
	v_fmac_f32_e32 v157, 0x3f317217, v136
	v_cmp_lt_f32_e64 s[38:39], |v136|, s6
	s_nop 1
	v_cndmask_b32_e64 v136, v136, v157, s[38:39]
	v_cndmask_b32_e32 v157, 0, v224, vcc
	v_sub_f32_e32 v136, v136, v157
	v_cmp_gt_f32_e32 vcc, s2, v137
	v_max_f32_e32 v157, 0xc2700000, v136
	s_nop 0
	v_cndmask_b32_e64 v136, 0, 32, vcc
	v_ldexp_f32 v136, v137, v136
	v_log_f32_e32 v136, v136
	s_nop 0
	v_mul_f32_e32 v137, 0x3f317217, v136
	v_fma_f32 v137, v136, s3, -v137
	v_fmac_f32_e32 v137, 0x3377d1cf, v136
	v_fmac_f32_e32 v137, 0x3f317217, v136
	v_cmp_lt_f32_e64 s[38:39], |v136|, s6
	s_nop 1
	v_cndmask_b32_e64 v136, v136, v137, s[38:39]
	v_cndmask_b32_e32 v137, 0, v224, vcc
	v_sub_f32_e32 v136, v136, v137
	v_max_f32_e32 v159, 0xc2700000, v136
	v_pk_mul_f32 v[136:137], v[180:181], v[168:169] op_sel_hi:[1,0]
	v_cvt_f32_i32_e32 v181, v63
	v_pk_mul_f32 v[136:137], v[196:197], v[136:137]
	v_cvt_f32_i32_e32 v180, v62
	v_pk_mul_f32 v[136:137], v[136:137], s[10:11] op_sel_hi:[1,0]
	s_nop 0
	v_exp_f32_e32 v136, v136
	v_exp_f32_e32 v137, v137
	s_nop 0
	v_pk_add_f32 v[136:137], v[136:137], 1.0 op_sel_hi:[1,0]
	s_nop 0
	v_rcp_f32_e32 v136, v136
	v_rcp_f32_e32 v137, v137
	s_nop 0
	v_pk_fma_f32 v[136:137], v[192:193], v[136:137], v[138:139]
	s_nop 0
	v_cmp_gt_f32_e32 vcc, s2, v136
	s_nop 1
	v_cndmask_b32_e64 v138, 0, 32, vcc
	v_ldexp_f32 v136, v136, v138
	v_log_f32_e32 v136, v136
	s_nop 0
	v_mul_f32_e32 v138, 0x3f317217, v136
	v_fma_f32 v138, v136, s3, -v138
	v_fmac_f32_e32 v138, 0x3377d1cf, v136
	v_fmac_f32_e32 v138, 0x3f317217, v136
	v_cmp_lt_f32_e64 s[38:39], |v136|, s6
	s_nop 1
	v_cndmask_b32_e64 v136, v136, v138, s[38:39]
	v_cndmask_b32_e32 v138, 0, v224, vcc
	v_sub_f32_e32 v136, v136, v138
	v_cmp_gt_f32_e32 vcc, s2, v137
	v_max_f32_e32 v138, 0xc2700000, v136
	s_nop 0
	v_cndmask_b32_e64 v136, 0, 32, vcc
	v_ldexp_f32 v136, v137, v136
	v_log_f32_e32 v136, v136
	s_nop 0
	v_mul_f32_e32 v137, 0x3f317217, v136
	v_fma_f32 v137, v136, s3, -v137
	v_fmac_f32_e32 v137, 0x3377d1cf, v136
	v_fmac_f32_e32 v137, 0x3f317217, v136
	v_cmp_lt_f32_e64 s[38:39], |v136|, s6
	s_nop 1
	v_cndmask_b32_e64 v136, v136, v137, s[38:39]
	v_cndmask_b32_e32 v137, 0, v224, vcc
	v_sub_f32_e32 v136, v136, v137
	v_max_f32_e32 v139, 0xc2700000, v136
	v_pk_mul_f32 v[136:137], v[170:171], v[168:169] op_sel_hi:[1,0]
	s_nop 0
	v_pk_mul_f32 v[136:137], v[210:211], v[136:137]
	s_nop 0
	v_pk_mul_f32 v[136:137], v[136:137], s[10:11] op_sel_hi:[1,0]
	s_nop 0
	v_exp_f32_e32 v136, v136
	v_exp_f32_e32 v137, v137
	s_nop 0
	v_pk_add_f32 v[136:137], v[136:137], 1.0 op_sel_hi:[1,0]
	s_nop 0
	v_rcp_f32_e32 v136, v136
	v_rcp_f32_e32 v137, v137
	s_nop 0
	v_pk_fma_f32 v[132:133], v[194:195], v[136:137], v[132:133]
	s_nop 0
	v_cmp_gt_f32_e32 vcc, s2, v132
	s_nop 1
	v_cndmask_b32_e64 v136, 0, 32, vcc
	v_ldexp_f32 v132, v132, v136
	v_log_f32_e32 v132, v132
	s_nop 0
	v_mul_f32_e32 v136, 0x3f317217, v132
	v_fma_f32 v136, v132, s3, -v136
	v_fmac_f32_e32 v136, 0x3377d1cf, v132
	v_fmac_f32_e32 v136, 0x3f317217, v132
	v_cmp_lt_f32_e64 s[38:39], |v132|, s6
	s_nop 1
	v_cndmask_b32_e64 v132, v132, v136, s[38:39]
	v_cndmask_b32_e32 v136, 0, v224, vcc
	v_sub_f32_e32 v132, v132, v136
	v_cmp_gt_f32_e32 vcc, s2, v133
	v_max_f32_e32 v136, 0xc2700000, v132
	s_nop 0
	v_cndmask_b32_e64 v132, 0, 32, vcc
	v_ldexp_f32 v132, v133, v132
	v_log_f32_e32 v132, v132
	s_nop 0
	v_mul_f32_e32 v133, 0x3f317217, v132
	v_fma_f32 v133, v132, s3, -v133
	v_fmac_f32_e32 v133, 0x3377d1cf, v132
	v_fmac_f32_e32 v133, 0x3f317217, v132
	v_cmp_lt_f32_e64 s[38:39], |v132|, s6
	s_nop 1
	v_cndmask_b32_e64 v132, v132, v133, s[38:39]
	v_cndmask_b32_e32 v133, 0, v224, vcc
	v_sub_f32_e32 v132, v132, v133
	v_max_f32_e32 v137, 0xc2700000, v132
	v_pk_mul_f32 v[132:133], v[150:151], v[168:169] op_sel_hi:[1,0]
	s_nop 0
	v_pk_mul_f32 v[132:133], v[208:209], v[132:133]
	s_nop 0
	v_pk_mul_f32 v[132:133], v[132:133], s[10:11] op_sel_hi:[1,0]
	s_nop 0
	v_exp_f32_e32 v132, v132
	v_exp_f32_e32 v133, v133
	s_nop 0
	v_pk_add_f32 v[132:133], v[132:133], 1.0 op_sel_hi:[1,0]
	s_nop 0
	v_rcp_f32_e32 v132, v132
	v_rcp_f32_e32 v133, v133
	s_nop 0
	v_pk_fma_f32 v[132:133], v[206:207], v[132:133], v[134:135]
	s_nop 0
	v_cmp_gt_f32_e32 vcc, s2, v132
	s_nop 1
	v_cndmask_b32_e64 v134, 0, 32, vcc
	v_ldexp_f32 v132, v132, v134
	v_log_f32_e32 v132, v132
	s_nop 0
	v_mul_f32_e32 v134, 0x3f317217, v132
	v_fma_f32 v134, v132, s3, -v134
	v_fmac_f32_e32 v134, 0x3377d1cf, v132
	v_fmac_f32_e32 v134, 0x3f317217, v132
	v_cmp_lt_f32_e64 s[38:39], |v132|, s6
	s_nop 1
	v_cndmask_b32_e64 v132, v132, v134, s[38:39]
	v_cndmask_b32_e32 v134, 0, v224, vcc
	v_sub_f32_e32 v132, v132, v134
	v_cmp_gt_f32_e32 vcc, s2, v133
	v_max_f32_e32 v135, 0xc2700000, v132
	v_cvt_pk_bf16_f32 v134, v136, v137
	v_cndmask_b32_e64 v132, 0, 32, vcc
	v_ldexp_f32 v132, v133, v132
	v_log_f32_e32 v132, v132
	v_mad_i64_i32 v[136:137], s[0:1], v234, s81, v[204:205]
	v_lshl_add_u64 v[136:137], v[136:137], 0, v[152:153]
	v_mul_f32_e32 v133, 0x3f317217, v132
	v_fma_f32 v133, v132, s3, -v133
	v_fmac_f32_e32 v133, 0x3377d1cf, v132
	v_fmac_f32_e32 v133, 0x3f317217, v132
	v_cmp_lt_f32_e64 s[38:39], |v132|, s6
	s_nop 1
	v_cndmask_b32_e64 v132, v132, v133, s[38:39]
	v_cndmask_b32_e32 v133, 0, v224, vcc
	v_sub_f32_e32 v132, v132, v133
	v_max_f32_e32 v150, 0xc2700000, v132
	v_cvt_pk_bf16_f32 v132, v157, v159
	v_cvt_pk_bf16_f32 v133, v138, v139
	v_cvt_pk_bf16_f32 v135, v135, v150
	global_store_dwordx4 v[136:137], v[132:135], off
	s_waitcnt vmcnt(8)
;     template <int KIND>
;     __device__ __forceinline__ void run(const f32x4 (&acc)[2][2][4][2], const Unit& u, int wr, int wc, int fr, int fq) const {
;     ...
;         for (int bj = 0; bj < 2; ++bj) {
;             f32x2_t sc2[4], aux2[4];
; #pragma unroll
;             for (int j = 0; j < 4; ++j) {
;                 const float k0 = (KIND == 4) ? (0.125f * LOG2E / 127.0f) : (1.0f / 127.0f);
;                 sc2[j] = (f32x2_t){wmax[col0 + bj * HALF + 2 * j] * k0, wmax[col0 + bj * HALF + 2 * j + 1] * k0};
;                 if (KIND == 1) aux2[j] = (f32x2_t){lb[col0 - C_HG + bj * HALF + 2 * j], lb[col0 - C_HG + bj * HALF + 2 * j + 1]};
;                 else if (KIND == 3) aux2[j] = (f32x2_t){gain[col0 - C_HGATE + bj * HALF + 2 * j], gain[col0 - C_HGATE + bj * HALF + 2 * j + 1]};
;                 else aux2[j] = (f32x2_t){0.f, 0.f};
;             }
; #pragma unroll
;             for (int ai = 0; ai < 2; ++ai)
; #pragma unroll
;                 for (int m = 0; m < 4; ++m) { const int row = row0 + ai * HALF + m * 16; const float a = __shfl(ai ? sa_hi : sa_lo, 16 * m + fr);
;                     const f32x4 f0 = __builtin_convertvector(__builtin_bit_cast(i32x4, acc[ai][bj][m][0]), f32x4), f1 = __builtin_convertvector(__builtin_bit_cast(i32x4, acc[ai][bj][m][1]), f32x4);
;                     f32x2_t v[4] = {(f32x2_t){f0[0], f0[1]}, (f32x2_t){f0[2], f0[3]}, (f32x2_t){f1[0], f1[1]}, (f32x2_t){f1[2], f1[3]}};
; #pragma unroll
;                     for (int j = 0; j < 4; ++j) {
;                         v[j] = v[j] * (sc2[j] * (f32x2_t){a, a});
;                         if (KIND == 0 || KIND == 1 || KIND == 3) {
;                             const f32x2_t e = v[j] * (f32x2_t){-LOG2E, -LOG2E};
;                             const f32x2_t dn = (f32x2_t){__builtin_amdgcn_exp2f(e[0]), __builtin_amdgcn_exp2f(e[1])} + (f32x2_t){1.0f, 1.0f};
;                             const f32x2_t sg = (f32x2_t){fast_rcp(dn[0]), fast_rcp(dn[1])};
;                             if (KIND == 0) v[j] = v[j] * sg;
;                             else if (KIND == 3) v[j] = (v[j] * sg) * aux2[j];
;                             else { const f32x2_t f = __builtin_elementwise_fma((f32x2_t){1.0f, 1.0f} - aux2[j], sg, aux2[j]);
;                                 v[j] = (f32x2_t){fmaxf(__logf(f[0]), -60.0f), fmaxf(__logf(f[1]), -60.0f)}; }
	s_nop 0
	v_mov_b32_e32 v188, v236
	v_mov_b32_e32 v189, v237
	v_mov_b32_e32 v190, v238
	v_mov_b32_e32 v191, v239
	v_mov_b32_e32 v192, v240
	v_mov_b32_e32 v193, v241
	v_mov_b32_e32 v194, v242
	v_mov_b32_e32 v195, v243
	v_mov_b32_e32 v132, v128
	v_mov_b32_e32 v133, v129
	v_mov_b32_e32 v134, v130
	v_mov_b32_e32 v135, v131
	v_mov_b32_e32 v136, v244
	v_mov_b32_e32 v137, v245
	v_mov_b32_e32 v138, v246
	v_mov_b32_e32 v139, v247
	v_mad_i64_i32 v[150:151], s[0:1], v234, s81, 0
	v_pk_mul_f32 v[152:153], v[188:189], s[8:9] op_sel_hi:[1,0]
	v_pk_mul_f32 v[170:171], v[192:193], s[8:9] op_sel_hi:[1,0]
	v_pk_mul_f32 v[154:155], v[194:195], s[8:9] op_sel_hi:[1,0]
	v_pk_mul_f32 v[194:195], v[66:67], v[170:171] op_sel_hi:[0,1]
	v_pk_mul_f32 v[180:181], v[180:181], v[194:195]
	v_cvt_f32_i32_e32 v189, v65
	v_pk_mul_f32 v[180:181], v[180:181], s[10:11] op_sel_hi:[1,0]
	v_cvt_f32_i32_e32 v188, v64
	v_exp_f32_e32 v180, v180
	v_exp_f32_e32 v181, v181
	v_pk_mul_f32 v[148:149], v[190:191], s[8:9] op_sel_hi:[1,0]
	v_cvt_f32_i32_e32 v191, v59
	v_cvt_f32_i32_e32 v190, v58
	v_pk_add_f32 v[180:181], v[180:181], 1.0 op_sel_hi:[1,0]
	v_cvt_f32_i32_e32 v193, v61
	v_rcp_f32_e32 v194, v180
	v_rcp_f32_e32 v195, v181
	v_pk_add_f32 v[180:181], v[136:137], 1.0 op_sel_hi:[1,0] neg_lo:[1,0] neg_hi:[1,0]
	v_cvt_f32_i32_e32 v192, v60
	v_pk_fma_f32 v[194:195], v[180:181], v[194:195], v[136:137]
	s_nop 0
	v_cmp_gt_f32_e32 vcc, s2, v194
	s_nop 1
	v_cndmask_b32_e64 v157, 0, 32, vcc
	v_ldexp_f32 v157, v194, v157
	v_log_f32_e32 v157, v157
	s_nop 0
	v_mul_f32_e32 v159, 0x3f317217, v157
	v_fma_f32 v159, v157, s3, -v159
	v_fmac_f32_e32 v159, 0x3377d1cf, v157
	v_fmac_f32_e32 v159, 0x3f317217, v157
	v_cmp_lt_f32_e64 s[38:39], |v157|, s6
	s_nop 1
	v_cndmask_b32_e64 v157, v157, v159, s[38:39]
	v_cndmask_b32_e32 v159, 0, v224, vcc
	v_cmp_gt_f32_e32 vcc, s2, v195
	v_sub_f32_e32 v157, v157, v159
	v_max_f32_e32 v157, 0xc2700000, v157
	v_cndmask_b32_e64 v159, 0, 32, vcc
	v_ldexp_f32 v159, v195, v159
	v_pk_mul_f32 v[194:195], v[66:67], v[154:155] op_sel_hi:[0,1]
	v_pk_mul_f32 v[188:189], v[188:189], v[194:195]
	v_log_f32_e32 v159, v159
	v_pk_mul_f32 v[188:189], v[188:189], s[10:11] op_sel_hi:[1,0]
	v_pk_mul_f32 v[200:201], v[156:157], v[170:171] op_sel_hi:[0,1]
	v_exp_f32_e32 v188, v188
	v_exp_f32_e32 v189, v189
	v_mul_f32_e32 v161, 0x3f317217, v159
	v_fma_f32 v161, v159, s3, -v161
	v_fmac_f32_e32 v161, 0x3377d1cf, v159
	v_pk_add_f32 v[188:189], v[188:189], 1.0 op_sel_hi:[1,0]
	v_fmac_f32_e32 v161, 0x3f317217, v159
	v_rcp_f32_e32 v194, v188
	v_rcp_f32_e32 v195, v189
	v_pk_add_f32 v[188:189], v[138:139], 1.0 op_sel_hi:[1,0] neg_lo:[1,0] neg_hi:[1,0]
	v_cmp_lt_f32_e64 s[38:39], |v159|, s6
	v_pk_mul_f32 v[198:199], v[198:199], v[200:201]
	v_pk_fma_f32 v[194:195], v[188:189], v[194:195], v[138:139]
	v_cndmask_b32_e64 v159, v159, v161, s[38:39]
	v_cndmask_b32_e32 v161, 0, v224, vcc
	v_cmp_gt_f32_e32 vcc, s2, v194
	v_sub_f32_e32 v159, v159, v161
	v_pk_mul_f32 v[198:199], v[198:199], s[10:11] op_sel_hi:[1,0]
	v_cndmask_b32_e64 v161, 0, 32, vcc
	v_ldexp_f32 v161, v194, v161
	v_log_f32_e32 v161, v161
	v_exp_f32_e32 v198, v198
	v_exp_f32_e32 v199, v199
	v_max_f32_e32 v159, 0xc2700000, v159
	v_mul_f32_e32 v163, 0x3f317217, v161
	v_fma_f32 v163, v161, s3, -v163
	v_fmac_f32_e32 v163, 0x3377d1cf, v161
	v_fmac_f32_e32 v163, 0x3f317217, v161
	v_cmp_lt_f32_e64 s[38:39], |v161|, s6
	v_pk_add_f32 v[198:199], v[198:199], 1.0 op_sel_hi:[1,0]
	s_nop 0
	v_cndmask_b32_e64 v161, v161, v163, s[38:39]
	v_cndmask_b32_e32 v163, 0, v224, vcc
	v_cmp_gt_f32_e32 vcc, s2, v195
	v_sub_f32_e32 v161, v161, v163
	v_rcp_f32_e32 v198, v198
	v_cndmask_b32_e64 v163, 0, 32, vcc
	v_ldexp_f32 v163, v195, v163
	v_pk_mul_f32 v[194:195], v[66:67], v[152:153] op_sel_hi:[0,1]
	v_pk_mul_f32 v[190:191], v[190:191], v[194:195]
	v_log_f32_e32 v163, v163
	v_pk_mul_f32 v[190:191], v[190:191], s[10:11] op_sel_hi:[1,0]
	v_rcp_f32_e32 v199, v199
	v_exp_f32_e32 v190, v190
	v_exp_f32_e32 v191, v191
	v_mul_f32_e32 v165, 0x3f317217, v163
	v_fma_f32 v165, v163, s3, -v165
	v_fmac_f32_e32 v165, 0x3377d1cf, v163
	v_pk_add_f32 v[190:191], v[190:191], 1.0 op_sel_hi:[1,0]
	v_fmac_f32_e32 v165, 0x3f317217, v163
	v_rcp_f32_e32 v194, v190
	v_rcp_f32_e32 v195, v191
	v_pk_add_f32 v[190:191], v[132:133], 1.0 op_sel_hi:[1,0] neg_lo:[1,0] neg_hi:[1,0]
	v_cmp_lt_f32_e64 s[38:39], |v163|, s6
	v_pk_fma_f32 v[198:199], v[180:181], v[198:199], v[136:137]
	v_pk_fma_f32 v[194:195], v[190:191], v[194:195], v[132:133]
	v_cndmask_b32_e64 v163, v163, v165, s[38:39]
	v_cndmask_b32_e32 v165, 0, v224, vcc
	v_cmp_gt_f32_e32 vcc, s2, v194
	v_sub_f32_e32 v163, v163, v165
	v_max_f32_e32 v161, 0xc2700000, v161
	v_cndmask_b32_e64 v165, 0, 32, vcc
	v_ldexp_f32 v165, v194, v165
	v_log_f32_e32 v165, v165
	v_max_f32_e32 v163, 0xc2700000, v163
	v_mul_f32_e32 v167, 0x3f317217, v165
	v_fma_f32 v167, v165, s3, -v167
	v_fmac_f32_e32 v167, 0x3377d1cf, v165
	v_fmac_f32_e32 v167, 0x3f317217, v165
	v_cmp_lt_f32_e64 s[38:39], |v165|, s6
	s_nop 1
	v_cndmask_b32_e64 v165, v165, v167, s[38:39]
	v_cndmask_b32_e32 v167, 0, v224, vcc
	v_cmp_gt_f32_e32 vcc, s2, v195
	v_sub_f32_e32 v165, v165, v167
	v_max_f32_e32 v165, 0xc2700000, v165
	v_cndmask_b32_e64 v167, 0, 32, vcc
	v_ldexp_f32 v167, v195, v167
	v_pk_mul_f32 v[194:195], v[66:67], v[148:149] op_sel_hi:[0,1]
	v_pk_mul_f32 v[192:193], v[192:193], v[194:195]
	v_log_f32_e32 v167, v167
	v_pk_mul_f32 v[192:193], v[192:193], s[10:11] op_sel_hi:[1,0]
	v_mul_f32_e32 v169, 0x3f317217, v167
	v_exp_f32_e32 v192, v192
	v_exp_f32_e32 v193, v193
	v_fma_f32 v169, v167, s3, -v169
	v_fmac_f32_e32 v169, 0x3377d1cf, v167
	v_fmac_f32_e32 v169, 0x3f317217, v167
; __device__ __forceinline__ unsigned cvt_pk_bf16(float lo, float hi) { f32x2_t v = {lo, hi}; bf16x2_t b = __builtin_convertvector(v, bf16x2_t); return __builtin_bit_cast(unsigned, b); }
; __device__ __forceinline__ float fast_rcp(float x) { return __builtin_amdgcn_rcpf(x); }
;     template <int KIND>
;     __device__ __forceinline__ void run(const f32x4 (&acc)[2][2][4][2], const Unit& u, int wr, int wc, int fr, int fq) const {
;     ...
;             for (int ai = 0; ai < 2; ++ai)
; #pragma unroll
;                 for (int m = 0; m < 4; ++m) { const int row = row0 + ai * HALF + m * 16; const float a = __shfl(ai ? sa_hi : sa_lo, 16 * m + fr);
;                     const f32x4 f0 = __builtin_convertvector(__builtin_bit_cast(i32x4, acc[ai][bj][m][0]), f32x4), f1 = __builtin_convertvector(__builtin_bit_cast(i32x4, acc[ai][bj][m][1]), f32x4);
;                     f32x2_t v[4] = {(f32x2_t){f0[0], f0[1]}, (f32x2_t){f0[2], f0[3]}, (f32x2_t){f1[0], f1[1]}, (f32x2_t){f1[2], f1[3]}};
; #pragma unroll
;                     for (int j = 0; j < 4; ++j) {
;                         v[j] = v[j] * (sc2[j] * (f32x2_t){a, a});
;                         if (KIND == 0 || KIND == 1 || KIND == 3) {
;                             const f32x2_t e = v[j] * (f32x2_t){-LOG2E, -LOG2E};
;                             const f32x2_t dn = (f32x2_t){__builtin_amdgcn_exp2f(e[0]), __builtin_amdgcn_exp2f(e[1])} + (f32x2_t){1.0f, 1.0f};
;                             const f32x2_t sg = (f32x2_t){fast_rcp(dn[0]), fast_rcp(dn[1])};
;                             if (KIND == 0) v[j] = v[j] * sg;
;                             else if (KIND == 3) v[j] = (v[j] * sg) * aux2[j];
;                             else { const f32x2_t f = __builtin_elementwise_fma((f32x2_t){1.0f, 1.0f} - aux2[j], sg, aux2[j]);
;                                 v[j] = (f32x2_t){fmaxf(__logf(f[0]), -60.0f), fmaxf(__logf(f[1]), -60.0f)}; }
;                         }
;                     }
;                     u32x4 w; w.x = cvt_pk_bf16(v[0][0], v[0][1]); w.y = cvt_pk_bf16(v[1][0], v[1][1]); w.z = cvt_pk_bf16(v[2][0], v[2][1]); w.w = cvt_pk_bf16(v[3][0], v[3][1]);
;                     *(u32x4*)(O + (size_t)row * NPROJ + col0 + bj * HALF) = w; }
	v_pk_add_f32 v[192:193], v[192:193], 1.0 op_sel_hi:[1,0]
	v_cmp_lt_f32_e64 s[38:39], |v167|, s6
	v_rcp_f32_e32 v194, v192
	v_rcp_f32_e32 v195, v193
	v_pk_add_f32 v[192:193], v[134:135], 1.0 op_sel_hi:[1,0] neg_lo:[1,0] neg_hi:[1,0]
	v_cndmask_b32_e64 v167, v167, v169, s[38:39]
	v_cndmask_b32_e32 v169, 0, v224, vcc
	v_pk_fma_f32 v[194:195], v[192:193], v[194:195], v[134:135]
	v_sub_f32_e32 v167, v167, v169
	v_cmp_gt_f32_e32 vcc, s2, v194
	v_max_f32_e32 v167, 0xc2700000, v167
	v_cvt_pk_bf16_f32 v196, v165, v167
	v_cndmask_b32_e64 v66, 0, 32, vcc
	v_ldexp_f32 v66, v194, v66
	v_log_f32_e32 v66, v66
	s_nop 0
	v_mul_f32_e32 v169, 0x3f317217, v66
	v_fma_f32 v169, v66, s3, -v169
	v_fmac_f32_e32 v169, 0x3377d1cf, v66
	v_fmac_f32_e32 v169, 0x3f317217, v66
	v_cmp_lt_f32_e64 s[38:39], |v66|, s6
	s_nop 1
	v_cndmask_b32_e64 v66, v66, v169, s[38:39]
	v_cndmask_b32_e32 v169, 0, v224, vcc
	v_cmp_gt_f32_e32 vcc, s2, v195
	v_sub_f32_e32 v66, v66, v169
	v_max_f32_e32 v66, 0xc2700000, v66
	v_cndmask_b32_e64 v169, 0, 32, vcc
	v_ldexp_f32 v169, v195, v169
	v_log_f32_e32 v169, v169
	v_cvt_pk_bf16_f32 v195, v161, v163
	v_mul_f32_e32 v194, 0x3f317217, v169
	v_fma_f32 v194, v169, s3, -v194
	v_fmac_f32_e32 v194, 0x3377d1cf, v169
	v_fmac_f32_e32 v194, 0x3f317217, v169
	v_cmp_lt_f32_e64 s[38:39], |v169|, s6
	s_nop 1
	v_cndmask_b32_e64 v169, v169, v194, s[38:39]
	v_cndmask_b32_e32 v194, 0, v224, vcc
	v_sub_f32_e32 v169, v169, v194
	v_max_f32_e32 v169, 0xc2700000, v169
	v_cmp_gt_f32_e32 vcc, s2, v198
	v_cvt_pk_bf16_f32 v197, v66, v169
	v_cvt_pk_bf16_f32 v194, v157, v159
	v_cndmask_b32_e64 v66, 0, 32, vcc
	v_ldexp_f32 v66, v198, v66
	v_log_f32_e32 v66, v66
	global_store_dwordx4 v[172:173], v[194:197], off offset:256
	v_cvt_f32_i32_e32 v173, v53
	v_cvt_f32_i32_e32 v172, v52
	v_mul_f32_e32 v157, 0x3f317217, v66
	v_fma_f32 v157, v66, s3, -v157
	v_fmac_f32_e32 v157, 0x3377d1cf, v66
	v_fmac_f32_e32 v157, 0x3f317217, v66
	v_cmp_lt_f32_e64 s[38:39], |v66|, s6
	v_cvt_f32_i32_e32 v197, v57
	v_cvt_f32_i32_e32 v196, v56
	v_cndmask_b32_e64 v66, v66, v157, s[38:39]
	v_cndmask_b32_e32 v157, 0, v224, vcc
	v_cmp_gt_f32_e32 vcc, s2, v199
	v_sub_f32_e32 v66, v66, v157
	v_cvt_f32_i32_e32 v195, v51
	v_cndmask_b32_e64 v157, 0, 32, vcc
	v_ldexp_f32 v157, v199, v157
	v_log_f32_e32 v157, v157
	v_cvt_f32_i32_e32 v194, v50
	v_max_f32_e32 v66, 0xc2700000, v66
	v_mul_f32_e32 v159, 0x3f317217, v157
	v_fma_f32 v159, v157, s3, -v159
	v_fmac_f32_e32 v159, 0x3377d1cf, v157
	v_fmac_f32_e32 v159, 0x3f317217, v157
	v_cmp_lt_f32_e64 s[38:39], |v157|, s6
	s_nop 1
	v_cndmask_b32_e64 v157, v157, v159, s[38:39]
	v_cndmask_b32_e32 v159, 0, v224, vcc
	v_sub_f32_e32 v157, v157, v159
	v_pk_mul_f32 v[198:199], v[156:157], v[154:155] op_sel_hi:[0,1]
	v_pk_mul_f32 v[196:197], v[196:197], v[198:199]
	v_max_f32_e32 v159, 0xc2700000, v157
	v_pk_mul_f32 v[196:197], v[196:197], s[10:11] op_sel_hi:[1,0]
	s_nop 0
	v_exp_f32_e32 v196, v196
	v_exp_f32_e32 v197, v197
	s_nop 0
	v_pk_add_f32 v[196:197], v[196:197], 1.0 op_sel_hi:[1,0]
	s_nop 0
	v_rcp_f32_e32 v196, v196
	v_rcp_f32_e32 v197, v197
	s_nop 0
	v_pk_fma_f32 v[196:197], v[188:189], v[196:197], v[138:139]
	s_nop 0
	v_cmp_gt_f32_e32 vcc, s2, v196
	s_nop 1
	v_cndmask_b32_e64 v157, 0, 32, vcc
	v_ldexp_f32 v157, v196, v157
	v_log_f32_e32 v157, v157
	s_nop 0
	v_mul_f32_e32 v161, 0x3f317217, v157
	v_fma_f32 v161, v157, s3, -v161
	v_fmac_f32_e32 v161, 0x3377d1cf, v157
	v_fmac_f32_e32 v161, 0x3f317217, v157
	v_cmp_lt_f32_e64 s[38:39], |v157|, s6
	s_nop 1
	v_cndmask_b32_e64 v157, v157, v161, s[38:39]
	v_cndmask_b32_e32 v161, 0, v224, vcc
	v_sub_f32_e32 v157, v157, v161
	v_cmp_gt_f32_e32 vcc, s2, v197
	v_max_f32_e32 v161, 0xc2700000, v157
	s_nop 0
	v_cndmask_b32_e64 v157, 0, 32, vcc
	v_ldexp_f32 v157, v197, v157
	v_log_f32_e32 v157, v157
	s_nop 0
	v_mul_f32_e32 v163, 0x3f317217, v157
	v_fma_f32 v163, v157, s3, -v163
	v_fmac_f32_e32 v163, 0x3377d1cf, v157
	v_fmac_f32_e32 v163, 0x3f317217, v157
	v_cmp_lt_f32_e64 s[38:39], |v157|, s6
	s_nop 1
	v_cndmask_b32_e64 v157, v157, v163, s[38:39]
	v_cndmask_b32_e32 v163, 0, v224, vcc
	v_sub_f32_e32 v157, v157, v163
	v_pk_mul_f32 v[196:197], v[156:157], v[152:153] op_sel_hi:[0,1]
	v_pk_mul_f32 v[194:195], v[194:195], v[196:197]
	v_max_f32_e32 v163, 0xc2700000, v157
	v_pk_mul_f32 v[194:195], v[194:195], s[10:11] op_sel_hi:[1,0]
	s_nop 0
	v_exp_f32_e32 v194, v194
	v_exp_f32_e32 v195, v195
	s_nop 0
	v_pk_add_f32 v[194:195], v[194:195], 1.0 op_sel_hi:[1,0]
	s_nop 0
	v_rcp_f32_e32 v194, v194
	v_rcp_f32_e32 v195, v195
	s_nop 0
	v_pk_fma_f32 v[194:195], v[190:191], v[194:195], v[132:133]
	s_nop 0
	v_cmp_gt_f32_e32 vcc, s2, v194
	s_nop 1
	v_cndmask_b32_e64 v157, 0, 32, vcc
	v_ldexp_f32 v157, v194, v157
	v_log_f32_e32 v157, v157
	v_cvt_pk_bf16_f32 v194, v66, v159
	v_mul_f32_e32 v165, 0x3f317217, v157
	v_fma_f32 v165, v157, s3, -v165
	v_fmac_f32_e32 v165, 0x3377d1cf, v157
	v_fmac_f32_e32 v165, 0x3f317217, v157
	v_cmp_lt_f32_e64 s[38:39], |v157|, s6
	s_nop 1
	v_cndmask_b32_e64 v157, v157, v165, s[38:39]
	v_cndmask_b32_e32 v165, 0, v224, vcc
	v_sub_f32_e32 v157, v157, v165
	v_cmp_gt_f32_e32 vcc, s2, v195
	v_max_f32_e32 v165, 0xc2700000, v157
	s_nop 0
	v_cndmask_b32_e64 v157, 0, 32, vcc
	v_ldexp_f32 v157, v195, v157
	v_log_f32_e32 v157, v157
	v_cvt_pk_bf16_f32 v195, v161, v163
	v_mul_f32_e32 v167, 0x3f317217, v157
	v_fma_f32 v167, v157, s3, -v167
	v_fmac_f32_e32 v167, 0x3377d1cf, v157
	v_fmac_f32_e32 v167, 0x3f317217, v157
	v_cmp_lt_f32_e64 s[38:39], |v157|, s6
	s_nop 1
	v_cndmask_b32_e64 v157, v157, v167, s[38:39]
	v_cndmask_b32_e32 v167, 0, v224, vcc
	v_sub_f32_e32 v157, v157, v167
	v_max_f32_e32 v167, 0xc2700000, v157
; __device__ __forceinline__ unsigned cvt_pk_bf16(float lo, float hi) { f32x2_t v = {lo, hi}; bf16x2_t b = __builtin_convertvector(v, bf16x2_t); return __builtin_bit_cast(unsigned, b); }
; __device__ __forceinline__ float fast_rcp(float x) { return __builtin_amdgcn_rcpf(x); }
;     template <int KIND>
;     __device__ __forceinline__ void run(const f32x4 (&acc)[2][2][4][2], const Unit& u, int wr, int wc, int fr, int fq) const {
;     ...
;             for (int ai = 0; ai < 2; ++ai)
; #pragma unroll
;                 for (int m = 0; m < 4; ++m) { const int row = row0 + ai * HALF + m * 16; const float a = __shfl(ai ? sa_hi : sa_lo, 16 * m + fr);
;                     const f32x4 f0 = __builtin_convertvector(__builtin_bit_cast(i32x4, acc[ai][bj][m][0]), f32x4), f1 = __builtin_convertvector(__builtin_bit_cast(i32x4, acc[ai][bj][m][1]), f32x4);
;                     f32x2_t v[4] = {(f32x2_t){f0[0], f0[1]}, (f32x2_t){f0[2], f0[3]}, (f32x2_t){f1[0], f1[1]}, (f32x2_t){f1[2], f1[3]}};
; #pragma unroll
;                     for (int j = 0; j < 4; ++j) {
;                         v[j] = v[j] * (sc2[j] * (f32x2_t){a, a});
;                         if (KIND == 0 || KIND == 1 || KIND == 3) {
;                             const f32x2_t e = v[j] * (f32x2_t){-LOG2E, -LOG2E};
;                             const f32x2_t dn = (f32x2_t){__builtin_amdgcn_exp2f(e[0]), __builtin_amdgcn_exp2f(e[1])} + (f32x2_t){1.0f, 1.0f};
;                             const f32x2_t sg = (f32x2_t){fast_rcp(dn[0]), fast_rcp(dn[1])};
;                             if (KIND == 0) v[j] = v[j] * sg;
;                             else if (KIND == 3) v[j] = (v[j] * sg) * aux2[j];
;                             else { const f32x2_t f = __builtin_elementwise_fma((f32x2_t){1.0f, 1.0f} - aux2[j], sg, aux2[j]);
;                                 v[j] = (f32x2_t){fmaxf(__logf(f[0]), -60.0f), fmaxf(__logf(f[1]), -60.0f)}; }
;                         }
;                     }
;                     u32x4 w; w.x = cvt_pk_bf16(v[0][0], v[0][1]); w.y = cvt_pk_bf16(v[1][0], v[1][1]); w.z = cvt_pk_bf16(v[2][0], v[2][1]); w.w = cvt_pk_bf16(v[3][0], v[3][1]);
;                     *(u32x4*)(O + (size_t)row * NPROJ + col0 + bj * HALF) = w; }
	v_pk_mul_f32 v[156:157], v[156:157], v[148:149] op_sel_hi:[0,1]
	v_pk_mul_f32 v[156:157], v[172:173], v[156:157]
	v_cvt_pk_bf16_f32 v196, v165, v167
	v_pk_mul_f32 v[156:157], v[156:157], s[10:11] op_sel_hi:[1,0]
	v_cvt_f32_i32_e32 v173, v43
	v_exp_f32_e32 v156, v156
	v_exp_f32_e32 v157, v157
	v_cvt_f32_i32_e32 v172, v42
	v_pk_add_f32 v[156:157], v[156:157], 1.0 op_sel_hi:[1,0]
	s_nop 0
	v_rcp_f32_e32 v156, v156
	v_rcp_f32_e32 v157, v157
	s_nop 0
	v_pk_fma_f32 v[156:157], v[192:193], v[156:157], v[134:135]
	s_nop 0
	v_cmp_gt_f32_e32 vcc, s2, v156
	s_nop 1
	v_cndmask_b32_e64 v169, 0, 32, vcc
	v_ldexp_f32 v156, v156, v169
	v_log_f32_e32 v156, v156
	s_nop 0
	v_mul_f32_e32 v169, 0x3f317217, v156
	v_fma_f32 v169, v156, s3, -v169
	v_fmac_f32_e32 v169, 0x3377d1cf, v156
	v_fmac_f32_e32 v169, 0x3f317217, v156
	v_cmp_lt_f32_e64 s[38:39], |v156|, s6
	s_nop 1
	v_cndmask_b32_e64 v156, v156, v169, s[38:39]
	v_cndmask_b32_e32 v169, 0, v224, vcc
	v_cmp_gt_f32_e32 vcc, s2, v157
	v_sub_f32_e32 v156, v156, v169
	v_max_f32_e32 v156, 0xc2700000, v156
	v_cndmask_b32_e64 v169, 0, 32, vcc
	v_ldexp_f32 v157, v157, v169
	v_log_f32_e32 v157, v157
	s_nop 0
	v_mul_f32_e32 v169, 0x3f317217, v157
	v_fma_f32 v169, v157, s3, -v169
	v_fmac_f32_e32 v169, 0x3377d1cf, v157
	v_fmac_f32_e32 v169, 0x3f317217, v157
	v_cmp_lt_f32_e64 s[38:39], |v157|, s6
	s_nop 1
	v_cndmask_b32_e64 v157, v157, v169, s[38:39]
	v_cndmask_b32_e32 v169, 0, v224, vcc
	v_sub_f32_e32 v157, v157, v169
	v_max_f32_e32 v157, 0xc2700000, v157
	v_cvt_pk_bf16_f32 v197, v156, v157
	global_store_dwordx4 v[174:175], v[194:197], off offset:256
	v_cvt_f32_i32_e32 v175, v49
	v_cvt_f32_i32_e32 v174, v48
	v_cvt_f32_i32_e32 v195, v47
	v_cvt_f32_i32_e32 v194, v46
	v_pk_mul_f32 v[196:197], v[158:159], v[170:171] op_sel_hi:[0,1]
	v_cvt_f32_i32_e32 v157, v45
	v_cvt_f32_i32_e32 v156, v44
	v_pk_mul_f32 v[194:195], v[194:195], v[196:197]
	s_nop 0
	v_pk_mul_f32 v[194:195], v[194:195], s[10:11] op_sel_hi:[1,0]
	s_nop 0
	v_exp_f32_e32 v194, v194
	v_exp_f32_e32 v195, v195
	s_nop 0
	v_pk_add_f32 v[194:195], v[194:195], 1.0 op_sel_hi:[1,0]
	s_nop 0
	v_rcp_f32_e32 v194, v194
	v_rcp_f32_e32 v195, v195
	s_nop 0
	v_pk_fma_f32 v[194:195], v[180:181], v[194:195], v[136:137]
	s_nop 0
	v_cmp_gt_f32_e32 vcc, s2, v194
	s_nop 1
	v_cndmask_b32_e64 v66, 0, 32, vcc
	v_ldexp_f32 v66, v194, v66
	v_log_f32_e32 v66, v66
	s_nop 0
	v_mul_f32_e32 v159, 0x3f317217, v66
	v_fma_f32 v159, v66, s3, -v159
	v_fmac_f32_e32 v159, 0x3377d1cf, v66
	v_fmac_f32_e32 v159, 0x3f317217, v66
	v_cmp_lt_f32_e64 s[38:39], |v66|, s6
	s_nop 1
	v_cndmask_b32_e64 v66, v66, v159, s[38:39]
	v_cndmask_b32_e32 v159, 0, v224, vcc
	v_cmp_gt_f32_e32 vcc, s2, v195
	v_sub_f32_e32 v66, v66, v159
	v_max_f32_e32 v66, 0xc2700000, v66
	v_cndmask_b32_e64 v159, 0, 32, vcc
	v_ldexp_f32 v159, v195, v159
	v_log_f32_e32 v159, v159
	s_nop 0
	v_mul_f32_e32 v161, 0x3f317217, v159
	v_fma_f32 v161, v159, s3, -v161
	v_fmac_f32_e32 v161, 0x3377d1cf, v159
	v_fmac_f32_e32 v161, 0x3f317217, v159
	v_cmp_lt_f32_e64 s[38:39], |v159|, s6
	s_nop 1
	v_cndmask_b32_e64 v159, v159, v161, s[38:39]
	v_cndmask_b32_e32 v161, 0, v224, vcc
	v_sub_f32_e32 v159, v159, v161
	v_pk_mul_f32 v[194:195], v[158:159], v[154:155] op_sel_hi:[0,1]
	v_pk_mul_f32 v[174:175], v[174:175], v[194:195]
	v_max_f32_e32 v161, 0xc2700000, v159
	v_pk_mul_f32 v[174:175], v[174:175], s[10:11] op_sel_hi:[1,0]
	s_nop 0
	v_exp_f32_e32 v174, v174
	v_exp_f32_e32 v175, v175
	s_nop 0
	v_pk_add_f32 v[174:175], v[174:175], 1.0 op_sel_hi:[1,0]
	s_nop 0
	v_rcp_f32_e32 v174, v174
	v_rcp_f32_e32 v175, v175
	s_nop 0
	v_pk_fma_f32 v[174:175], v[188:189], v[174:175], v[138:139]
	s_nop 0
	v_cmp_gt_f32_e32 vcc, s2, v174
	s_nop 1
	v_cndmask_b32_e64 v159, 0, 32, vcc
	v_ldexp_f32 v159, v174, v159
	v_log_f32_e32 v159, v159
	s_nop 0
	v_mul_f32_e32 v163, 0x3f317217, v159
	v_fma_f32 v163, v159, s3, -v163
	v_fmac_f32_e32 v163, 0x3377d1cf, v159
	v_fmac_f32_e32 v163, 0x3f317217, v159
	v_cmp_lt_f32_e64 s[38:39], |v159|, s6
	s_nop 1
	v_cndmask_b32_e64 v159, v159, v163, s[38:39]
	v_cndmask_b32_e32 v163, 0, v224, vcc
	v_sub_f32_e32 v159, v159, v163
	v_cmp_gt_f32_e32 vcc, s2, v175
	v_max_f32_e32 v163, 0xc2700000, v159
	s_nop 0
	v_cndmask_b32_e64 v159, 0, 32, vcc
	v_ldexp_f32 v159, v175, v159
	v_log_f32_e32 v159, v159
	s_nop 0
	v_mul_f32_e32 v165, 0x3f317217, v159
	v_fma_f32 v165, v159, s3, -v165
	v_fmac_f32_e32 v165, 0x3377d1cf, v159
	v_fmac_f32_e32 v165, 0x3f317217, v159
	v_cmp_lt_f32_e64 s[38:39], |v159|, s6
	s_nop 1
	v_cndmask_b32_e64 v159, v159, v165, s[38:39]
	v_cndmask_b32_e32 v165, 0, v224, vcc
	v_sub_f32_e32 v159, v159, v165
	v_pk_mul_f32 v[174:175], v[158:159], v[152:153] op_sel_hi:[0,1]
	v_pk_mul_f32 v[172:173], v[172:173], v[174:175]
	v_max_f32_e32 v165, 0xc2700000, v159
	v_pk_mul_f32 v[172:173], v[172:173], s[10:11] op_sel_hi:[1,0]
	v_cvt_f32_i32_e32 v175, v39
	v_exp_f32_e32 v172, v172
	v_exp_f32_e32 v173, v173
	v_cvt_f32_i32_e32 v174, v38
	v_pk_add_f32 v[172:173], v[172:173], 1.0 op_sel_hi:[1,0]
	s_nop 0
	v_rcp_f32_e32 v172, v172
	v_rcp_f32_e32 v173, v173
	s_nop 0
	v_pk_fma_f32 v[172:173], v[190:191], v[172:173], v[132:133]
	s_nop 0
	v_cmp_gt_f32_e32 vcc, s2, v172
	s_nop 1
	v_cndmask_b32_e64 v159, 0, 32, vcc
	v_ldexp_f32 v159, v172, v159
	v_log_f32_e32 v159, v159
	s_nop 0
	v_mul_f32_e32 v167, 0x3f317217, v159
	v_fma_f32 v167, v159, s3, -v167
	v_fmac_f32_e32 v167, 0x3377d1cf, v159
	v_fmac_f32_e32 v167, 0x3f317217, v159
	v_cmp_lt_f32_e64 s[38:39], |v159|, s6
	s_nop 1
	v_cndmask_b32_e64 v159, v159, v167, s[38:39]
	v_cndmask_b32_e32 v167, 0, v224, vcc
	v_sub_f32_e32 v159, v159, v167
	v_cmp_gt_f32_e32 vcc, s2, v173
	v_max_f32_e32 v167, 0xc2700000, v159
	s_nop 0
; __device__ __forceinline__ unsigned cvt_pk_bf16(float lo, float hi) { f32x2_t v = {lo, hi}; bf16x2_t b = __builtin_convertvector(v, bf16x2_t); return __builtin_bit_cast(unsigned, b); }
; __device__ __forceinline__ float fast_rcp(float x) { return __builtin_amdgcn_rcpf(x); }
;     template <int KIND>
;     __device__ __forceinline__ void run(const f32x4 (&acc)[2][2][4][2], const Unit& u, int wr, int wc, int fr, int fq) const {
;     ...
;             for (int ai = 0; ai < 2; ++ai)
; #pragma unroll
;                 for (int m = 0; m < 4; ++m) { const int row = row0 + ai * HALF + m * 16; const float a = __shfl(ai ? sa_hi : sa_lo, 16 * m + fr);
;                     const f32x4 f0 = __builtin_convertvector(__builtin_bit_cast(i32x4, acc[ai][bj][m][0]), f32x4), f1 = __builtin_convertvector(__builtin_bit_cast(i32x4, acc[ai][bj][m][1]), f32x4);
;                     f32x2_t v[4] = {(f32x2_t){f0[0], f0[1]}, (f32x2_t){f0[2], f0[3]}, (f32x2_t){f1[0], f1[1]}, (f32x2_t){f1[2], f1[3]}};
; #pragma unroll
;                     for (int j = 0; j < 4; ++j) {
;                         v[j] = v[j] * (sc2[j] * (f32x2_t){a, a});
;                         if (KIND == 0 || KIND == 1 || KIND == 3) {
;                             const f32x2_t e = v[j] * (f32x2_t){-LOG2E, -LOG2E};
;                             const f32x2_t dn = (f32x2_t){__builtin_amdgcn_exp2f(e[0]), __builtin_amdgcn_exp2f(e[1])} + (f32x2_t){1.0f, 1.0f};
;                             const f32x2_t sg = (f32x2_t){fast_rcp(dn[0]), fast_rcp(dn[1])};
;                             if (KIND == 0) v[j] = v[j] * sg;
;                             else if (KIND == 3) v[j] = (v[j] * sg) * aux2[j];
;                             else { const f32x2_t f = __builtin_elementwise_fma((f32x2_t){1.0f, 1.0f} - aux2[j], sg, aux2[j]);
;                                 v[j] = (f32x2_t){fmaxf(__logf(f[0]), -60.0f), fmaxf(__logf(f[1]), -60.0f)}; }
;                         }
;                     }
;                     u32x4 w; w.x = cvt_pk_bf16(v[0][0], v[0][1]); w.y = cvt_pk_bf16(v[1][0], v[1][1]); w.z = cvt_pk_bf16(v[2][0], v[2][1]); w.w = cvt_pk_bf16(v[3][0], v[3][1]);
;                     *(u32x4*)(O + (size_t)row * NPROJ + col0 + bj * HALF) = w; }
	v_cndmask_b32_e64 v159, 0, 32, vcc
	v_ldexp_f32 v159, v173, v159
	v_log_f32_e32 v159, v159
	v_cvt_f32_i32_e32 v173, v41
	v_mul_f32_e32 v169, 0x3f317217, v159
	v_fma_f32 v169, v159, s3, -v169
	v_fmac_f32_e32 v169, 0x3377d1cf, v159
	v_fmac_f32_e32 v169, 0x3f317217, v159
	v_cmp_lt_f32_e64 s[38:39], |v159|, s6
	s_nop 1
	v_cndmask_b32_e64 v159, v159, v169, s[38:39]
	v_cndmask_b32_e32 v169, 0, v224, vcc
	v_sub_f32_e32 v159, v159, v169
	v_max_f32_e32 v169, 0xc2700000, v159
	v_pk_mul_f32 v[158:159], v[158:159], v[148:149] op_sel_hi:[0,1]
	v_pk_mul_f32 v[156:157], v[156:157], v[158:159]
	s_nop 0
	v_pk_mul_f32 v[156:157], v[156:157], s[10:11] op_sel_hi:[1,0]
	s_nop 0
	v_exp_f32_e32 v156, v156
	v_exp_f32_e32 v157, v157
	s_nop 0
	v_pk_add_f32 v[156:157], v[156:157], 1.0 op_sel_hi:[1,0]
	s_nop 0
	v_rcp_f32_e32 v156, v156
	v_rcp_f32_e32 v157, v157
	s_nop 0
	v_pk_fma_f32 v[156:157], v[192:193], v[156:157], v[134:135]
	s_nop 0
	v_cmp_gt_f32_e32 vcc, s2, v156
	s_nop 1
	v_cndmask_b32_e64 v158, 0, 32, vcc
	v_ldexp_f32 v156, v156, v158
	v_log_f32_e32 v156, v156
	s_nop 0
	v_mul_f32_e32 v158, 0x3f317217, v156
	v_fma_f32 v158, v156, s3, -v158
	v_fmac_f32_e32 v158, 0x3377d1cf, v156
	v_fmac_f32_e32 v158, 0x3f317217, v156
	v_cmp_lt_f32_e64 s[38:39], |v156|, s6
	s_nop 1
	v_cndmask_b32_e64 v156, v156, v158, s[38:39]
	v_cndmask_b32_e32 v158, 0, v224, vcc
	v_sub_f32_e32 v156, v156, v158
	v_cmp_gt_f32_e32 vcc, s2, v157
	v_max_f32_e32 v159, 0xc2700000, v156
	v_cvt_pk_bf16_f32 v158, v167, v169
	v_cndmask_b32_e64 v156, 0, 32, vcc
	v_ldexp_f32 v156, v157, v156
	v_log_f32_e32 v156, v156
	s_nop 0
	v_mul_f32_e32 v157, 0x3f317217, v156
	v_fma_f32 v157, v156, s3, -v157
	v_fmac_f32_e32 v157, 0x3377d1cf, v156
	v_fmac_f32_e32 v157, 0x3f317217, v156
	v_cmp_lt_f32_e64 s[38:39], |v156|, s6
	s_nop 1
	v_cndmask_b32_e64 v156, v156, v157, s[38:39]
	v_cndmask_b32_e32 v157, 0, v224, vcc
	v_sub_f32_e32 v156, v156, v157
	v_max_f32_e32 v172, 0xc2700000, v156
	v_cvt_pk_bf16_f32 v156, v66, v161
	v_cvt_pk_bf16_f32 v157, v163, v165
	v_cvt_pk_bf16_f32 v159, v159, v172
	global_store_dwordx4 v[176:177], v[156:159], off offset:256
	v_pk_mul_f32 v[176:177], v[160:161], v[170:171] op_sel_hi:[0,1]
	v_pk_mul_f32 v[174:175], v[174:175], v[176:177]
	v_cvt_f32_i32_e32 v172, v40
	v_pk_mul_f32 v[174:175], v[174:175], s[10:11] op_sel_hi:[1,0]
	v_cvt_f32_i32_e32 v159, v35
	v_exp_f32_e32 v174, v174
	v_exp_f32_e32 v175, v175
	v_cvt_f32_i32_e32 v158, v34
	v_cvt_f32_i32_e32 v157, v37
	v_cvt_f32_i32_e32 v156, v36
	v_pk_add_f32 v[174:175], v[174:175], 1.0 op_sel_hi:[1,0]
	s_nop 0
	v_rcp_f32_e32 v174, v174
	v_rcp_f32_e32 v175, v175
	s_nop 0
	v_pk_fma_f32 v[174:175], v[180:181], v[174:175], v[136:137]
	s_nop 0
	v_cmp_gt_f32_e32 vcc, s2, v174
	s_nop 1
	v_cndmask_b32_e64 v66, 0, 32, vcc
	v_ldexp_f32 v66, v174, v66
	v_log_f32_e32 v66, v66
	s_nop 0
	v_mul_f32_e32 v161, 0x3f317217, v66
	v_fma_f32 v161, v66, s3, -v161
	v_fmac_f32_e32 v161, 0x3377d1cf, v66
	v_fmac_f32_e32 v161, 0x3f317217, v66
	v_cmp_lt_f32_e64 s[38:39], |v66|, s6
	s_nop 1
	v_cndmask_b32_e64 v66, v66, v161, s[38:39]
	v_cndmask_b32_e32 v161, 0, v224, vcc
	v_cmp_gt_f32_e32 vcc, s2, v175
	v_sub_f32_e32 v66, v66, v161
	v_max_f32_e32 v66, 0xc2700000, v66
	v_cndmask_b32_e64 v161, 0, 32, vcc
	v_ldexp_f32 v161, v175, v161
	v_log_f32_e32 v161, v161
	s_nop 0
	v_mul_f32_e32 v163, 0x3f317217, v161
	v_fma_f32 v163, v161, s3, -v163
	v_fmac_f32_e32 v163, 0x3377d1cf, v161
	v_fmac_f32_e32 v163, 0x3f317217, v161
	v_cmp_lt_f32_e64 s[38:39], |v161|, s6
	s_nop 1
	v_cndmask_b32_e64 v161, v161, v163, s[38:39]
	v_cndmask_b32_e32 v163, 0, v224, vcc
	v_sub_f32_e32 v161, v161, v163
	v_max_f32_e32 v161, 0xc2700000, v161
	v_pk_mul_f32 v[174:175], v[160:161], v[154:155] op_sel_hi:[0,1]
	v_pk_mul_f32 v[172:173], v[172:173], v[174:175]
	s_nop 0
	v_pk_mul_f32 v[172:173], v[172:173], s[10:11] op_sel_hi:[1,0]
	s_nop 0
	v_exp_f32_e32 v172, v172
	v_exp_f32_e32 v173, v173
	s_nop 0
	v_pk_add_f32 v[172:173], v[172:173], 1.0 op_sel_hi:[1,0]
	s_nop 0
	v_rcp_f32_e32 v172, v172
	v_rcp_f32_e32 v173, v173
	s_nop 0
	v_pk_fma_f32 v[172:173], v[188:189], v[172:173], v[138:139]
	s_nop 0
	v_cmp_gt_f32_e32 vcc, s2, v172
	s_nop 1
	v_cndmask_b32_e64 v163, 0, 32, vcc
	v_ldexp_f32 v163, v172, v163
	v_log_f32_e32 v163, v163
	s_nop 0
	v_mul_f32_e32 v165, 0x3f317217, v163
	v_fma_f32 v165, v163, s3, -v165
	v_fmac_f32_e32 v165, 0x3377d1cf, v163
	v_fmac_f32_e32 v165, 0x3f317217, v163
	v_cmp_lt_f32_e64 s[38:39], |v163|, s6
	s_nop 1
	v_cndmask_b32_e64 v163, v163, v165, s[38:39]
	v_cndmask_b32_e32 v165, 0, v224, vcc
	v_cmp_gt_f32_e32 vcc, s2, v173
	v_sub_f32_e32 v163, v163, v165
	v_max_f32_e32 v163, 0xc2700000, v163
	v_cndmask_b32_e64 v165, 0, 32, vcc
	v_ldexp_f32 v165, v173, v165
	v_pk_mul_f32 v[172:173], v[160:161], v[152:153] op_sel_hi:[0,1]
	v_pk_mul_f32 v[158:159], v[158:159], v[172:173]
	v_log_f32_e32 v165, v165
	v_pk_mul_f32 v[158:159], v[158:159], s[10:11] op_sel_hi:[1,0]
	v_cvt_f32_i32_e32 v173, v31
	v_exp_f32_e32 v158, v158
	v_exp_f32_e32 v159, v159
	v_mul_f32_e32 v167, 0x3f317217, v165
	v_fma_f32 v167, v165, s3, -v167
	v_fmac_f32_e32 v167, 0x3377d1cf, v165
	v_pk_add_f32 v[158:159], v[158:159], 1.0 op_sel_hi:[1,0]
	v_fmac_f32_e32 v167, 0x3f317217, v165
	v_rcp_f32_e32 v158, v158
	v_rcp_f32_e32 v159, v159
	v_cmp_lt_f32_e64 s[38:39], |v165|, s6
	v_cvt_f32_i32_e32 v172, v30
	v_pk_mul_f32 v[174:175], v[162:163], v[170:171] op_sel_hi:[0,1]
	v_pk_fma_f32 v[158:159], v[190:191], v[158:159], v[132:133]
	v_cndmask_b32_e64 v165, v165, v167, s[38:39]
	v_cndmask_b32_e32 v167, 0, v224, vcc
	v_cmp_gt_f32_e32 vcc, s2, v158
	v_sub_f32_e32 v165, v165, v167
	v_pk_mul_f32 v[172:173], v[172:173], v[174:175]
	v_cndmask_b32_e64 v167, 0, 32, vcc
; __device__ __forceinline__ unsigned cvt_pk_bf16(float lo, float hi) { f32x2_t v = {lo, hi}; bf16x2_t b = __builtin_convertvector(v, bf16x2_t); return __builtin_bit_cast(unsigned, b); }
; __device__ __forceinline__ float fast_rcp(float x) { return __builtin_amdgcn_rcpf(x); }
;     template <int KIND>
;     __device__ __forceinline__ void run(const f32x4 (&acc)[2][2][4][2], const Unit& u, int wr, int wc, int fr, int fq) const {
;     ...
;             for (int ai = 0; ai < 2; ++ai)
; #pragma unroll
;                 for (int m = 0; m < 4; ++m) { const int row = row0 + ai * HALF + m * 16; const float a = __shfl(ai ? sa_hi : sa_lo, 16 * m + fr);
;                     const f32x4 f0 = __builtin_convertvector(__builtin_bit_cast(i32x4, acc[ai][bj][m][0]), f32x4), f1 = __builtin_convertvector(__builtin_bit_cast(i32x4, acc[ai][bj][m][1]), f32x4);
;                     f32x2_t v[4] = {(f32x2_t){f0[0], f0[1]}, (f32x2_t){f0[2], f0[3]}, (f32x2_t){f1[0], f1[1]}, (f32x2_t){f1[2], f1[3]}};
; #pragma unroll
;                     for (int j = 0; j < 4; ++j) {
;                         v[j] = v[j] * (sc2[j] * (f32x2_t){a, a});
;                         if (KIND == 0 || KIND == 1 || KIND == 3) {
;                             const f32x2_t e = v[j] * (f32x2_t){-LOG2E, -LOG2E};
;                             const f32x2_t dn = (f32x2_t){__builtin_amdgcn_exp2f(e[0]), __builtin_amdgcn_exp2f(e[1])} + (f32x2_t){1.0f, 1.0f};
;                             const f32x2_t sg = (f32x2_t){fast_rcp(dn[0]), fast_rcp(dn[1])};
;                             if (KIND == 0) v[j] = v[j] * sg;
;                             else if (KIND == 3) v[j] = (v[j] * sg) * aux2[j];
;                             else { const f32x2_t f = __builtin_elementwise_fma((f32x2_t){1.0f, 1.0f} - aux2[j], sg, aux2[j]);
;                                 v[j] = (f32x2_t){fmaxf(__logf(f[0]), -60.0f), fmaxf(__logf(f[1]), -60.0f)}; }
;                         }
;                     }
;                     u32x4 w; w.x = cvt_pk_bf16(v[0][0], v[0][1]); w.y = cvt_pk_bf16(v[1][0], v[1][1]); w.z = cvt_pk_bf16(v[2][0], v[2][1]); w.w = cvt_pk_bf16(v[3][0], v[3][1]);
;                     *(u32x4*)(O + (size_t)row * NPROJ + col0 + bj * HALF) = w; }
	v_ldexp_f32 v158, v158, v167
	v_log_f32_e32 v158, v158
	v_pk_mul_f32 v[172:173], v[172:173], s[10:11] op_sel_hi:[1,0]
	v_max_f32_e32 v165, 0xc2700000, v165
	v_exp_f32_e32 v172, v172
	v_mul_f32_e32 v167, 0x3f317217, v158
	v_fma_f32 v167, v158, s3, -v167
	v_fmac_f32_e32 v167, 0x3377d1cf, v158
	v_fmac_f32_e32 v167, 0x3f317217, v158
	v_cmp_lt_f32_e64 s[38:39], |v158|, s6
	v_exp_f32_e32 v173, v173
	s_nop 0
	v_cndmask_b32_e64 v158, v158, v167, s[38:39]
	v_cndmask_b32_e32 v167, 0, v224, vcc
	v_sub_f32_e32 v158, v158, v167
	v_cmp_gt_f32_e32 vcc, s2, v159
	v_max_f32_e32 v167, 0xc2700000, v158
	v_pk_add_f32 v[172:173], v[172:173], 1.0 op_sel_hi:[1,0]
	v_cndmask_b32_e64 v158, 0, 32, vcc
	v_ldexp_f32 v158, v159, v158
	v_log_f32_e32 v158, v158
	v_rcp_f32_e32 v172, v172
	v_rcp_f32_e32 v173, v173
	v_mul_f32_e32 v159, 0x3f317217, v158
	v_fma_f32 v159, v158, s3, -v159
	v_fmac_f32_e32 v159, 0x3377d1cf, v158
	v_fmac_f32_e32 v159, 0x3f317217, v158
	v_cmp_lt_f32_e64 s[38:39], |v158|, s6
	v_pk_fma_f32 v[172:173], v[180:181], v[172:173], v[136:137]
	s_nop 0
	v_cndmask_b32_e64 v158, v158, v159, s[38:39]
	v_cndmask_b32_e32 v159, 0, v224, vcc
	v_sub_f32_e32 v158, v158, v159
	v_max_f32_e32 v169, 0xc2700000, v158
	v_pk_mul_f32 v[158:159], v[160:161], v[148:149] op_sel_hi:[0,1]
	v_pk_mul_f32 v[156:157], v[156:157], v[158:159]
	s_nop 0
	v_pk_mul_f32 v[156:157], v[156:157], s[10:11] op_sel_hi:[1,0]
	s_nop 0
	v_exp_f32_e32 v156, v156
	v_exp_f32_e32 v157, v157
	s_nop 0
	v_pk_add_f32 v[156:157], v[156:157], 1.0 op_sel_hi:[1,0]
	s_nop 0
	v_rcp_f32_e32 v156, v156
	v_rcp_f32_e32 v157, v157
	s_nop 0
	v_pk_fma_f32 v[156:157], v[192:193], v[156:157], v[134:135]
	s_nop 0
	v_cmp_gt_f32_e32 vcc, s2, v156
	s_nop 1
	v_cndmask_b32_e64 v158, 0, 32, vcc
	v_ldexp_f32 v156, v156, v158
	v_log_f32_e32 v156, v156
	s_nop 0
	v_mul_f32_e32 v158, 0x3f317217, v156
	v_fma_f32 v158, v156, s3, -v158
	v_fmac_f32_e32 v158, 0x3377d1cf, v156
	v_fmac_f32_e32 v158, 0x3f317217, v156
	v_cmp_lt_f32_e64 s[38:39], |v156|, s6
	s_nop 1
	v_cndmask_b32_e64 v156, v156, v158, s[38:39]
	v_cndmask_b32_e32 v158, 0, v224, vcc
	v_sub_f32_e32 v156, v156, v158
	v_cmp_gt_f32_e32 vcc, s2, v157
	v_max_f32_e32 v159, 0xc2700000, v156
	v_cvt_pk_bf16_f32 v158, v167, v169
	v_cndmask_b32_e64 v156, 0, 32, vcc
	v_ldexp_f32 v156, v157, v156
	v_log_f32_e32 v156, v156
	s_nop 0
	v_mul_f32_e32 v157, 0x3f317217, v156
	v_fma_f32 v157, v156, s3, -v157
	v_fmac_f32_e32 v157, 0x3377d1cf, v156
	v_fmac_f32_e32 v157, 0x3f317217, v156
	v_cmp_lt_f32_e64 s[38:39], |v156|, s6
	s_nop 1
	v_cndmask_b32_e64 v156, v156, v157, s[38:39]
	v_cndmask_b32_e32 v157, 0, v224, vcc
	v_sub_f32_e32 v156, v156, v157
	v_cmp_gt_f32_e32 vcc, s2, v172
	v_max_f32_e32 v160, 0xc2700000, v156
	v_cvt_pk_bf16_f32 v156, v66, v161
	v_cndmask_b32_e64 v66, 0, 32, vcc
	v_ldexp_f32 v66, v172, v66
	v_log_f32_e32 v66, v66
	v_cvt_pk_bf16_f32 v157, v163, v165
	v_cvt_pk_bf16_f32 v159, v159, v160
	v_cvt_f32_i32_e32 v161, v33
	v_mul_f32_e32 v163, 0x3f317217, v66
	v_fma_f32 v163, v66, s3, -v163
	v_fmac_f32_e32 v163, 0x3377d1cf, v66
	v_fmac_f32_e32 v163, 0x3f317217, v66
	v_cmp_lt_f32_e64 s[38:39], |v66|, s6
	v_cvt_f32_i32_e32 v160, v32
	global_store_dwordx4 v[178:179], v[156:159], off offset:256
	v_cndmask_b32_e64 v66, v66, v163, s[38:39]
	v_cndmask_b32_e32 v163, 0, v224, vcc
	v_cmp_gt_f32_e32 vcc, s2, v173
	v_sub_f32_e32 v66, v66, v163
	v_cvt_f32_i32_e32 v159, v27
	v_cndmask_b32_e64 v163, 0, 32, vcc
	v_ldexp_f32 v163, v173, v163
	v_log_f32_e32 v163, v163
	v_cvt_f32_i32_e32 v158, v26
	v_cvt_f32_i32_e32 v157, v29
	v_cvt_f32_i32_e32 v156, v28
	v_mul_f32_e32 v165, 0x3f317217, v163
	v_fma_f32 v165, v163, s3, -v165
	v_fmac_f32_e32 v165, 0x3377d1cf, v163
	v_fmac_f32_e32 v165, 0x3f317217, v163
	v_cmp_lt_f32_e64 s[38:39], |v163|, s6
	v_max_f32_e32 v66, 0xc2700000, v66
	s_nop 0
	v_cndmask_b32_e64 v163, v163, v165, s[38:39]
	v_cndmask_b32_e32 v165, 0, v224, vcc
	v_sub_f32_e32 v163, v163, v165
	v_max_f32_e32 v163, 0xc2700000, v163
	v_pk_mul_f32 v[172:173], v[162:163], v[154:155] op_sel_hi:[0,1]
	v_pk_mul_f32 v[160:161], v[160:161], v[172:173]
	s_nop 0
	v_pk_mul_f32 v[160:161], v[160:161], s[10:11] op_sel_hi:[1,0]
	s_nop 0
	v_exp_f32_e32 v160, v160
	v_exp_f32_e32 v161, v161
	s_nop 0
	v_pk_add_f32 v[160:161], v[160:161], 1.0 op_sel_hi:[1,0]
	s_nop 0
	v_rcp_f32_e32 v160, v160
	v_rcp_f32_e32 v161, v161
	s_nop 0
	v_pk_fma_f32 v[160:161], v[188:189], v[160:161], v[138:139]
	s_nop 0
	v_cmp_gt_f32_e32 vcc, s2, v160
	s_nop 1
	v_cndmask_b32_e64 v165, 0, 32, vcc
	v_ldexp_f32 v160, v160, v165
	v_log_f32_e32 v160, v160
	s_nop 0
	v_mul_f32_e32 v165, 0x3f317217, v160
	v_fma_f32 v165, v160, s3, -v165
	v_fmac_f32_e32 v165, 0x3377d1cf, v160
	v_fmac_f32_e32 v165, 0x3f317217, v160
	v_cmp_lt_f32_e64 s[38:39], |v160|, s6
	s_nop 1
	v_cndmask_b32_e64 v160, v160, v165, s[38:39]
	v_cndmask_b32_e32 v165, 0, v224, vcc
	v_sub_f32_e32 v160, v160, v165
	v_cmp_gt_f32_e32 vcc, s2, v161
	v_max_f32_e32 v165, 0xc2700000, v160
	v_pk_mul_f32 v[172:173], v[164:165], v[170:171] op_sel_hi:[0,1]
	v_cndmask_b32_e64 v160, 0, 32, vcc
	v_ldexp_f32 v160, v161, v160
	v_log_f32_e32 v160, v160
	s_nop 0
	v_mul_f32_e32 v161, 0x3f317217, v160
	v_fma_f32 v161, v160, s3, -v161
	v_fmac_f32_e32 v161, 0x3377d1cf, v160
	v_fmac_f32_e32 v161, 0x3f317217, v160
	v_cmp_lt_f32_e64 s[38:39], |v160|, s6
	s_nop 1
	v_cndmask_b32_e64 v160, v160, v161, s[38:39]
	v_cndmask_b32_e32 v161, 0, v224, vcc
	v_sub_f32_e32 v160, v160, v161
	v_max_f32_e32 v167, 0xc2700000, v160
	v_pk_mul_f32 v[160:161], v[162:163], v[152:153] op_sel_hi:[0,1]
	v_pk_mul_f32 v[158:159], v[158:159], v[160:161]
	s_nop 0
	v_pk_mul_f32 v[158:159], v[158:159], s[10:11] op_sel_hi:[1,0]
	s_nop 0
; __device__ __forceinline__ unsigned cvt_pk_bf16(float lo, float hi) { f32x2_t v = {lo, hi}; bf16x2_t b = __builtin_convertvector(v, bf16x2_t); return __builtin_bit_cast(unsigned, b); }
; __device__ __forceinline__ float fast_rcp(float x) { return __builtin_amdgcn_rcpf(x); }
;     template <int KIND>
;     __device__ __forceinline__ void run(const f32x4 (&acc)[2][2][4][2], const Unit& u, int wr, int wc, int fr, int fq) const {
;     ...
;             for (int ai = 0; ai < 2; ++ai)
; #pragma unroll
;                 for (int m = 0; m < 4; ++m) { const int row = row0 + ai * HALF + m * 16; const float a = __shfl(ai ? sa_hi : sa_lo, 16 * m + fr);
;                     const f32x4 f0 = __builtin_convertvector(__builtin_bit_cast(i32x4, acc[ai][bj][m][0]), f32x4), f1 = __builtin_convertvector(__builtin_bit_cast(i32x4, acc[ai][bj][m][1]), f32x4);
;                     f32x2_t v[4] = {(f32x2_t){f0[0], f0[1]}, (f32x2_t){f0[2], f0[3]}, (f32x2_t){f1[0], f1[1]}, (f32x2_t){f1[2], f1[3]}};
; #pragma unroll
;                     for (int j = 0; j < 4; ++j) {
;                         v[j] = v[j] * (sc2[j] * (f32x2_t){a, a});
;                         if (KIND == 0 || KIND == 1 || KIND == 3) {
;                             const f32x2_t e = v[j] * (f32x2_t){-LOG2E, -LOG2E};
;                             const f32x2_t dn = (f32x2_t){__builtin_amdgcn_exp2f(e[0]), __builtin_amdgcn_exp2f(e[1])} + (f32x2_t){1.0f, 1.0f};
;                             const f32x2_t sg = (f32x2_t){fast_rcp(dn[0]), fast_rcp(dn[1])};
;                             if (KIND == 0) v[j] = v[j] * sg;
;                             else if (KIND == 3) v[j] = (v[j] * sg) * aux2[j];
;                             else { const f32x2_t f = __builtin_elementwise_fma((f32x2_t){1.0f, 1.0f} - aux2[j], sg, aux2[j]);
;                                 v[j] = (f32x2_t){fmaxf(__logf(f[0]), -60.0f), fmaxf(__logf(f[1]), -60.0f)}; }
;                         }
;                     }
;                     u32x4 w; w.x = cvt_pk_bf16(v[0][0], v[0][1]); w.y = cvt_pk_bf16(v[1][0], v[1][1]); w.z = cvt_pk_bf16(v[2][0], v[2][1]); w.w = cvt_pk_bf16(v[3][0], v[3][1]);
;                     *(u32x4*)(O + (size_t)row * NPROJ + col0 + bj * HALF) = w; }
	v_exp_f32_e32 v158, v158
	v_exp_f32_e32 v159, v159
	s_nop 0
	v_pk_add_f32 v[158:159], v[158:159], 1.0 op_sel_hi:[1,0]
	s_nop 0
	v_rcp_f32_e32 v158, v158
	v_rcp_f32_e32 v159, v159
	s_nop 0
	v_pk_fma_f32 v[158:159], v[190:191], v[158:159], v[132:133]
	s_nop 0
	v_cmp_gt_f32_e32 vcc, s2, v158
	s_nop 1
	v_cndmask_b32_e64 v160, 0, 32, vcc
	v_ldexp_f32 v158, v158, v160
	v_log_f32_e32 v158, v158
	s_nop 0
	v_mul_f32_e32 v160, 0x3f317217, v158
	v_fma_f32 v160, v158, s3, -v160
	v_fmac_f32_e32 v160, 0x3377d1cf, v158
	v_fmac_f32_e32 v160, 0x3f317217, v158
	v_cmp_lt_f32_e64 s[38:39], |v158|, s6
	s_nop 1
	v_cndmask_b32_e64 v158, v158, v160, s[38:39]
	v_cndmask_b32_e32 v160, 0, v224, vcc
	v_sub_f32_e32 v158, v158, v160
	v_cmp_gt_f32_e32 vcc, s2, v159
	v_max_f32_e32 v160, 0xc2700000, v158
	s_nop 0
	v_cndmask_b32_e64 v158, 0, 32, vcc
	v_ldexp_f32 v158, v159, v158
	v_log_f32_e32 v158, v158
	s_nop 0
	v_mul_f32_e32 v159, 0x3f317217, v158
	v_fma_f32 v159, v158, s3, -v159
	v_fmac_f32_e32 v159, 0x3377d1cf, v158
	v_fmac_f32_e32 v159, 0x3f317217, v158
	v_cmp_lt_f32_e64 s[38:39], |v158|, s6
	s_nop 1
	v_cndmask_b32_e64 v158, v158, v159, s[38:39]
	v_cndmask_b32_e32 v159, 0, v224, vcc
	v_sub_f32_e32 v158, v158, v159
	v_max_f32_e32 v161, 0xc2700000, v158
	v_pk_mul_f32 v[158:159], v[162:163], v[148:149] op_sel_hi:[0,1]
	v_pk_mul_f32 v[156:157], v[156:157], v[158:159]
	s_nop 0
	v_pk_mul_f32 v[156:157], v[156:157], s[10:11] op_sel_hi:[1,0]
	s_nop 0
	v_exp_f32_e32 v156, v156
	v_exp_f32_e32 v157, v157
	s_nop 0
	v_pk_add_f32 v[156:157], v[156:157], 1.0 op_sel_hi:[1,0]
	s_nop 0
	v_rcp_f32_e32 v156, v156
	v_rcp_f32_e32 v157, v157
	s_nop 0
	v_pk_fma_f32 v[156:157], v[192:193], v[156:157], v[134:135]
	s_nop 0
	v_cmp_gt_f32_e32 vcc, s2, v156
	s_nop 1
	v_cndmask_b32_e64 v158, 0, 32, vcc
	v_ldexp_f32 v156, v156, v158
	v_log_f32_e32 v156, v156
	s_nop 0
	v_mul_f32_e32 v158, 0x3f317217, v156
	v_fma_f32 v158, v156, s3, -v158
	v_fmac_f32_e32 v158, 0x3377d1cf, v156
	v_fmac_f32_e32 v158, 0x3f317217, v156
	v_cmp_lt_f32_e64 s[38:39], |v156|, s6
	s_nop 1
	v_cndmask_b32_e64 v156, v156, v158, s[38:39]
	v_cndmask_b32_e32 v158, 0, v224, vcc
	v_sub_f32_e32 v156, v156, v158
	v_cmp_gt_f32_e32 vcc, s2, v157
	v_max_f32_e32 v159, 0xc2700000, v156
	v_cvt_pk_bf16_f32 v158, v160, v161
	v_cndmask_b32_e64 v156, 0, 32, vcc
	v_ldexp_f32 v156, v157, v156
	v_log_f32_e32 v156, v156
	v_cvt_f32_i32_e32 v161, v25
	v_cvt_f32_i32_e32 v160, v24
	v_mul_f32_e32 v157, 0x3f317217, v156
	v_fma_f32 v157, v156, s3, -v157
	v_fmac_f32_e32 v157, 0x3377d1cf, v156
	v_fmac_f32_e32 v157, 0x3f317217, v156
	v_cmp_lt_f32_e64 s[38:39], |v156|, s6
	s_nop 1
	v_cndmask_b32_e64 v156, v156, v157, s[38:39]
	v_cndmask_b32_e32 v157, 0, v224, vcc
	v_sub_f32_e32 v156, v156, v157
	v_max_f32_e32 v162, 0xc2700000, v156
	v_cvt_pk_bf16_f32 v156, v66, v163
	v_cvt_pk_bf16_f32 v159, v159, v162
	v_cvt_f32_i32_e32 v163, v23
	v_cvt_f32_i32_e32 v162, v22
	v_cvt_pk_bf16_f32 v157, v165, v167
	global_store_dwordx4 v[182:183], v[156:159], off offset:256
	v_pk_mul_f32 v[162:163], v[162:163], v[172:173]
	s_nop 0
	v_pk_mul_f32 v[162:163], v[162:163], s[10:11] op_sel_hi:[1,0]
	v_cvt_f32_i32_e32 v159, v19
	v_exp_f32_e32 v162, v162
	v_exp_f32_e32 v163, v163
	v_cvt_f32_i32_e32 v158, v18
	v_cvt_f32_i32_e32 v157, v21
	v_cvt_f32_i32_e32 v156, v20
	v_pk_add_f32 v[162:163], v[162:163], 1.0 op_sel_hi:[1,0]
	s_nop 0
	v_rcp_f32_e32 v162, v162
	v_rcp_f32_e32 v163, v163
	s_nop 0
	v_pk_fma_f32 v[162:163], v[180:181], v[162:163], v[136:137]
	s_nop 0
	v_cmp_gt_f32_e32 vcc, s2, v162
	s_nop 1
	v_cndmask_b32_e64 v66, 0, 32, vcc
	v_ldexp_f32 v66, v162, v66
	v_log_f32_e32 v66, v66
	s_nop 0
	v_mul_f32_e32 v162, 0x3f317217, v66
	v_fma_f32 v162, v66, s3, -v162
	v_fmac_f32_e32 v162, 0x3377d1cf, v66
	v_fmac_f32_e32 v162, 0x3f317217, v66
	v_cmp_lt_f32_e64 s[38:39], |v66|, s6
	s_nop 1
	v_cndmask_b32_e64 v66, v66, v162, s[38:39]
	v_cndmask_b32_e32 v162, 0, v224, vcc
	v_cmp_gt_f32_e32 vcc, s2, v163
	v_sub_f32_e32 v66, v66, v162
	v_max_f32_e32 v66, 0xc2700000, v66
	v_cndmask_b32_e64 v162, 0, 32, vcc
	v_ldexp_f32 v162, v163, v162
	v_log_f32_e32 v162, v162
	s_nop 0
	v_mul_f32_e32 v163, 0x3f317217, v162
	v_fma_f32 v163, v162, s3, -v163
	v_fmac_f32_e32 v163, 0x3377d1cf, v162
	v_fmac_f32_e32 v163, 0x3f317217, v162
	v_cmp_lt_f32_e64 s[38:39], |v162|, s6
	s_nop 1
	v_cndmask_b32_e64 v162, v162, v163, s[38:39]
	v_cndmask_b32_e32 v163, 0, v224, vcc
	v_sub_f32_e32 v162, v162, v163
	v_max_f32_e32 v165, 0xc2700000, v162
	v_pk_mul_f32 v[162:163], v[164:165], v[154:155] op_sel_hi:[0,1]
	v_pk_mul_f32 v[160:161], v[160:161], v[162:163]
	s_nop 0
	v_pk_mul_f32 v[160:161], v[160:161], s[10:11] op_sel_hi:[1,0]
	s_nop 0
	v_exp_f32_e32 v160, v160
	v_exp_f32_e32 v161, v161
	s_nop 0
	v_pk_add_f32 v[160:161], v[160:161], 1.0 op_sel_hi:[1,0]
	s_nop 0
	v_rcp_f32_e32 v160, v160
	v_rcp_f32_e32 v161, v161
	s_nop 0
	v_pk_fma_f32 v[160:161], v[188:189], v[160:161], v[138:139]
	s_nop 0
	v_cmp_gt_f32_e32 vcc, s2, v160
	s_nop 1
	v_cndmask_b32_e64 v162, 0, 32, vcc
	v_ldexp_f32 v160, v160, v162
	v_log_f32_e32 v160, v160
	s_nop 0
	v_mul_f32_e32 v162, 0x3f317217, v160
	v_fma_f32 v162, v160, s3, -v162
	v_fmac_f32_e32 v162, 0x3377d1cf, v160
	v_fmac_f32_e32 v162, 0x3f317217, v160
	v_cmp_lt_f32_e64 s[38:39], |v160|, s6
	s_nop 1
	v_cndmask_b32_e64 v160, v160, v162, s[38:39]
	v_cndmask_b32_e32 v162, 0, v224, vcc
	v_sub_f32_e32 v160, v160, v162
	v_cmp_gt_f32_e32 vcc, s2, v161
	v_max_f32_e32 v162, 0xc2700000, v160
	s_nop 0
	v_cndmask_b32_e64 v160, 0, 32, vcc
	v_ldexp_f32 v160, v161, v160
	v_log_f32_e32 v160, v160
	s_nop 0
	v_mul_f32_e32 v161, 0x3f317217, v160
	v_fma_f32 v161, v160, s3, -v161
	v_fmac_f32_e32 v161, 0x3377d1cf, v160
; __device__ __forceinline__ unsigned cvt_pk_bf16(float lo, float hi) { f32x2_t v = {lo, hi}; bf16x2_t b = __builtin_convertvector(v, bf16x2_t); return __builtin_bit_cast(unsigned, b); }
; __device__ __forceinline__ float fast_rcp(float x) { return __builtin_amdgcn_rcpf(x); }
;     template <int KIND>
;     __device__ __forceinline__ void run(const f32x4 (&acc)[2][2][4][2], const Unit& u, int wr, int wc, int fr, int fq) const {
;     ...
;             for (int ai = 0; ai < 2; ++ai)
; #pragma unroll
;                 for (int m = 0; m < 4; ++m) { const int row = row0 + ai * HALF + m * 16; const float a = __shfl(ai ? sa_hi : sa_lo, 16 * m + fr);
;                     const f32x4 f0 = __builtin_convertvector(__builtin_bit_cast(i32x4, acc[ai][bj][m][0]), f32x4), f1 = __builtin_convertvector(__builtin_bit_cast(i32x4, acc[ai][bj][m][1]), f32x4);
;                     f32x2_t v[4] = {(f32x2_t){f0[0], f0[1]}, (f32x2_t){f0[2], f0[3]}, (f32x2_t){f1[0], f1[1]}, (f32x2_t){f1[2], f1[3]}};
; #pragma unroll
;                     for (int j = 0; j < 4; ++j) {
;                         v[j] = v[j] * (sc2[j] * (f32x2_t){a, a});
;                         if (KIND == 0 || KIND == 1 || KIND == 3) {
;                             const f32x2_t e = v[j] * (f32x2_t){-LOG2E, -LOG2E};
;                             const f32x2_t dn = (f32x2_t){__builtin_amdgcn_exp2f(e[0]), __builtin_amdgcn_exp2f(e[1])} + (f32x2_t){1.0f, 1.0f};
;                             const f32x2_t sg = (f32x2_t){fast_rcp(dn[0]), fast_rcp(dn[1])};
;                             if (KIND == 0) v[j] = v[j] * sg;
;                             else if (KIND == 3) v[j] = (v[j] * sg) * aux2[j];
;                             else { const f32x2_t f = __builtin_elementwise_fma((f32x2_t){1.0f, 1.0f} - aux2[j], sg, aux2[j]);
;                                 v[j] = (f32x2_t){fmaxf(__logf(f[0]), -60.0f), fmaxf(__logf(f[1]), -60.0f)}; }
;                         }
;                     }
;                     u32x4 w; w.x = cvt_pk_bf16(v[0][0], v[0][1]); w.y = cvt_pk_bf16(v[1][0], v[1][1]); w.z = cvt_pk_bf16(v[2][0], v[2][1]); w.w = cvt_pk_bf16(v[3][0], v[3][1]);
;                     *(u32x4*)(O + (size_t)row * NPROJ + col0 + bj * HALF) = w; }
	v_fmac_f32_e32 v161, 0x3f317217, v160
	v_cmp_lt_f32_e64 s[38:39], |v160|, s6
	s_nop 1
	v_cndmask_b32_e64 v160, v160, v161, s[38:39]
	v_cndmask_b32_e32 v161, 0, v224, vcc
	v_sub_f32_e32 v160, v160, v161
	v_max_f32_e32 v163, 0xc2700000, v160
	v_pk_mul_f32 v[160:161], v[164:165], v[152:153] op_sel_hi:[0,1]
	v_pk_mul_f32 v[158:159], v[158:159], v[160:161]
	s_nop 0
	v_pk_mul_f32 v[158:159], v[158:159], s[10:11] op_sel_hi:[1,0]
	s_nop 0
	v_exp_f32_e32 v158, v158
	v_exp_f32_e32 v159, v159
	s_nop 0
	v_pk_add_f32 v[158:159], v[158:159], 1.0 op_sel_hi:[1,0]
	s_nop 0
	v_rcp_f32_e32 v158, v158
	v_rcp_f32_e32 v159, v159
	s_nop 0
	v_pk_fma_f32 v[158:159], v[190:191], v[158:159], v[132:133]
	s_nop 0
	v_cmp_gt_f32_e32 vcc, s2, v158
	s_nop 1
	v_cndmask_b32_e64 v160, 0, 32, vcc
	v_ldexp_f32 v158, v158, v160
	v_log_f32_e32 v158, v158
	s_nop 0
	v_mul_f32_e32 v160, 0x3f317217, v158
	v_fma_f32 v160, v158, s3, -v160
	v_fmac_f32_e32 v160, 0x3377d1cf, v158
	v_fmac_f32_e32 v160, 0x3f317217, v158
	v_cmp_lt_f32_e64 s[38:39], |v158|, s6
	s_nop 1
	v_cndmask_b32_e64 v158, v158, v160, s[38:39]
	v_cndmask_b32_e32 v160, 0, v224, vcc
	v_sub_f32_e32 v158, v158, v160
	v_cmp_gt_f32_e32 vcc, s2, v159
	v_max_f32_e32 v160, 0xc2700000, v158
	s_nop 0
	v_cndmask_b32_e64 v158, 0, 32, vcc
	v_ldexp_f32 v158, v159, v158
	v_log_f32_e32 v158, v158
	s_nop 0
	v_mul_f32_e32 v159, 0x3f317217, v158
	v_fma_f32 v159, v158, s3, -v159
	v_fmac_f32_e32 v159, 0x3377d1cf, v158
	v_fmac_f32_e32 v159, 0x3f317217, v158
	v_cmp_lt_f32_e64 s[38:39], |v158|, s6
	s_nop 1
	v_cndmask_b32_e64 v158, v158, v159, s[38:39]
	v_cndmask_b32_e32 v159, 0, v224, vcc
	v_sub_f32_e32 v158, v158, v159
	v_max_f32_e32 v161, 0xc2700000, v158
	v_pk_mul_f32 v[158:159], v[164:165], v[148:149] op_sel_hi:[0,1]
	v_pk_mul_f32 v[156:157], v[156:157], v[158:159]
	s_nop 0
	v_pk_mul_f32 v[156:157], v[156:157], s[10:11] op_sel_hi:[1,0]
	s_nop 0
	v_exp_f32_e32 v156, v156
	v_exp_f32_e32 v157, v157
	s_nop 0
	v_pk_add_f32 v[156:157], v[156:157], 1.0 op_sel_hi:[1,0]
	s_nop 0
	v_rcp_f32_e32 v156, v156
	v_rcp_f32_e32 v157, v157
	s_nop 0
	v_pk_fma_f32 v[156:157], v[192:193], v[156:157], v[134:135]
	s_nop 0
	v_cmp_gt_f32_e32 vcc, s2, v156
	s_nop 1
	v_cndmask_b32_e64 v158, 0, 32, vcc
	v_ldexp_f32 v156, v156, v158
	v_log_f32_e32 v156, v156
	s_nop 0
	v_mul_f32_e32 v158, 0x3f317217, v156
	v_fma_f32 v158, v156, s3, -v158
	v_fmac_f32_e32 v158, 0x3377d1cf, v156
	v_fmac_f32_e32 v158, 0x3f317217, v156
	v_cmp_lt_f32_e64 s[38:39], |v156|, s6
	s_nop 1
	v_cndmask_b32_e64 v156, v156, v158, s[38:39]
	v_cndmask_b32_e32 v158, 0, v224, vcc
	v_sub_f32_e32 v156, v156, v158
	v_cmp_gt_f32_e32 vcc, s2, v157
	v_max_f32_e32 v159, 0xc2700000, v156
	v_cvt_pk_bf16_f32 v158, v160, v161
	v_cndmask_b32_e64 v156, 0, 32, vcc
	v_ldexp_f32 v156, v157, v156
	v_log_f32_e32 v156, v156
	v_cvt_f32_i32_e32 v161, v17
	v_cvt_f32_i32_e32 v160, v16
	v_mul_f32_e32 v157, 0x3f317217, v156
	v_fma_f32 v157, v156, s3, -v157
	v_fmac_f32_e32 v157, 0x3377d1cf, v156
	v_fmac_f32_e32 v157, 0x3f317217, v156
	v_cmp_lt_f32_e64 s[38:39], |v156|, s6
	s_nop 1
	v_cndmask_b32_e64 v156, v156, v157, s[38:39]
	v_cndmask_b32_e32 v157, 0, v224, vcc
	v_sub_f32_e32 v156, v156, v157
	v_cvt_pk_bf16_f32 v157, v162, v163
	v_cvt_f32_i32_e32 v163, v15
	v_cvt_f32_i32_e32 v162, v14
	v_max_f32_e32 v164, 0xc2700000, v156
	v_cvt_pk_bf16_f32 v156, v66, v165
	v_cvt_pk_bf16_f32 v159, v159, v164
	v_pk_mul_f32 v[164:165], v[166:167], v[170:171] op_sel_hi:[0,1]
	v_pk_mul_f32 v[162:163], v[162:163], v[164:165]
	global_store_dwordx4 v[184:185], v[156:159], off offset:256
	v_pk_mul_f32 v[162:163], v[162:163], s[10:11] op_sel_hi:[1,0]
	s_nop 0
	v_exp_f32_e32 v162, v162
	v_exp_f32_e32 v163, v163
	v_cvt_f32_i32_e32 v159, v11
	v_cvt_f32_i32_e32 v158, v10
	v_cvt_f32_i32_e32 v157, v13
	v_pk_add_f32 v[162:163], v[162:163], 1.0 op_sel_hi:[1,0]
	v_cvt_f32_i32_e32 v156, v12
	v_rcp_f32_e32 v162, v162
	v_rcp_f32_e32 v163, v163
	s_nop 0
	v_pk_fma_f32 v[162:163], v[180:181], v[162:163], v[136:137]
	s_nop 0
	v_cmp_gt_f32_e32 vcc, s2, v162
	s_nop 1
	v_cndmask_b32_e64 v66, 0, 32, vcc
	v_ldexp_f32 v66, v162, v66
	v_log_f32_e32 v66, v66
	s_nop 0
	v_mul_f32_e32 v162, 0x3f317217, v66
	v_fma_f32 v162, v66, s3, -v162
	v_fmac_f32_e32 v162, 0x3377d1cf, v66
	v_fmac_f32_e32 v162, 0x3f317217, v66
	v_cmp_lt_f32_e64 s[38:39], |v66|, s6
	s_nop 1
	v_cndmask_b32_e64 v66, v66, v162, s[38:39]
	v_cndmask_b32_e32 v162, 0, v224, vcc
	v_cmp_gt_f32_e32 vcc, s2, v163
	v_sub_f32_e32 v66, v66, v162
	v_max_f32_e32 v66, 0xc2700000, v66
	v_cndmask_b32_e64 v162, 0, 32, vcc
	v_ldexp_f32 v162, v163, v162
	v_log_f32_e32 v162, v162
	s_nop 0
	v_mul_f32_e32 v163, 0x3f317217, v162
	v_fma_f32 v163, v162, s3, -v163
	v_fmac_f32_e32 v163, 0x3377d1cf, v162
	v_fmac_f32_e32 v163, 0x3f317217, v162
	v_cmp_lt_f32_e64 s[38:39], |v162|, s6
	s_nop 1
	v_cndmask_b32_e64 v162, v162, v163, s[38:39]
	v_cndmask_b32_e32 v163, 0, v224, vcc
	v_sub_f32_e32 v162, v162, v163
	v_max_f32_e32 v164, 0xc2700000, v162
	v_pk_mul_f32 v[162:163], v[166:167], v[154:155] op_sel_hi:[0,1]
	v_pk_mul_f32 v[160:161], v[160:161], v[162:163]
	v_pk_mul_f32 v[154:155], v[168:169], v[154:155] op_sel_hi:[0,1]
	v_pk_mul_f32 v[160:161], v[160:161], s[10:11] op_sel_hi:[1,0]
	s_nop 0
	v_exp_f32_e32 v160, v160
	v_exp_f32_e32 v161, v161
	s_nop 0
	v_pk_add_f32 v[160:161], v[160:161], 1.0 op_sel_hi:[1,0]
	s_nop 0
	v_rcp_f32_e32 v160, v160
	v_rcp_f32_e32 v161, v161
	s_nop 0
	v_pk_fma_f32 v[160:161], v[188:189], v[160:161], v[138:139]
	s_nop 0
	v_cmp_gt_f32_e32 vcc, s2, v160
	s_nop 1
	v_cndmask_b32_e64 v162, 0, 32, vcc
	v_ldexp_f32 v160, v160, v162
	v_log_f32_e32 v160, v160
	s_nop 0
	v_mul_f32_e32 v162, 0x3f317217, v160
	v_fma_f32 v162, v160, s3, -v162
; __device__ __forceinline__ unsigned cvt_pk_bf16(float lo, float hi) { f32x2_t v = {lo, hi}; bf16x2_t b = __builtin_convertvector(v, bf16x2_t); return __builtin_bit_cast(unsigned, b); }
; __device__ __forceinline__ float fast_rcp(float x) { return __builtin_amdgcn_rcpf(x); }
;     template <int KIND>
;     __device__ __forceinline__ void run(const f32x4 (&acc)[2][2][4][2], const Unit& u, int wr, int wc, int fr, int fq) const {
;     ...
;             for (int ai = 0; ai < 2; ++ai)
; #pragma unroll
;                 for (int m = 0; m < 4; ++m) { const int row = row0 + ai * HALF + m * 16; const float a = __shfl(ai ? sa_hi : sa_lo, 16 * m + fr);
;                     const f32x4 f0 = __builtin_convertvector(__builtin_bit_cast(i32x4, acc[ai][bj][m][0]), f32x4), f1 = __builtin_convertvector(__builtin_bit_cast(i32x4, acc[ai][bj][m][1]), f32x4);
;                     f32x2_t v[4] = {(f32x2_t){f0[0], f0[1]}, (f32x2_t){f0[2], f0[3]}, (f32x2_t){f1[0], f1[1]}, (f32x2_t){f1[2], f1[3]}};
; #pragma unroll
;                     for (int j = 0; j < 4; ++j) {
;                         v[j] = v[j] * (sc2[j] * (f32x2_t){a, a});
;                         if (KIND == 0 || KIND == 1 || KIND == 3) {
;                             const f32x2_t e = v[j] * (f32x2_t){-LOG2E, -LOG2E};
;                             const f32x2_t dn = (f32x2_t){__builtin_amdgcn_exp2f(e[0]), __builtin_amdgcn_exp2f(e[1])} + (f32x2_t){1.0f, 1.0f};
;                             const f32x2_t sg = (f32x2_t){fast_rcp(dn[0]), fast_rcp(dn[1])};
;                             if (KIND == 0) v[j] = v[j] * sg;
;                             else if (KIND == 3) v[j] = (v[j] * sg) * aux2[j];
;                             else { const f32x2_t f = __builtin_elementwise_fma((f32x2_t){1.0f, 1.0f} - aux2[j], sg, aux2[j]);
;                                 v[j] = (f32x2_t){fmaxf(__logf(f[0]), -60.0f), fmaxf(__logf(f[1]), -60.0f)}; }
;                         }
;                     }
;                     u32x4 w; w.x = cvt_pk_bf16(v[0][0], v[0][1]); w.y = cvt_pk_bf16(v[1][0], v[1][1]); w.z = cvt_pk_bf16(v[2][0], v[2][1]); w.w = cvt_pk_bf16(v[3][0], v[3][1]);
;                     *(u32x4*)(O + (size_t)row * NPROJ + col0 + bj * HALF) = w; }
	v_fmac_f32_e32 v162, 0x3377d1cf, v160
	v_fmac_f32_e32 v162, 0x3f317217, v160
	v_cmp_lt_f32_e64 s[38:39], |v160|, s6
	s_nop 1
	v_cndmask_b32_e64 v160, v160, v162, s[38:39]
	v_cndmask_b32_e32 v162, 0, v224, vcc
	v_sub_f32_e32 v160, v160, v162
	v_cmp_gt_f32_e32 vcc, s2, v161
	v_max_f32_e32 v162, 0xc2700000, v160
	s_nop 0
	v_cndmask_b32_e64 v160, 0, 32, vcc
	v_ldexp_f32 v160, v161, v160
	v_log_f32_e32 v160, v160
	s_nop 0
	v_mul_f32_e32 v161, 0x3f317217, v160
	v_fma_f32 v161, v160, s3, -v161
	v_fmac_f32_e32 v161, 0x3377d1cf, v160
	v_fmac_f32_e32 v161, 0x3f317217, v160
	v_cmp_lt_f32_e64 s[38:39], |v160|, s6
	s_nop 1
	v_cndmask_b32_e64 v160, v160, v161, s[38:39]
	v_cndmask_b32_e32 v161, 0, v224, vcc
	v_sub_f32_e32 v160, v160, v161
	v_max_f32_e32 v163, 0xc2700000, v160
	v_pk_mul_f32 v[160:161], v[166:167], v[152:153] op_sel_hi:[0,1]
	v_pk_mul_f32 v[158:159], v[158:159], v[160:161]
	v_pk_mul_f32 v[152:153], v[168:169], v[152:153] op_sel_hi:[0,1]
	v_pk_mul_f32 v[158:159], v[158:159], s[10:11] op_sel_hi:[1,0]
	s_nop 0
	v_exp_f32_e32 v158, v158
	v_exp_f32_e32 v159, v159
	s_nop 0
	v_pk_add_f32 v[158:159], v[158:159], 1.0 op_sel_hi:[1,0]
	s_nop 0
	v_rcp_f32_e32 v158, v158
	v_rcp_f32_e32 v159, v159
	s_nop 0
	v_pk_fma_f32 v[158:159], v[190:191], v[158:159], v[132:133]
	s_nop 0
	v_cmp_gt_f32_e32 vcc, s2, v158
	s_nop 1
	v_cndmask_b32_e64 v160, 0, 32, vcc
	v_ldexp_f32 v158, v158, v160
	v_log_f32_e32 v158, v158
	s_nop 0
	v_mul_f32_e32 v160, 0x3f317217, v158
	v_fma_f32 v160, v158, s3, -v160
	v_fmac_f32_e32 v160, 0x3377d1cf, v158
	v_fmac_f32_e32 v160, 0x3f317217, v158
	v_cmp_lt_f32_e64 s[38:39], |v158|, s6
	s_nop 1
	v_cndmask_b32_e64 v158, v158, v160, s[38:39]
	v_cndmask_b32_e32 v160, 0, v224, vcc
	v_sub_f32_e32 v158, v158, v160
	v_cmp_gt_f32_e32 vcc, s2, v159
	v_max_f32_e32 v160, 0xc2700000, v158
	s_nop 0
	v_cndmask_b32_e64 v158, 0, 32, vcc
	v_ldexp_f32 v158, v159, v158
	v_log_f32_e32 v158, v158
	s_nop 0
	v_mul_f32_e32 v159, 0x3f317217, v158
	v_fma_f32 v159, v158, s3, -v159
	v_fmac_f32_e32 v159, 0x3377d1cf, v158
	v_fmac_f32_e32 v159, 0x3f317217, v158
	v_cmp_lt_f32_e64 s[38:39], |v158|, s6
	s_nop 1
	v_cndmask_b32_e64 v158, v158, v159, s[38:39]
	v_cndmask_b32_e32 v159, 0, v224, vcc
	v_sub_f32_e32 v158, v158, v159
	v_max_f32_e32 v161, 0xc2700000, v158
	v_pk_mul_f32 v[158:159], v[166:167], v[148:149] op_sel_hi:[0,1]
	v_pk_mul_f32 v[156:157], v[156:157], v[158:159]
	v_pk_mul_f32 v[148:149], v[168:169], v[148:149] op_sel_hi:[0,1]
	v_pk_mul_f32 v[156:157], v[156:157], s[10:11] op_sel_hi:[1,0]
	s_nop 0
	v_exp_f32_e32 v156, v156
	v_exp_f32_e32 v157, v157
	s_nop 0
	v_pk_add_f32 v[156:157], v[156:157], 1.0 op_sel_hi:[1,0]
	s_nop 0
	v_rcp_f32_e32 v156, v156
	v_rcp_f32_e32 v157, v157
	s_nop 0
	v_pk_fma_f32 v[156:157], v[192:193], v[156:157], v[134:135]
	s_nop 0
	v_cmp_gt_f32_e32 vcc, s2, v156
	s_nop 1
	v_cndmask_b32_e64 v158, 0, 32, vcc
	v_ldexp_f32 v156, v156, v158
	v_log_f32_e32 v156, v156
	s_nop 0
	v_mul_f32_e32 v158, 0x3f317217, v156
	v_fma_f32 v158, v156, s3, -v158
	v_fmac_f32_e32 v158, 0x3377d1cf, v156
	v_fmac_f32_e32 v158, 0x3f317217, v156
	v_cmp_lt_f32_e64 s[38:39], |v156|, s6
	s_nop 1
	v_cndmask_b32_e64 v156, v156, v158, s[38:39]
	v_cndmask_b32_e32 v158, 0, v224, vcc
	v_sub_f32_e32 v156, v156, v158
	v_cmp_gt_f32_e32 vcc, s2, v157
	v_max_f32_e32 v159, 0xc2700000, v156
	v_cvt_pk_bf16_f32 v158, v160, v161
	v_cndmask_b32_e64 v156, 0, 32, vcc
	v_ldexp_f32 v156, v157, v156
	v_log_f32_e32 v156, v156
	v_cvt_f32_i32_e32 v161, v9
	v_cvt_f32_i32_e32 v160, v8
	v_mul_f32_e32 v157, 0x3f317217, v156
	v_fma_f32 v157, v156, s3, -v157
	v_fmac_f32_e32 v157, 0x3377d1cf, v156
	v_fmac_f32_e32 v157, 0x3f317217, v156
	v_cmp_lt_f32_e64 s[38:39], |v156|, s6
	v_pk_mul_f32 v[154:155], v[160:161], v[154:155]
	s_nop 0
	v_cndmask_b32_e64 v156, v156, v157, s[38:39]
	v_cndmask_b32_e32 v157, 0, v224, vcc
	v_sub_f32_e32 v156, v156, v157
	v_cvt_pk_bf16_f32 v157, v162, v163
	v_cvt_f32_i32_e32 v163, v7
	v_cvt_f32_i32_e32 v162, v6
	v_max_f32_e32 v165, 0xc2700000, v156
	v_cvt_pk_bf16_f32 v156, v66, v164
	v_cvt_pk_bf16_f32 v159, v159, v165
	v_pk_mul_f32 v[164:165], v[168:169], v[170:171] op_sel_hi:[0,1]
	v_pk_mul_f32 v[162:163], v[162:163], v[164:165]
	v_pk_mul_f32 v[154:155], v[154:155], s[10:11] op_sel_hi:[1,0]
	v_pk_mul_f32 v[162:163], v[162:163], s[10:11] op_sel_hi:[1,0]
	v_exp_f32_e32 v154, v154
	v_exp_f32_e32 v162, v162
	v_exp_f32_e32 v163, v163
	v_exp_f32_e32 v155, v155
	global_store_dwordx4 v[186:187], v[156:159], off offset:256
	v_pk_add_f32 v[162:163], v[162:163], 1.0 op_sel_hi:[1,0]
	s_nop 0
	v_rcp_f32_e32 v162, v162
	v_rcp_f32_e32 v163, v163
	v_pk_add_f32 v[154:155], v[154:155], 1.0 op_sel_hi:[1,0]
	v_cvt_f32_i32_e32 v159, v3
; __device__ __forceinline__ unsigned cvt_pk_bf16(float lo, float hi) { f32x2_t v = {lo, hi}; bf16x2_t b = __builtin_convertvector(v, bf16x2_t); return __builtin_bit_cast(unsigned, b); }
; __device__ __forceinline__ float fast_rcp(float x) { return __builtin_amdgcn_rcpf(x); }
;     template <int KIND>
;     __device__ __forceinline__ void run(const f32x4 (&acc)[2][2][4][2], const Unit& u, int wr, int wc, int fr, int fq) const {
;     ...
;             for (int ai = 0; ai < 2; ++ai)
; #pragma unroll
;                 for (int m = 0; m < 4; ++m) { const int row = row0 + ai * HALF + m * 16; const float a = __shfl(ai ? sa_hi : sa_lo, 16 * m + fr);
;                     const f32x4 f0 = __builtin_convertvector(__builtin_bit_cast(i32x4, acc[ai][bj][m][0]), f32x4), f1 = __builtin_convertvector(__builtin_bit_cast(i32x4, acc[ai][bj][m][1]), f32x4);
;                     f32x2_t v[4] = {(f32x2_t){f0[0], f0[1]}, (f32x2_t){f0[2], f0[3]}, (f32x2_t){f1[0], f1[1]}, (f32x2_t){f1[2], f1[3]}};
; #pragma unroll
;                     for (int j = 0; j < 4; ++j) {
;                         v[j] = v[j] * (sc2[j] * (f32x2_t){a, a});
;                         if (KIND == 0 || KIND == 1 || KIND == 3) {
;                             const f32x2_t e = v[j] * (f32x2_t){-LOG2E, -LOG2E};
;                             const f32x2_t dn = (f32x2_t){__builtin_amdgcn_exp2f(e[0]), __builtin_amdgcn_exp2f(e[1])} + (f32x2_t){1.0f, 1.0f};
;                             const f32x2_t sg = (f32x2_t){fast_rcp(dn[0]), fast_rcp(dn[1])};
;                             if (KIND == 0) v[j] = v[j] * sg;
;                             else if (KIND == 3) v[j] = (v[j] * sg) * aux2[j];
;                             else { const f32x2_t f = __builtin_elementwise_fma((f32x2_t){1.0f, 1.0f} - aux2[j], sg, aux2[j]);
;                                 v[j] = (f32x2_t){fmaxf(__logf(f[0]), -60.0f), fmaxf(__logf(f[1]), -60.0f)}; }
;                         }
;                     }
;                     u32x4 w; w.x = cvt_pk_bf16(v[0][0], v[0][1]); w.y = cvt_pk_bf16(v[1][0], v[1][1]); w.z = cvt_pk_bf16(v[2][0], v[2][1]); w.w = cvt_pk_bf16(v[3][0], v[3][1]);
;                     *(u32x4*)(O + (size_t)row * NPROJ + col0 + bj * HALF) = w; }
	v_rcp_f32_e32 v154, v154
	v_pk_fma_f32 v[136:137], v[180:181], v[162:163], v[136:137]
	v_rcp_f32_e32 v155, v155
	v_cmp_gt_f32_e32 vcc, s2, v136
	v_cvt_f32_i32_e32 v158, v2
	v_cvt_f32_i32_e32 v157, v5
	v_cndmask_b32_e64 v66, 0, 32, vcc
	v_ldexp_f32 v66, v136, v66
	v_log_f32_e32 v66, v66
	v_pk_fma_f32 v[138:139], v[188:189], v[154:155], v[138:139]
	v_pk_mul_f32 v[152:153], v[158:159], v[152:153]
	v_cvt_f32_i32_e32 v156, v4
	v_mul_f32_e32 v136, 0x3f317217, v66
	v_fma_f32 v136, v66, s3, -v136
	v_fmac_f32_e32 v136, 0x3377d1cf, v66
	v_fmac_f32_e32 v136, 0x3f317217, v66
	v_cmp_lt_f32_e64 s[38:39], |v66|, s6
	v_pk_mul_f32 v[152:153], v[152:153], s[10:11] op_sel_hi:[1,0]
	v_pk_mul_f32 v[148:149], v[156:157], v[148:149]
	v_cndmask_b32_e64 v66, v66, v136, s[38:39]
	v_cndmask_b32_e32 v136, 0, v224, vcc
	v_sub_f32_e32 v66, v66, v136
	v_cmp_gt_f32_e32 vcc, s2, v137
	v_max_f32_e32 v136, 0xc2700000, v66
	v_exp_f32_e32 v152, v152
	v_cndmask_b32_e64 v66, 0, 32, vcc
	v_ldexp_f32 v66, v137, v66
	v_log_f32_e32 v66, v66
	v_exp_f32_e32 v153, v153
	v_pk_mul_f32 v[148:149], v[148:149], s[10:11] op_sel_hi:[1,0]
	v_mul_f32_e32 v137, 0x3f317217, v66
	v_fma_f32 v137, v66, s3, -v137
	v_fmac_f32_e32 v137, 0x3377d1cf, v66
	v_fmac_f32_e32 v137, 0x3f317217, v66
	v_cmp_lt_f32_e64 s[38:39], |v66|, s6
	v_pk_add_f32 v[152:153], v[152:153], 1.0 op_sel_hi:[1,0]
	v_exp_f32_e32 v148, v148
	v_cndmask_b32_e64 v66, v66, v137, s[38:39]
	v_cndmask_b32_e32 v137, 0, v224, vcc
	v_sub_f32_e32 v66, v66, v137
	v_cmp_gt_f32_e32 vcc, s2, v138
	v_max_f32_e32 v137, 0xc2700000, v66
	v_rcp_f32_e32 v152, v152
	v_cndmask_b32_e64 v66, 0, 32, vcc
	v_ldexp_f32 v66, v138, v66
	v_log_f32_e32 v66, v66
	v_rcp_f32_e32 v153, v153
	v_exp_f32_e32 v149, v149
	v_mul_f32_e32 v138, 0x3f317217, v66
	v_fma_f32 v138, v66, s3, -v138
	v_fmac_f32_e32 v138, 0x3377d1cf, v66
	v_fmac_f32_e32 v138, 0x3f317217, v66
	v_cmp_lt_f32_e64 s[38:39], |v66|, s6
	v_pk_fma_f32 v[132:133], v[190:191], v[152:153], v[132:133]
	v_pk_add_f32 v[148:149], v[148:149], 1.0 op_sel_hi:[1,0]
	v_cndmask_b32_e64 v66, v66, v138, s[38:39]
	v_cndmask_b32_e32 v138, 0, v224, vcc
	v_sub_f32_e32 v66, v66, v138
	v_cmp_gt_f32_e32 vcc, s2, v139
	v_max_f32_e32 v138, 0xc2700000, v66
	v_rcp_f32_e32 v148, v148
	v_cndmask_b32_e64 v66, 0, 32, vcc
	v_ldexp_f32 v66, v139, v66
	v_log_f32_e32 v66, v66
	v_rcp_f32_e32 v149, v149
	v_mul_f32_e32 v139, 0x3f317217, v66
	v_fma_f32 v139, v66, s3, -v139
	v_fmac_f32_e32 v139, 0x3377d1cf, v66
	v_fmac_f32_e32 v139, 0x3f317217, v66
	v_cmp_lt_f32_e64 s[38:39], |v66|, s6
	v_pk_fma_f32 v[134:135], v[192:193], v[148:149], v[134:135]
	s_nop 0
	v_cndmask_b32_e64 v66, v66, v139, s[38:39]
	v_cndmask_b32_e32 v139, 0, v224, vcc
	v_sub_f32_e32 v66, v66, v139
	v_cmp_gt_f32_e32 vcc, s2, v132
	v_max_f32_e32 v139, 0xc2700000, v66
	s_nop 0
	v_cndmask_b32_e64 v66, 0, 32, vcc
	v_ldexp_f32 v66, v132, v66
	v_log_f32_e32 v66, v66
	s_nop 0
	v_mul_f32_e32 v132, 0x3f317217, v66
	v_fma_f32 v132, v66, s3, -v132
	v_fmac_f32_e32 v132, 0x3377d1cf, v66
	v_fmac_f32_e32 v132, 0x3f317217, v66
	v_cmp_lt_f32_e64 s[38:39], |v66|, s6
	s_nop 1
	v_cndmask_b32_e64 v66, v66, v132, s[38:39]
	v_cndmask_b32_e32 v132, 0, v224, vcc
	v_sub_f32_e32 v66, v66, v132
	v_cmp_gt_f32_e32 vcc, s2, v133
	v_max_f32_e32 v132, 0xc2700000, v66
	s_nop 0
	v_cndmask_b32_e64 v66, 0, 32, vcc
	v_ldexp_f32 v66, v133, v66
	v_log_f32_e32 v66, v66
	s_nop 0
	v_mul_f32_e32 v133, 0x3f317217, v66
	v_fma_f32 v133, v66, s3, -v133
	v_fmac_f32_e32 v133, 0x3377d1cf, v66
	v_fmac_f32_e32 v133, 0x3f317217, v66
	v_cmp_lt_f32_e64 s[38:39], |v66|, s6
	s_nop 1
	v_cndmask_b32_e64 v66, v66, v133, s[38:39]
	v_cndmask_b32_e32 v133, 0, v224, vcc
	v_sub_f32_e32 v66, v66, v133
	v_cmp_gt_f32_e32 vcc, s2, v134
	v_max_f32_e32 v133, 0xc2700000, v66
	s_nop 0
	v_cndmask_b32_e64 v66, 0, 32, vcc
	v_ldexp_f32 v66, v134, v66
	v_log_f32_e32 v66, v66
	s_nop 0
	v_mul_f32_e32 v134, 0x3f317217, v66
	v_fma_f32 v134, v66, s3, -v134
	v_fmac_f32_e32 v134, 0x3377d1cf, v66
	v_fmac_f32_e32 v134, 0x3f317217, v66
	v_cmp_lt_f32_e64 s[38:39], |v66|, s6
	s_nop 1
	v_cndmask_b32_e64 v66, v66, v134, s[38:39]
	v_cndmask_b32_e32 v134, 0, v224, vcc
	v_sub_f32_e32 v66, v66, v134
	v_cmp_gt_f32_e32 vcc, s2, v135
	v_max_f32_e32 v134, 0xc2700000, v66
	s_nop 0
	v_cndmask_b32_e64 v66, 0, 32, vcc
	v_ldexp_f32 v66, v135, v66
	v_log_f32_e32 v66, v66
	s_nop 0
	v_mul_f32_e32 v135, 0x3f317217, v66
	v_fma_f32 v135, v66, s3, -v135
	v_fmac_f32_e32 v135, 0x3377d1cf, v66
	v_fmac_f32_e32 v135, 0x3f317217, v66
	v_cmp_lt_f32_e64 s[38:39], |v66|, s6
	s_nop 1
	v_cndmask_b32_e64 v66, v66, v135, s[38:39]
	v_cndmask_b32_e32 v135, 0, v224, vcc
	v_sub_f32_e32 v66, v66, v135
	v_max_f32_e32 v135, 0xc2700000, v66
